# grid barrier: non-leader workgroups poll the cross-XCD arrival counter directly (one hop fewer) on top of the current best
# speedup vs baseline: 1.0027x; 1.0027x over previous
; __device__ __forceinline__ unsigned xb_ld(unsigned* p)              { return __hip_atomic_load(p, __ATOMIC_RELAXED, __HIP_MEMORY_SCOPE_AGENT); }
; __device__ __forceinline__ unsigned xb_add(unsigned* p, unsigned v) { return __hip_atomic_fetch_add(p, v, __ATOMIC_RELAXED, __HIP_MEMORY_SCOPE_AGENT); }
; #define XB_SPIN(cond, bar) do { unsigned _sp = 0; while (cond) { __builtin_amdgcn_s_sleep(1); \
;     if ((++_sp & 255u) == 0u) { if (xb_ld(&(bar)[XB_TMO])) break; if (_sp > XB_SPIN_CAP) { atomicAdd(&(bar)[XB_TMO], 1u); break; } } } } while (0)
; __device__ __forceinline__ void xcd_barrier(const XcdBarrier& b) {
;     ...
;         const unsigned old = xb_add(&bar[XB_XSUB(b.x)], 1u);
;         const unsigned gen = old / nloc;
;         if (old + 1u == (gen + 1u) * nloc) {
;             __builtin_amdgcn_fence(__ATOMIC_RELEASE, "agent");
;             asm volatile("s_waitcnt vmcnt(0)" ::: "memory");
;             const unsigned og = xb_add(&bar[XB_TOP], 1u);
;             const unsigned tg = og / nx;
;             if (og + 1u == (tg + 1u) * nx) xb_add(&bar[XB_TOPGEN], 1u);
;             else XB_SPIN(xb_ld(&bar[XB_TOPGEN]) == tg, bar);
;             __builtin_amdgcn_fence(__ATOMIC_ACQUIRE, "agent");
;             xb_add(&bar[XB_XGEN(b.x)], 1u);
;             asm volatile("s_waitcnt vmcnt(0)" ::: "memory");
;         } else {
;             XB_SPIN(xb_ld(&bar[XB_XGEN(b.x)]) == gen, bar);
;             __builtin_amdgcn_fence(__ATOMIC_ACQUIRE, "agent");
.LBB0_142:
	s_or_b64 exec, exec, s[8:9]
	v_cvt_f32_u32_e32 v5, v3
	s_waitcnt vmcnt(0)
	v_readfirstlane_b32 s6, v4
	v_sub_u32_e32 v4, 0, v3
	v_rcp_iflag_f32_e32 v5, v5
	v_add_u32_e32 v6, s6, v2
	v_mul_f32_e32 v5, 0x4f7ffffe, v5
	v_cvt_u32_f32_e32 v5, v5
	v_mul_lo_u32 v2, v4, v5
	v_mul_hi_u32 v2, v5, v2
	v_add_u32_e32 v2, v5, v2
	v_mul_hi_u32 v2, v6, v2
	v_mul_lo_u32 v4, v2, v3
	v_sub_u32_e32 v4, v6, v4
	v_add_u32_e32 v5, 1, v2
	v_cmp_ge_u32_e32 vcc, v4, v3
	s_nop 1
	v_cndmask_b32_e32 v2, v2, v5, vcc
	v_sub_u32_e32 v5, v4, v3
	v_cndmask_b32_e32 v4, v4, v5, vcc
	v_add_u32_e32 v5, 1, v2
	v_cmp_ge_u32_e32 vcc, v4, v3
	v_add_u32_e32 v4, 1, v6
	s_nop 0
	v_cndmask_b32_e32 v2, v2, v5, vcc
	v_mul_lo_u32 v5, v3, v2
	v_add_u32_e32 v3, v5, v3
	v_cmp_ne_u32_e32 vcc, v4, v3
	s_and_saveexec_b64 s[6:7], vcc
	s_xor_b64 s[6:7], exec, s[6:7]
	s_cbranch_execz .LBB0_156
	s_waitcnt lgkmcnt(0)
	buffer_inv sc1
	v_mad_u32_u24 v2, v2, v1, v1
	v_mov_b32_e32 v1, 0x2e403000
	global_load_dword v1, v1, s[2:3] offset:1024 sc1
	s_add_u32 s12, s2, 0x2e403400
	s_addc_u32 s13, s3, 0
	s_waitcnt vmcnt(0)
	v_cmp_lt_u32_e32 vcc, v1, v2
	s_and_saveexec_b64 s[8:9], vcc
	s_cbranch_execz .LBB0_155
	s_add_u32 s10, s2, 0x2e400200
	s_addc_u32 s11, s3, 0
	s_mov_b32 s24, 1
	s_mov_b64 s[14:15], 0
	v_mov_b32_e32 v1, 0
	s_branch .LBB0_146

; __device__ __forceinline__ unsigned xb_ld(unsigned* p)              { return __hip_atomic_load(p, __ATOMIC_RELAXED, __HIP_MEMORY_SCOPE_AGENT); }
; #define XB_SPIN(cond, bar) do { unsigned _sp = 0; while (cond) { __builtin_amdgcn_s_sleep(1); \
;     if ((++_sp & 255u) == 0u) { if (xb_ld(&(bar)[XB_TMO])) break; if (_sp > XB_SPIN_CAP) { atomicAdd(&(bar)[XB_TMO], 1u); break; } } } } while (0)
; __device__ __forceinline__ void xcd_barrier(const XcdBarrier& b) {
;     ...
;             XB_SPIN(xb_ld(&bar[XB_XGEN(b.x)]) == gen, bar);
.LBB0_148:
	global_load_dword v3, v1, s[12:13] sc1
	s_add_i32 s24, s24, 1
	s_mov_b64 s[20:21], -1
	s_waitcnt vmcnt(0)
	v_cmp_ge_u32_e32 vcc, v3, v2
	s_orn2_b64 s[18:19], vcc, exec
	s_branch .LBB0_145

; #define PG8_STAGE(bufoff, gbase, voff) do { _Pragma("unroll") for (int _i = 0; _i < 2; ++_i) \
;         __builtin_amdgcn_global_load_lds((const unsigned*)((const char*)(gbase) + (voff)[_i]), (PG8_LAS unsigned*)(lds + (bufoff) + ldsw + _i * 8192), 16, 0, 0); } while (0)
; #define PG8_LDA(dst, b, h) do { _Pragma("unroll") for (int m = 0; m < 4; ++m) _Pragma("unroll") for (int k = 0; k < 2; ++k) dst[m][k] = *(const PG8_LAS bf16x8*)(lds + PG8_SA(b, h) + aoff + m * 2048 + k * 1024); } while (0)
; #define PG8_LDB(dst, b, h) do { _Pragma("unroll") for (int n = 0; n < 2; ++n) _Pragma("unroll") for (int k = 0; k < 2; ++k) dst[n][k] = *(const PG8_LAS bf16x8*)(lds + PG8_SB(b, h) + boff + n * 2048 + k * 1024); } while (0)
; #define PG8_WAIT_V(n) asm volatile("s_waitcnt vmcnt(" #n ")" ::: "memory")
; #define PG8_WAIT_L(n) asm volatile("s_waitcnt lgkmcnt(" #n ")" ::: "memory")
; #define PG8_BAR __builtin_amdgcn_s_barrier()
; template <class Epi, class Sched, bool ALIGN_EPI = false, bool SP2 = false>
; __device__ __forceinline__ void gemm_phase(PG8_LAS unsigned char* lds, const Gemm g, const Sched& S, const Epi& E) {
;     ...
;         const bool has_next = S.next(ui + 1, nxt);
;         const char* nA = has_next ? (const char*)g.A + (size_t)nxt.pm * tstep : cA; const char* nB = has_next ? (const char*)g.Bt + (size_t)nxt.pn * tstep : cB;
;         for (int t = 0; t < nt; t += 2) {
;             const bool last = (t == nt - 2);
;             const char* a1 = cA + (size_t)(t + 1) * kstep;
;             const char* a2 = last ? nA : cA + (size_t)(t + 2) * kstep; const char* b2 = last ? nB : cB + (size_t)(t + 2) * kstep;
;             const char* a3 = a2 + kstep; const char* b3 = b2 + kstep;
;             if (last && has_next) S.a_ready(nxt);
;             if constexpr (SP2) {
;             PG8_LDB(B0, 0, 0); PG8_LDB(B1, 0, 1); PG8_SCHED; PG8_LDA(At, 0, 0); PG8_STAGE(PG8_SA(1, 1), a1 + hstep, voffA);
;             PG8_WAIT_V(8); PG8_WAIT_L(0); PG8_BAR; PG8_MMA(0, 0, At, B0); PG8_MMA(0, 1, At, B1); PG8_BAR; PG8_SCHED;
;     ...
; #pragma unroll
;         for (int a = 0; a < 2; ++a)
; #pragma unroll
;             for (int b = 0; b < 2; ++b)
; #pragma unroll
;                 for (int m = 0; m < 4; ++m)
; #pragma unroll
;                     for (int n = 0; n < 2; ++n) acc[a][b][m][n] = (f32x4){0.f, 0.f, 0.f, 0.f};
;         cur = nxt; cA = nA; cB = nB; ++ui;
.LBB0_220:
	s_ashr_i32 s25, s24, 31
	s_lshl_b64 s[2:3], s[24:25], 20
	s_add_u32 s2, s12, s2
	s_addc_u32 s3, s13, s3
	s_and_b64 s[26:27], s[8:9], exec
	s_cselect_b32 s25, s3, s1
	s_cselect_b32 s46, s2, s0
	s_ashr_i32 s23, s22, 31
	s_lshl_b64 s[26:27], s[22:23], 20
	s_add_u32 s26, s31, s26
	s_addc_u32 s27, s34, s27
	s_and_b64 s[28:29], s[8:9], exec
	s_cselect_b32 s23, s27, s5
	s_cselect_b32 s47, s26, s4
	s_add_u32 s0, s0, 0x80080
	s_addc_u32 s1, s1, 0
	s_add_u32 s48, s4, 0x100
	v_mov_b32_e32 v0, 0
	s_addc_u32 s49, s5, 0
	s_mov_b32 s50, -2
	v_mov_b32_e32 v1, v0
	s_waitcnt lgkmcnt(0)
	v_mov_b32_e32 v2, v0
	v_mov_b32_e32 v3, v0
	v_mov_b32_e32 v4, v0
	v_mov_b32_e32 v5, v0
	v_mov_b32_e32 v6, v0
	v_mov_b32_e32 v7, v0
	v_mov_b32_e32 v16, v0
	v_mov_b32_e32 v17, v0
	s_waitcnt vmcnt(0)
	v_mov_b32_e32 v18, v0
	v_mov_b32_e32 v19, v0
	v_mov_b32_e32 v20, v0
	v_mov_b32_e32 v21, v0
	v_mov_b32_e32 v22, v0
	v_mov_b32_e32 v23, v0
	v_mov_b32_e32 v32, v0
	v_mov_b32_e32 v33, v0
	v_mov_b32_e32 v34, v0
	v_mov_b32_e32 v35, v0
	v_mov_b32_e32 v36, v0
	v_mov_b32_e32 v37, v0
	v_mov_b32_e32 v38, v0
	v_mov_b32_e32 v39, v0
	v_mov_b32_e32 v48, v0
	v_mov_b32_e32 v49, v0
	v_mov_b32_e32 v50, v0
	v_mov_b32_e32 v51, v0
	v_mov_b32_e32 v52, v0
	v_mov_b32_e32 v53, v0
	v_mov_b32_e32 v54, v0
	v_mov_b32_e32 v55, v0
	v_mov_b32_e32 v8, v0
	v_mov_b32_e32 v9, v0
	v_mov_b32_e32 v10, v0
	v_mov_b32_e32 v11, v0
	v_mov_b32_e32 v12, v0
	v_mov_b32_e32 v13, v0
	v_mov_b32_e32 v14, v0
	v_mov_b32_e32 v15, v0
	v_mov_b32_e32 v24, v0
	v_mov_b32_e32 v25, v0
	v_mov_b32_e32 v26, v0
	v_mov_b32_e32 v27, v0
	v_mov_b32_e32 v28, v0
	v_mov_b32_e32 v29, v0
	v_mov_b32_e32 v30, v0
	v_mov_b32_e32 v31, v0
	v_mov_b32_e32 v40, v0
	v_mov_b32_e32 v41, v0
	v_mov_b32_e32 v42, v0
	v_mov_b32_e32 v43, v0
	v_mov_b32_e32 v44, v0
	v_mov_b32_e32 v45, v0
	v_mov_b32_e32 v46, v0
	v_mov_b32_e32 v47, v0
	v_mov_b32_e32 v56, v0
	v_mov_b32_e32 v57, v0
	v_mov_b32_e32 v58, v0
	v_mov_b32_e32 v59, v0
	v_mov_b32_e32 v60, v0
	v_mov_b32_e32 v61, v0
	v_mov_b32_e32 v62, v0
	v_mov_b32_e32 v63, v0
	v_mov_b32_e32 v64, v0
	v_mov_b32_e32 v65, v0
	v_mov_b32_e32 v66, v0
	v_mov_b32_e32 v67, v0
	v_mov_b32_e32 v68, v0
	v_mov_b32_e32 v69, v0
	v_mov_b32_e32 v70, v0
	v_mov_b32_e32 v71, v0
	v_mov_b32_e32 v80, v0
	v_mov_b32_e32 v81, v0
	v_mov_b32_e32 v82, v0
	v_mov_b32_e32 v83, v0
	v_mov_b32_e32 v84, v0
	v_mov_b32_e32 v85, v0
	v_mov_b32_e32 v86, v0
	v_mov_b32_e32 v87, v0
	v_mov_b32_e32 v96, v0
	v_mov_b32_e32 v97, v0
	v_mov_b32_e32 v98, v0
	v_mov_b32_e32 v99, v0
	v_mov_b32_e32 v100, v0
	v_mov_b32_e32 v101, v0
	v_mov_b32_e32 v102, v0
	v_mov_b32_e32 v103, v0
	v_mov_b32_e32 v112, v0
	v_mov_b32_e32 v113, v0
	v_mov_b32_e32 v114, v0
	v_mov_b32_e32 v115, v0
	v_mov_b32_e32 v116, v0
	v_mov_b32_e32 v117, v0
	v_mov_b32_e32 v118, v0
	v_mov_b32_e32 v119, v0
	v_mov_b32_e32 v72, v0
	v_mov_b32_e32 v73, v0
	v_mov_b32_e32 v74, v0
	v_mov_b32_e32 v75, v0
	v_mov_b32_e32 v76, v0
	v_mov_b32_e32 v77, v0
	v_mov_b32_e32 v78, v0
	v_mov_b32_e32 v79, v0
	v_mov_b32_e32 v88, v0
	v_mov_b32_e32 v89, v0
	v_mov_b32_e32 v90, v0
	v_mov_b32_e32 v91, v0
	v_mov_b32_e32 v92, v0
	v_mov_b32_e32 v93, v0
	v_mov_b32_e32 v94, v0
	v_mov_b32_e32 v95, v0
	v_mov_b32_e32 v104, v0
	v_mov_b32_e32 v105, v0
	v_mov_b32_e32 v106, v0
	v_mov_b32_e32 v107, v0
	v_mov_b32_e32 v108, v0
	v_mov_b32_e32 v109, v0
	v_mov_b32_e32 v110, v0
	v_mov_b32_e32 v111, v0
	v_mov_b32_e32 v120, v0
	v_mov_b32_e32 v121, v0
	v_mov_b32_e32 v122, v0
	v_mov_b32_e32 v123, v0
	v_mov_b32_e32 v124, v0
	v_mov_b32_e32 v125, v0
	v_mov_b32_e32 v126, v0
	v_mov_b32_e32 v127, v0
	s_nop 0
	s_nop 0
	s_nop 0
	s_nop 0
	s_nop 0
	s_nop 0
	s_nop 0
	s_nop 0
	s_nop 0
	s_nop 0
	s_nop 0
	s_nop 0
	s_nop 0
.LBB0_221:
	s_add_u32 s4, s0, 0xfff80080
	s_addc_u32 s5, s1, -1
	s_add_i32 s51, 0, 0x10000
	s_cmp_eq_u32 s50, 28
	s_cselect_b32 s29, s25, s5
	s_cselect_b32 s28, s46, s4
	v_add_u32_e32 v146, s51, v150
	s_cselect_b32 s5, s23, s49
	s_cselect_b32 s4, s47, s48
	s_add_i32 s54, 0, 0x14000
	ds_read_b128 v[138:141], v146
	ds_read_b128 v[142:145], v146 offset:1024
	ds_read_b128 v[164:167], v146 offset:2048
	ds_read_b128 v[168:171], v146 offset:3072
	v_add_u32_e32 v146, s54, v150
	ds_read_b128 v[172:175], v146
	ds_read_b128 v[176:179], v146 offset:1024
	ds_read_b128 v[180:183], v146 offset:2048
	ds_read_b128 v[184:187], v146 offset:3072
	v_lshl_add_u64 v[146:147], s[0:1], 0, v[134:135]
	s_add_i32 m0, s35, 0xc000
	ds_read_b128 v[188:191], v151
	ds_read_b128 v[192:195], v151 offset:1024
	ds_read_b128 v[196:199], v151 offset:2048
	ds_read_b128 v[200:203], v151 offset:3072
	ds_read_b128 v[204:207], v151 offset:4096
	ds_read_b128 v[208:211], v151 offset:5120
	ds_read_b128 v[212:215], v151 offset:6144
	ds_read_b128 v[216:219], v151 offset:7168
	global_load_lds_dwordx4 v[146:147], off
	v_lshl_add_u64 v[146:147], s[0:1], 0, v[136:137]
	s_add_i32 m0, s35, 0xe000
	s_nop 0
	global_load_lds_dwordx4 v[146:147], off
	s_waitcnt vmcnt(8)
	s_waitcnt lgkmcnt(0)
	s_setprio 1
	s_barrier
; #define PG8_STAGE(bufoff, gbase, voff) do { _Pragma("unroll") for (int _i = 0; _i < 2; ++_i) \
;         __builtin_amdgcn_global_load_lds((const unsigned*)((const char*)(gbase) + (voff)[_i]), (PG8_LAS unsigned*)(lds + (bufoff) + ldsw + _i * 8192), 16, 0, 0); } while (0)
; #define PG8_LDA(dst, b, h) do { _Pragma("unroll") for (int m = 0; m < 4; ++m) _Pragma("unroll") for (int k = 0; k < 2; ++k) dst[m][k] = *(const PG8_LAS bf16x8*)(lds + PG8_SA(b, h) + aoff + m * 2048 + k * 1024); } while (0)
; #define PG8_MMA(ai, bj, At, Bt) do { __builtin_amdgcn_s_setprio(1); _Pragma("unroll") for (int m = 0; m < 4; ++m) _Pragma("unroll") for (int n = 0; n < 2; ++n) _Pragma("unroll") for (int k = 0; k < 2; ++k) \
;         acc[ai][bj][m][n] = __builtin_amdgcn_mfma_f32_16x16x32_bf16(Bt[n][k], At[m][k], acc[ai][bj][m][n], 0, 0, 0); __builtin_amdgcn_s_setprio(0); } while (0)
; #define PG8_WAIT_V(n) asm volatile("s_waitcnt vmcnt(" #n ")" ::: "memory")
; #define PG8_WAIT_L(n) asm volatile("s_waitcnt lgkmcnt(" #n ")" ::: "memory")
; #define PG8_BAR __builtin_amdgcn_s_barrier()
; #define PG8_SCHED __builtin_amdgcn_sched_barrier(0)
; template <class Epi, class Sched, bool ALIGN_EPI = false, bool SP2 = false>
; __device__ __forceinline__ void gemm_phase(PG8_LAS unsigned char* lds, const Gemm g, const Sched& S, const Epi& E) {
;     ...
;             PG8_WAIT_V(8); PG8_WAIT_L(0); PG8_BAR; PG8_MMA(0, 0, At, B0); PG8_MMA(0, 1, At, B1); PG8_BAR; PG8_SCHED;
;             PG8_LDA(At, 0, 1); PG8_STAGE(PG8_SB(0, 0), b2, voffB); PG8_STAGE(PG8_SB(0, 1), b2 + hstep, voffB); PG8_STAGE(PG8_SA(0, 0), a2, voffA);
;             PG8_WAIT_V(8); PG8_WAIT_L(0); PG8_BAR; PG8_MMA(1, 0, At, B0); PG8_MMA(1, 1, At, B1); PG8_BAR; PG8_SCHED;
	v_mfma_f32_16x16x32_bf16 v[124:127], v[138:141], v[188:191], v[124:127]
	v_mfma_f32_16x16x32_bf16 v[120:123], v[164:167], v[188:191], v[120:123]
	v_mfma_f32_16x16x32_bf16 v[108:111], v[138:141], v[196:199], v[108:111]
	v_mfma_f32_16x16x32_bf16 v[104:107], v[164:167], v[196:199], v[104:107]
	v_mfma_f32_16x16x32_bf16 v[92:95], v[138:141], v[204:207], v[92:95]
	v_mfma_f32_16x16x32_bf16 v[88:91], v[164:167], v[204:207], v[88:91]
	v_mfma_f32_16x16x32_bf16 v[76:79], v[138:141], v[212:215], v[76:79]
	v_mfma_f32_16x16x32_bf16 v[72:75], v[164:167], v[212:215], v[72:75]
	v_mfma_f32_16x16x32_bf16 v[124:127], v[142:145], v[192:195], v[124:127]
	v_mfma_f32_16x16x32_bf16 v[120:123], v[168:171], v[192:195], v[120:123]
	v_mfma_f32_16x16x32_bf16 v[108:111], v[142:145], v[200:203], v[108:111]
	v_mfma_f32_16x16x32_bf16 v[104:107], v[168:171], v[200:203], v[104:107]
	v_mfma_f32_16x16x32_bf16 v[92:95], v[142:145], v[208:211], v[92:95]
	v_mfma_f32_16x16x32_bf16 v[88:91], v[168:171], v[208:211], v[88:91]
	v_mfma_f32_16x16x32_bf16 v[76:79], v[142:145], v[216:219], v[76:79]
	v_mfma_f32_16x16x32_bf16 v[72:75], v[168:171], v[216:219], v[72:75]
	s_setprio 0
	s_setprio 1
	v_mfma_f32_16x16x32_bf16 v[116:119], v[172:175], v[188:191], v[116:119]
	v_mfma_f32_16x16x32_bf16 v[112:115], v[180:183], v[188:191], v[112:115]
	v_mfma_f32_16x16x32_bf16 v[100:103], v[172:175], v[196:199], v[100:103]
	v_mfma_f32_16x16x32_bf16 v[96:99], v[180:183], v[196:199], v[96:99]
	v_mfma_f32_16x16x32_bf16 v[84:87], v[172:175], v[204:207], v[84:87]
	v_mfma_f32_16x16x32_bf16 v[80:83], v[180:183], v[204:207], v[80:83]
	v_mfma_f32_16x16x32_bf16 v[68:71], v[172:175], v[212:215], v[68:71]
	v_mfma_f32_16x16x32_bf16 v[64:67], v[180:183], v[212:215], v[64:67]
	v_mfma_f32_16x16x32_bf16 v[116:119], v[176:179], v[192:195], v[116:119]
	v_mfma_f32_16x16x32_bf16 v[112:115], v[184:187], v[192:195], v[112:115]
	v_mfma_f32_16x16x32_bf16 v[100:103], v[176:179], v[200:203], v[100:103]
	v_mfma_f32_16x16x32_bf16 v[96:99], v[184:187], v[200:203], v[96:99]
	v_mfma_f32_16x16x32_bf16 v[84:87], v[176:179], v[208:211], v[84:87]
	v_mfma_f32_16x16x32_bf16 v[80:83], v[184:187], v[208:211], v[80:83]
	v_mfma_f32_16x16x32_bf16 v[68:71], v[176:179], v[216:219], v[68:71]
	v_mfma_f32_16x16x32_bf16 v[64:67], v[184:187], v[216:219], v[64:67]
	s_setprio 0
	s_barrier
	s_add_i32 s51, s51, s30
	v_lshl_add_u64 v[146:147], s[4:5], 0, v[152:153]
	s_mov_b32 m0, s51
	ds_read_b128 v[188:191], v151 offset:16384
	ds_read_b128 v[192:195], v151 offset:17408
	ds_read_b128 v[196:199], v151 offset:18432
	ds_read_b128 v[200:203], v151 offset:19456
	ds_read_b128 v[204:207], v151 offset:20480
	ds_read_b128 v[208:211], v151 offset:21504
	ds_read_b128 v[212:215], v151 offset:22528
	ds_read_b128 v[216:219], v151 offset:23552
	global_load_lds_dwordx4 v[146:147], off
	s_add_i32 m0, s51, 0x2000
	s_add_u32 s52, s4, 0x80000
	v_lshl_add_u64 v[220:221], s[4:5], 0, v[128:129]
	s_addc_u32 s53, s5, 0
	s_add_i32 s51, s54, s30
	global_load_lds_dwordx4 v[220:221], off
	v_lshl_add_u64 v[222:223], s[52:53], 0, v[152:153]
	s_mov_b32 m0, s51
	v_lshl_add_u64 v[224:225], s[28:29], 0, v[130:131]
	global_load_lds_dwordx4 v[222:223], off
	v_lshl_add_u64 v[222:223], s[52:53], 0, v[128:129]
	s_add_i32 m0, s51, 0x2000
	s_nop 0
	global_load_lds_dwordx4 v[222:223], off
	v_lshl_add_u64 v[222:223], s[28:29], 0, v[132:133]
	s_mov_b32 m0, s35
	s_nop 0
	global_load_lds_dwordx4 v[222:223], off
	s_mov_b32 m0, s36
	s_nop 0
	global_load_lds_dwordx4 v[224:225], off
	s_waitcnt vmcnt(8)
	s_waitcnt lgkmcnt(0)
	s_setprio 1
	s_barrier
	v_mfma_f32_16x16x32_bf16 v[60:63], v[138:141], v[188:191], v[60:63]
	v_mfma_f32_16x16x32_bf16 v[56:59], v[164:167], v[188:191], v[56:59]
	v_mfma_f32_16x16x32_bf16 v[44:47], v[138:141], v[196:199], v[44:47]
	v_mfma_f32_16x16x32_bf16 v[40:43], v[164:167], v[196:199], v[40:43]
	v_mfma_f32_16x16x32_bf16 v[28:31], v[138:141], v[204:207], v[28:31]
	v_mfma_f32_16x16x32_bf16 v[24:27], v[164:167], v[204:207], v[24:27]
	v_mfma_f32_16x16x32_bf16 v[12:15], v[138:141], v[212:215], v[12:15]
	v_mfma_f32_16x16x32_bf16 v[8:11], v[164:167], v[212:215], v[8:11]
	v_mfma_f32_16x16x32_bf16 v[60:63], v[142:145], v[192:195], v[60:63]
	v_mfma_f32_16x16x32_bf16 v[56:59], v[168:171], v[192:195], v[56:59]
	v_mfma_f32_16x16x32_bf16 v[44:47], v[142:145], v[200:203], v[44:47]
	v_mfma_f32_16x16x32_bf16 v[40:43], v[168:171], v[200:203], v[40:43]
	v_mfma_f32_16x16x32_bf16 v[28:31], v[142:145], v[208:211], v[28:31]
	v_mfma_f32_16x16x32_bf16 v[24:27], v[168:171], v[208:211], v[24:27]
	v_mfma_f32_16x16x32_bf16 v[12:15], v[142:145], v[216:219], v[12:15]
	v_mfma_f32_16x16x32_bf16 v[8:11], v[168:171], v[216:219], v[8:11]
	s_setprio 0
	s_setprio 1
	v_mfma_f32_16x16x32_bf16 v[52:55], v[172:175], v[188:191], v[52:55]
	v_mfma_f32_16x16x32_bf16 v[48:51], v[180:183], v[188:191], v[48:51]
	v_mfma_f32_16x16x32_bf16 v[36:39], v[172:175], v[196:199], v[36:39]
	v_mfma_f32_16x16x32_bf16 v[32:35], v[180:183], v[196:199], v[32:35]
	v_mfma_f32_16x16x32_bf16 v[20:23], v[172:175], v[204:207], v[20:23]
	v_mfma_f32_16x16x32_bf16 v[16:19], v[180:183], v[204:207], v[16:19]
	v_mfma_f32_16x16x32_bf16 v[4:7], v[172:175], v[212:215], v[4:7]
	v_mfma_f32_16x16x32_bf16 v[0:3], v[180:183], v[212:215], v[0:3]
	v_mfma_f32_16x16x32_bf16 v[52:55], v[176:179], v[192:195], v[52:55]
	v_mfma_f32_16x16x32_bf16 v[48:51], v[184:187], v[192:195], v[48:51]
	v_mfma_f32_16x16x32_bf16 v[36:39], v[176:179], v[200:203], v[36:39]
	v_mfma_f32_16x16x32_bf16 v[32:35], v[184:187], v[200:203], v[32:35]
	v_mfma_f32_16x16x32_bf16 v[20:23], v[176:179], v[208:211], v[20:23]
	v_mfma_f32_16x16x32_bf16 v[16:19], v[184:187], v[208:211], v[16:19]
	v_mfma_f32_16x16x32_bf16 v[4:7], v[176:179], v[216:219], v[4:7]
	v_mfma_f32_16x16x32_bf16 v[0:3], v[184:187], v[216:219], v[0:3]
	s_setprio 0
	s_barrier
; #define PG8_STAGE(bufoff, gbase, voff) do { _Pragma("unroll") for (int _i = 0; _i < 2; ++_i) \
;         __builtin_amdgcn_global_load_lds((const unsigned*)((const char*)(gbase) + (voff)[_i]), (PG8_LAS unsigned*)(lds + (bufoff) + ldsw + _i * 8192), 16, 0, 0); } while (0)
; #define PG8_LDA(dst, b, h) do { _Pragma("unroll") for (int m = 0; m < 4; ++m) _Pragma("unroll") for (int k = 0; k < 2; ++k) dst[m][k] = *(const PG8_LAS bf16x8*)(lds + PG8_SA(b, h) + aoff + m * 2048 + k * 1024); } while (0)
; #define PG8_LDB(dst, b, h) do { _Pragma("unroll") for (int n = 0; n < 2; ++n) _Pragma("unroll") for (int k = 0; k < 2; ++k) dst[n][k] = *(const PG8_LAS bf16x8*)(lds + PG8_SB(b, h) + boff + n * 2048 + k * 1024); } while (0)
; #define PG8_MMA(ai, bj, At, Bt) do { __builtin_amdgcn_s_setprio(1); _Pragma("unroll") for (int m = 0; m < 4; ++m) _Pragma("unroll") for (int n = 0; n < 2; ++n) _Pragma("unroll") for (int k = 0; k < 2; ++k) \
;         acc[ai][bj][m][n] = __builtin_amdgcn_mfma_f32_16x16x32_bf16(Bt[n][k], At[m][k], acc[ai][bj][m][n], 0, 0, 0); __builtin_amdgcn_s_setprio(0); } while (0)
; #define PG8_WAIT_V(n) asm volatile("s_waitcnt vmcnt(" #n ")" ::: "memory")
; #define PG8_WAIT_L(n) asm volatile("s_waitcnt lgkmcnt(" #n ")" ::: "memory")
; #define PG8_BAR __builtin_amdgcn_s_barrier()
; #define PG8_SCHED __builtin_amdgcn_sched_barrier(0)
; template <class Epi, class Sched, bool ALIGN_EPI = false, bool SP2 = false>
; __device__ __forceinline__ void gemm_phase(PG8_LAS unsigned char* lds, const Gemm g, const Sched& S, const Epi& E) {
;     ...
;             PG8_LDB(B0, 1, 0); PG8_LDB(B1, 1, 1); PG8_SCHED; PG8_LDA(At, 1, 0); PG8_STAGE(PG8_SA(0, 1), a2 + hstep, voffA);
;             PG8_WAIT_V(8); PG8_WAIT_L(0); PG8_BAR; PG8_MMA(0, 0, At, B0); PG8_MMA(0, 1, At, B1); PG8_BAR; PG8_SCHED;
	s_add_i32 s51, 0, 0x18000
	s_add_i32 s52, 0, 0x1c000
	v_add_u32_e32 v168, s51, v150
	v_add_u32_e32 v184, s52, v150
	ds_read_b128 v[138:141], v168
	ds_read_b128 v[142:145], v168 offset:1024
	ds_read_b128 v[164:167], v168 offset:2048
	ds_read_b128 v[168:171], v168 offset:3072
	ds_read_b128 v[172:175], v184
	ds_read_b128 v[176:179], v184 offset:1024
	ds_read_b128 v[180:183], v184 offset:2048
	ds_read_b128 v[184:187], v184 offset:3072
	s_add_u32 s28, s28, 0x80000
	s_addc_u32 s29, s29, 0
	s_mov_b32 m0, s37
	v_lshl_add_u64 v[226:227], s[28:29], 0, v[132:133]
	ds_read_b128 v[188:191], v151 offset:32768
	ds_read_b128 v[192:195], v151 offset:33792
	ds_read_b128 v[196:199], v151 offset:34816
	ds_read_b128 v[200:203], v151 offset:35840
	ds_read_b128 v[204:207], v151 offset:36864
	ds_read_b128 v[208:211], v151 offset:37888
	ds_read_b128 v[212:215], v151 offset:38912
	ds_read_b128 v[216:219], v151 offset:39936
	global_load_lds_dwordx4 v[226:227], off
	v_lshl_add_u64 v[226:227], s[28:29], 0, v[130:131]
	s_mov_b32 m0, s38
	s_nop 0
	global_load_lds_dwordx4 v[226:227], off
	s_waitcnt vmcnt(8)
	s_waitcnt lgkmcnt(0)
	s_setprio 1
	s_barrier
	v_mfma_f32_16x16x32_bf16 v[124:127], v[138:141], v[188:191], v[124:127]
	v_mfma_f32_16x16x32_bf16 v[120:123], v[164:167], v[188:191], v[120:123]
	v_mfma_f32_16x16x32_bf16 v[108:111], v[138:141], v[196:199], v[108:111]
	v_mfma_f32_16x16x32_bf16 v[104:107], v[164:167], v[196:199], v[104:107]
	v_mfma_f32_16x16x32_bf16 v[92:95], v[138:141], v[204:207], v[92:95]
	v_mfma_f32_16x16x32_bf16 v[88:91], v[164:167], v[204:207], v[88:91]
	v_mfma_f32_16x16x32_bf16 v[76:79], v[138:141], v[212:215], v[76:79]
	v_mfma_f32_16x16x32_bf16 v[72:75], v[164:167], v[212:215], v[72:75]
	v_mfma_f32_16x16x32_bf16 v[124:127], v[142:145], v[192:195], v[124:127]
	v_mfma_f32_16x16x32_bf16 v[120:123], v[168:171], v[192:195], v[120:123]
	v_mfma_f32_16x16x32_bf16 v[108:111], v[142:145], v[200:203], v[108:111]
	v_mfma_f32_16x16x32_bf16 v[104:107], v[168:171], v[200:203], v[104:107]
	v_mfma_f32_16x16x32_bf16 v[92:95], v[142:145], v[208:211], v[92:95]
	v_mfma_f32_16x16x32_bf16 v[88:91], v[168:171], v[208:211], v[88:91]
	v_mfma_f32_16x16x32_bf16 v[76:79], v[142:145], v[216:219], v[76:79]
	v_mfma_f32_16x16x32_bf16 v[72:75], v[168:171], v[216:219], v[72:75]
	s_setprio 0
	s_setprio 1
	v_mfma_f32_16x16x32_bf16 v[116:119], v[172:175], v[188:191], v[116:119]
	v_mfma_f32_16x16x32_bf16 v[112:115], v[180:183], v[188:191], v[112:115]
	v_mfma_f32_16x16x32_bf16 v[100:103], v[172:175], v[196:199], v[100:103]
	v_mfma_f32_16x16x32_bf16 v[96:99], v[180:183], v[196:199], v[96:99]
	v_mfma_f32_16x16x32_bf16 v[84:87], v[172:175], v[204:207], v[84:87]
	v_mfma_f32_16x16x32_bf16 v[80:83], v[180:183], v[204:207], v[80:83]
	v_mfma_f32_16x16x32_bf16 v[68:71], v[172:175], v[212:215], v[68:71]
	v_mfma_f32_16x16x32_bf16 v[64:67], v[180:183], v[212:215], v[64:67]
	v_mfma_f32_16x16x32_bf16 v[116:119], v[176:179], v[192:195], v[116:119]
	v_mfma_f32_16x16x32_bf16 v[112:115], v[184:187], v[192:195], v[112:115]
	v_mfma_f32_16x16x32_bf16 v[100:103], v[176:179], v[200:203], v[100:103]
	v_mfma_f32_16x16x32_bf16 v[96:99], v[184:187], v[200:203], v[96:99]
	v_mfma_f32_16x16x32_bf16 v[84:87], v[176:179], v[208:211], v[84:87]
	v_mfma_f32_16x16x32_bf16 v[80:83], v[184:187], v[208:211], v[80:83]
	v_mfma_f32_16x16x32_bf16 v[68:71], v[176:179], v[216:219], v[68:71]
	v_mfma_f32_16x16x32_bf16 v[64:67], v[184:187], v[216:219], v[64:67]
	s_setprio 0
	s_barrier
; #define PG8_STAGE(bufoff, gbase, voff) do { _Pragma("unroll") for (int _i = 0; _i < 2; ++_i) \
;         __builtin_amdgcn_global_load_lds((const unsigned*)((const char*)(gbase) + (voff)[_i]), (PG8_LAS unsigned*)(lds + (bufoff) + ldsw + _i * 8192), 16, 0, 0); } while (0)
; #define PG8_LDA(dst, b, h) do { _Pragma("unroll") for (int m = 0; m < 4; ++m) _Pragma("unroll") for (int k = 0; k < 2; ++k) dst[m][k] = *(const PG8_LAS bf16x8*)(lds + PG8_SA(b, h) + aoff + m * 2048 + k * 1024); } while (0)
; #define PG8_MMA(ai, bj, At, Bt) do { __builtin_amdgcn_s_setprio(1); _Pragma("unroll") for (int m = 0; m < 4; ++m) _Pragma("unroll") for (int n = 0; n < 2; ++n) _Pragma("unroll") for (int k = 0; k < 2; ++k) \
;         acc[ai][bj][m][n] = __builtin_amdgcn_mfma_f32_16x16x32_bf16(Bt[n][k], At[m][k], acc[ai][bj][m][n], 0, 0, 0); __builtin_amdgcn_s_setprio(0); } while (0)
; #define PG8_WAIT_V(n) asm volatile("s_waitcnt vmcnt(" #n ")" ::: "memory")
; #define PG8_WAIT_L(n) asm volatile("s_waitcnt lgkmcnt(" #n ")" ::: "memory")
; #define PG8_BAR __builtin_amdgcn_s_barrier()
; #define PG8_SCHED __builtin_amdgcn_sched_barrier(0)
; template <class Epi, class Sched, bool ALIGN_EPI = false, bool SP2 = false>
; __device__ __forceinline__ void gemm_phase(PG8_LAS unsigned char* lds, const Gemm g, const Sched& S, const Epi& E) {
;     ...
;             PG8_LDA(At, 1, 1); PG8_STAGE(PG8_SB(1, 0), b3, voffB); PG8_STAGE(PG8_SB(1, 1), b3 + hstep, voffB); PG8_STAGE(PG8_SA(1, 0), a3, voffA);
;             PG8_WAIT_V(8); PG8_WAIT_L(0); PG8_BAR; PG8_MMA(1, 0, At, B0); PG8_MMA(1, 1, At, B1); PG8_BAR; PG8_SCHED;
;     ...
;         if constexpr (ALIGN_EPI) { if (wr == 0) PG8_BAR; }
	s_add_i32 s28, s51, s30
	v_lshl_add_u64 v[146:147], v[146:147], 0, s[74:75]
	s_mov_b32 m0, s28
	ds_read_b128 v[188:191], v151 offset:49152
	ds_read_b128 v[192:195], v151 offset:50176
	ds_read_b128 v[196:199], v151 offset:51200
	ds_read_b128 v[200:203], v151 offset:52224
	ds_read_b128 v[204:207], v151 offset:53248
	ds_read_b128 v[208:211], v151 offset:54272
	ds_read_b128 v[212:215], v151 offset:55296
	ds_read_b128 v[216:219], v151 offset:56320
	global_load_lds_dwordx4 v[146:147], off
	s_add_i32 m0, s28, 0x2000
	s_add_u32 s4, s4, 0x80080
	v_lshl_add_u64 v[146:147], v[220:221], 0, s[74:75]
	s_addc_u32 s5, s5, 0
	s_add_i32 s28, s52, s30
	global_load_lds_dwordx4 v[146:147], off
	v_lshl_add_u64 v[146:147], s[4:5], 0, v[152:153]
	s_mov_b32 m0, s28
	s_nop 0
	global_load_lds_dwordx4 v[146:147], off
	v_lshl_add_u64 v[146:147], s[4:5], 0, v[128:129]
	s_add_i32 m0, s28, 0x2000
	s_nop 0
	global_load_lds_dwordx4 v[146:147], off
	v_lshl_add_u64 v[146:147], v[222:223], 0, s[74:75]
	s_mov_b32 m0, s42
	s_nop 0
	global_load_lds_dwordx4 v[146:147], off
	v_lshl_add_u64 v[146:147], v[224:225], 0, s[74:75]
	s_mov_b32 m0, s43
	s_nop 0
	global_load_lds_dwordx4 v[146:147], off
	s_waitcnt vmcnt(8)
	s_waitcnt lgkmcnt(0)
	s_setprio 1
	s_barrier
	v_mfma_f32_16x16x32_bf16 v[60:63], v[138:141], v[188:191], v[60:63]
	v_mfma_f32_16x16x32_bf16 v[56:59], v[164:167], v[188:191], v[56:59]
	v_mfma_f32_16x16x32_bf16 v[44:47], v[138:141], v[196:199], v[44:47]
	v_mfma_f32_16x16x32_bf16 v[40:43], v[164:167], v[196:199], v[40:43]
	v_mfma_f32_16x16x32_bf16 v[28:31], v[138:141], v[204:207], v[28:31]
	v_mfma_f32_16x16x32_bf16 v[24:27], v[164:167], v[204:207], v[24:27]
	v_mfma_f32_16x16x32_bf16 v[12:15], v[138:141], v[212:215], v[12:15]
	v_mfma_f32_16x16x32_bf16 v[8:11], v[164:167], v[212:215], v[8:11]
	v_mfma_f32_16x16x32_bf16 v[60:63], v[142:145], v[192:195], v[60:63]
	v_mfma_f32_16x16x32_bf16 v[56:59], v[168:171], v[192:195], v[56:59]
	v_mfma_f32_16x16x32_bf16 v[44:47], v[142:145], v[200:203], v[44:47]
	v_mfma_f32_16x16x32_bf16 v[40:43], v[168:171], v[200:203], v[40:43]
	v_mfma_f32_16x16x32_bf16 v[28:31], v[142:145], v[208:211], v[28:31]
	v_mfma_f32_16x16x32_bf16 v[24:27], v[168:171], v[208:211], v[24:27]
	v_mfma_f32_16x16x32_bf16 v[12:15], v[142:145], v[216:219], v[12:15]
	v_mfma_f32_16x16x32_bf16 v[8:11], v[168:171], v[216:219], v[8:11]
	s_setprio 0
	s_setprio 1
	v_mfma_f32_16x16x32_bf16 v[52:55], v[172:175], v[188:191], v[52:55]
	v_mfma_f32_16x16x32_bf16 v[48:51], v[180:183], v[188:191], v[48:51]
	v_mfma_f32_16x16x32_bf16 v[36:39], v[172:175], v[196:199], v[36:39]
	v_mfma_f32_16x16x32_bf16 v[32:35], v[180:183], v[196:199], v[32:35]
	v_mfma_f32_16x16x32_bf16 v[20:23], v[172:175], v[204:207], v[20:23]
	v_mfma_f32_16x16x32_bf16 v[16:19], v[180:183], v[204:207], v[16:19]
	v_mfma_f32_16x16x32_bf16 v[4:7], v[172:175], v[212:215], v[4:7]
	v_mfma_f32_16x16x32_bf16 v[0:3], v[180:183], v[212:215], v[0:3]
	v_mfma_f32_16x16x32_bf16 v[52:55], v[176:179], v[192:195], v[52:55]
	v_mfma_f32_16x16x32_bf16 v[48:51], v[184:187], v[192:195], v[48:51]
	v_mfma_f32_16x16x32_bf16 v[36:39], v[176:179], v[200:203], v[36:39]
	v_mfma_f32_16x16x32_bf16 v[32:35], v[184:187], v[200:203], v[32:35]
	v_mfma_f32_16x16x32_bf16 v[20:23], v[176:179], v[208:211], v[20:23]
	v_mfma_f32_16x16x32_bf16 v[16:19], v[184:187], v[208:211], v[16:19]
	v_mfma_f32_16x16x32_bf16 v[4:7], v[176:179], v[216:219], v[4:7]
	v_mfma_f32_16x16x32_bf16 v[0:3], v[184:187], v[216:219], v[0:3]
	s_setprio 0
	s_barrier
	s_add_i32 s50, s50, 2
	s_add_u32 s0, s0, 0x100
	s_addc_u32 s1, s1, 0
	s_add_u32 s48, s48, 0x100
	s_addc_u32 s49, s49, 0
	s_cmp_gt_u32 s50, 29
	s_cbranch_scc0 .LBB0_221
	s_and_b64 vcc, exec, s[20:21]
	s_cbranch_vccz .LBB0_224
	s_barrier

; __device__ __forceinline__ unsigned xb_ld(unsigned* p)              { return __hip_atomic_load(p, __ATOMIC_RELAXED, __HIP_MEMORY_SCOPE_AGENT); }
; __device__ __forceinline__ unsigned xb_add(unsigned* p, unsigned v) { return __hip_atomic_fetch_add(p, v, __ATOMIC_RELAXED, __HIP_MEMORY_SCOPE_AGENT); }
; #define XB_SPIN(cond, bar) do { unsigned _sp = 0; while (cond) { __builtin_amdgcn_s_sleep(1); \
;     if ((++_sp & 255u) == 0u) { if (xb_ld(&(bar)[XB_TMO])) break; if (_sp > XB_SPIN_CAP) { atomicAdd(&(bar)[XB_TMO], 1u); break; } } } } while (0)
; __device__ __forceinline__ void xcd_barrier(const XcdBarrier& b) {
;     ...
;         const unsigned old = xb_add(&bar[XB_XSUB(b.x)], 1u);
;         const unsigned gen = old / nloc;
;         if (old + 1u == (gen + 1u) * nloc) {
;             __builtin_amdgcn_fence(__ATOMIC_RELEASE, "agent");
;             asm volatile("s_waitcnt vmcnt(0)" ::: "memory");
;             const unsigned og = xb_add(&bar[XB_TOP], 1u);
;             const unsigned tg = og / nx;
;             if (og + 1u == (tg + 1u) * nx) xb_add(&bar[XB_TOPGEN], 1u);
;             else XB_SPIN(xb_ld(&bar[XB_TOPGEN]) == tg, bar);
;             __builtin_amdgcn_fence(__ATOMIC_ACQUIRE, "agent");
;             xb_add(&bar[XB_XGEN(b.x)], 1u);
;             asm volatile("s_waitcnt vmcnt(0)" ::: "memory");
;         } else {
;             XB_SPIN(xb_ld(&bar[XB_XGEN(b.x)]) == gen, bar);
;             __builtin_amdgcn_fence(__ATOMIC_ACQUIRE, "agent");
.LBB0_295:
	s_or_b64 exec, exec, s[8:9]
	v_cvt_f32_u32_e32 v4, v2
	s_waitcnt vmcnt(0)
	v_readfirstlane_b32 s6, v3
	v_sub_u32_e32 v3, 0, v2
	v_rcp_iflag_f32_e32 v4, v4
	v_add_u32_e32 v5, s6, v1
	v_mul_f32_e32 v4, 0x4f7ffffe, v4
	v_cvt_u32_f32_e32 v4, v4
	v_mul_lo_u32 v1, v3, v4
	v_mul_hi_u32 v1, v4, v1
	v_add_u32_e32 v1, v4, v1
	v_mul_hi_u32 v1, v5, v1
	v_mul_lo_u32 v3, v1, v2
	v_sub_u32_e32 v3, v5, v3
	v_add_u32_e32 v4, 1, v1
	v_cmp_ge_u32_e32 vcc, v3, v2
	s_nop 1
	v_cndmask_b32_e32 v1, v1, v4, vcc
	v_sub_u32_e32 v4, v3, v2
	v_cndmask_b32_e32 v3, v3, v4, vcc
	v_add_u32_e32 v4, 1, v1
	v_cmp_ge_u32_e32 vcc, v3, v2
	v_add_u32_e32 v3, 1, v5
	s_nop 0
	v_cndmask_b32_e32 v1, v1, v4, vcc
	v_mul_lo_u32 v4, v2, v1
	v_add_u32_e32 v2, v4, v2
	v_cmp_ne_u32_e32 vcc, v3, v2
	s_and_saveexec_b64 s[6:7], vcc
	s_xor_b64 s[6:7], exec, s[6:7]
	s_cbranch_execz .LBB0_309
	s_waitcnt lgkmcnt(0)
	buffer_inv sc1
	v_mad_u32_u24 v1, v1, v0, v0
	v_mov_b32_e32 v0, 0x2e403000
	global_load_dword v0, v0, s[2:3] offset:1024 sc1
	s_add_u32 s12, s2, 0x2e403400
	s_addc_u32 s13, s3, 0
	s_waitcnt vmcnt(0)
	v_cmp_lt_u32_e32 vcc, v0, v1
	s_and_saveexec_b64 s[8:9], vcc
	s_cbranch_execz .LBB0_308
	s_add_u32 s10, s2, 0x2e400200
	s_addc_u32 s11, s3, 0
	s_mov_b32 s24, 1
	s_mov_b64 s[14:15], 0
	s_branch .LBB0_299

; __device__ __forceinline__ unsigned xb_ld(unsigned* p)              { return __hip_atomic_load(p, __ATOMIC_RELAXED, __HIP_MEMORY_SCOPE_AGENT); }
; #define XB_SPIN(cond, bar) do { unsigned _sp = 0; while (cond) { __builtin_amdgcn_s_sleep(1); \
;     if ((++_sp & 255u) == 0u) { if (xb_ld(&(bar)[XB_TMO])) break; if (_sp > XB_SPIN_CAP) { atomicAdd(&(bar)[XB_TMO], 1u); break; } } } } while (0)
; __device__ __forceinline__ void xcd_barrier(const XcdBarrier& b) {
;     ...
;             XB_SPIN(xb_ld(&bar[XB_XGEN(b.x)]) == gen, bar);
.LBB0_301:
	global_load_dword v0, v153, s[12:13] sc1
	s_add_i32 s24, s24, 1
	s_mov_b64 s[20:21], -1
	s_waitcnt vmcnt(0)
	v_cmp_ge_u32_e32 vcc, v0, v1
	s_orn2_b64 s[18:19], vcc, exec
	s_branch .LBB0_298

; #define PG8_STAGE(bufoff, gbase, voff) do { _Pragma("unroll") for (int _i = 0; _i < 2; ++_i) \
;         __builtin_amdgcn_global_load_lds((const unsigned*)((const char*)(gbase) + (voff)[_i]), (PG8_LAS unsigned*)(lds + (bufoff) + ldsw + _i * 8192), 16, 0, 0); } while (0)
; #define PG8_WAIT_V(n) asm volatile("s_waitcnt vmcnt(" #n ")" ::: "memory")
; #define PG8_BAR __builtin_amdgcn_s_barrier()
; template <class Epi, class Sched, bool ALIGN_EPI = false, bool SP2 = false>
; __device__ __forceinline__ void gemm_phase(PG8_LAS unsigned char* lds, const Gemm g, const Sched& S, const Epi& E) {
;     int tid_l = threadIdx.x; asm volatile("" : "+v"(tid_l)); const int tid = tid_l, wid = __builtin_amdgcn_readfirstlane(tid >> 6), lane = tid & 63, wr = wid >> 2, wc = wid & 3, fr = lane & 15, fq = lane >> 4;
;     const int K = g.K, nt = K / BK;
;     unsigned voffA[2], voffB[2];
; #pragma unroll
;     for (int i = 0; i < 2; ++i) { int R, C; stage_rc(tid * 16 + i * 8192, R, C); const int Rb = Epi::PERM ? ((R & ~31) + perm32(R & 31)) : R;
;         voffA[i] = (unsigned)(R * K + C) * 2u; voffB[i] = (unsigned)(Rb * K + C) * 2u; }
;     const size_t kstep = (size_t)(BK * 2);
;     const size_t hstep = (size_t)HALF * K * 2;
;     const size_t tstep = 2 * hstep;
;     const unsigned ldsw = (unsigned)wid * 1024u;
;     const int aoff = lds_byte(wr * 64 + fr, fq * 8), boff = lds_byte(wc * 32 + fr, fq * 8);
;     ...
;         PG8_WAIT_V(2); PG8_BAR;
;         PG8_STAGE(PG8_SB(1, 0), cB + kstep, voffB); PG8_STAGE(PG8_SA(1, 0), cA + kstep, voffA); PG8_STAGE(PG8_SB(1, 1), cB + hstep + kstep, voffB);
;         PG8_WAIT_V(6); PG8_BAR;
.LBB0_437:
	s_add_u32 s18, s14, 0x1a600000
	s_addc_u32 s19, s15, 0
	s_add_u32 s20, s14, 0x1ba00000
	s_addc_u32 s21, s15, 0
	s_add_u32 s22, s14, 0x1be00000
	s_addc_u32 s23, s15, 0
	s_add_u32 s24, s14, 0x1ce00000
	s_addc_u32 s25, s15, 0
	s_add_u32 s26, s14, 0x2e200000
	s_addc_u32 s27, s15, 0
	s_add_u32 s28, s14, 0x2e500000
	s_addc_u32 s29, s15, 0
	s_add_u32 s30, s14, 0x2e300000
	s_addc_u32 s31, s15, 0
	s_add_u32 s34, s14, 0x2e340000
	s_addc_u32 s35, s15, 0
	s_lshl_b64 s[36:37], s[72:73], 19
	s_add_u32 s3, s12, s36
	s_addc_u32 s33, s13, s37
	s_add_u32 s36, s3, 0x4140000
	s_addc_u32 s37, s33, 0
	s_lshl_b64 s[38:39], s[72:73], 15
	s_add_u32 s9, s12, s38
	s_addc_u32 s39, s13, s39
	s_add_u32 s38, s9, 0x4240000
	s_addc_u32 s39, s39, 0
	s_and_b32 s7, s7, 3
	s_add_i32 m0, s55, 0x18000
	v_lshl_add_u64 v[6:7], v[6:7], 0, s[74:75]
	s_mov_b64 s[86:87], s[72:73]
	s_lshl_b32 s70, s8, 6
	s_lshl_b32 s40, s8, 13
	s_lshl_b32 s71, s7, 5
	s_lshl_b32 s41, s7, 12
	s_waitcnt vmcnt(2)
	s_barrier
	global_load_lds_dwordx4 v[6:7], off
	v_lshl_add_u64 v[4:5], v[4:5], 0, s[74:75]
	s_add_i32 m0, s55, 0x1a000
	s_add_i32 s72, s55, 0x8000
	s_add_i32 s73, s55, 0xa000
	global_load_lds_dwordx4 v[4:5], off
	v_lshl_add_u64 v[0:1], v[0:1], 0, s[74:75]
	s_mov_b32 m0, s72
	s_add_u32 s8, s4, 0x80080
	global_load_lds_dwordx4 v[0:1], off
	v_lshl_add_u64 v[0:1], v[2:3], 0, s[74:75]
	s_mov_b32 m0, s73
	s_addc_u32 s9, s5, 0
	global_load_lds_dwordx4 v[0:1], off
	s_add_i32 m0, s55, 0x1c000
	v_lshl_add_u64 v[0:1], s[8:9], 0, v[166:167]
	global_load_lds_dwordx4 v[0:1], off
	v_lshl_add_u64 v[0:1], s[8:9], 0, v[170:171]
	s_add_i32 m0, s55, 0x1e000
	v_bfe_u32 v191, v8, 4, 2
	global_load_lds_dwordx4 v[0:1], off
	v_and_b32_e32 v190, 15, v8
	v_lshlrev_b32_e32 v0, 4, v191
	v_lshlrev_b32_e32 v1, 2, v8
	s_or_b32 s74, s71, 0xfffffb00
	v_lshl_or_b32 v0, v190, 6, v0
	v_and_b32_e32 v1, 32, v1
	s_cmpk_lt_u32 s6, 0x100
	v_bitop3_b32 v2, v0, s40, v1 bitop3:0xde
	v_bitop3_b32 v192, v0, s41, v1 bitop3:0xde
	s_cselect_b64 s[40:41], -1, 0
	s_and_b32 s77, s6, 0xc0
	s_or_b32 s75, s71, 0xfffffa00
	s_lshl_b32 s76, s7, 6
	s_or_b32 s78, s77, 0x400
	s_or_b32 s79, s77, 0x420
	s_lshl_b32 s6, s7, 7
	v_lshlrev_b32_e32 v0, 15, v9
	s_add_u32 s6, s14, s6
	v_and_b32_e32 v0, 0xffff0000, v0
	s_addc_u32 s8, s15, 0
	v_lshl_add_u32 v0, v10, 12, v0
	v_and_b32_e32 v1, 1, v9
	s_add_u32 s42, s6, 0x1b600000
	v_lshl_or_b32 v0, v1, 6, v0
	s_addc_u32 s43, s8, 0
	s_lshl_b32 s6, s7, 8
	v_lshl_add_u32 v172, v11, 1, v0
	v_lshlrev_b32_e32 v0, 15, v12
	s_add_u32 s3, s3, s6
	v_and_b32_e32 v0, 0xffff0000, v0
	s_waitcnt vmcnt(6)
	s_addc_u32 s6, s33, 0
	v_lshl_add_u32 v0, v13, 12, v0
	v_and_b32_e32 v1, 1, v12
	s_add_u32 s44, s3, 0x4040000
	v_lshl_or_b32 v0, v1, 6, v0
	s_addc_u32 s45, s6, 0
	v_mov_b32_e32 v173, v153
	v_lshl_add_u32 v174, v14, 1, v0
	v_mov_b32_e32 v175, v153
	s_mov_b32 s80, 0
	v_add_u32_e32 v193, 0, v2
	s_barrier
	s_branch .LBB0_440
	s_nop 0
.LBB0_438:
	s_mov_b64 s[0:1], 0

; #define PG8_STAGE(bufoff, gbase, voff) do { _Pragma("unroll") for (int _i = 0; _i < 2; ++_i) \
;         __builtin_amdgcn_global_load_lds((const unsigned*)((const char*)(gbase) + (voff)[_i]), (PG8_LAS unsigned*)(lds + (bufoff) + ldsw + _i * 8192), 16, 0, 0); } while (0)
; #define PG8_LDA(dst, b, h) do { _Pragma("unroll") for (int m = 0; m < 4; ++m) _Pragma("unroll") for (int k = 0; k < 2; ++k) dst[m][k] = *(const PG8_LAS bf16x8*)(lds + PG8_SA(b, h) + aoff + m * 2048 + k * 1024); } while (0)
; #define PG8_LDB(dst, b, h) do { _Pragma("unroll") for (int n = 0; n < 2; ++n) _Pragma("unroll") for (int k = 0; k < 2; ++k) dst[n][k] = *(const PG8_LAS bf16x8*)(lds + PG8_SB(b, h) + boff + n * 2048 + k * 1024); } while (0)
; #define PG8_WAIT_V(n) asm volatile("s_waitcnt vmcnt(" #n ")" ::: "memory")
; #define PG8_WAIT_L(n) asm volatile("s_waitcnt lgkmcnt(" #n ")" ::: "memory")
; #define PG8_BAR __builtin_amdgcn_s_barrier()
; template <class Epi, class Sched, bool ALIGN_EPI = false, bool SP2 = false>
; __device__ __forceinline__ void gemm_phase(PG8_LAS unsigned char* lds, const Gemm g, const Sched& S, const Epi& E) {
;     ...
;         const bool has_next = S.next(ui + 1, nxt);
;         const char* nA = has_next ? (const char*)g.A + (size_t)nxt.pm * tstep : cA; const char* nB = has_next ? (const char*)g.Bt + (size_t)nxt.pn * tstep : cB;
;         for (int t = 0; t < nt; t += 2) {
;             const bool last = (t == nt - 2);
;             const char* a1 = cA + (size_t)(t + 1) * kstep;
;             const char* a2 = last ? nA : cA + (size_t)(t + 2) * kstep; const char* b2 = last ? nB : cB + (size_t)(t + 2) * kstep;
;             const char* a3 = a2 + kstep; const char* b3 = b2 + kstep;
;             if (last && has_next) S.a_ready(nxt);
;             if constexpr (SP2) {
;             PG8_LDB(B0, 0, 0); PG8_LDB(B1, 0, 1); PG8_SCHED; PG8_LDA(At, 0, 0); PG8_STAGE(PG8_SA(1, 1), a1 + hstep, voffA);
;             PG8_WAIT_V(8); PG8_WAIT_L(0); PG8_BAR; PG8_MMA(0, 0, At, B0); PG8_MMA(0, 1, At, B1); PG8_BAR; PG8_SCHED;
;     ...
; #pragma unroll
;         for (int a = 0; a < 2; ++a)
; #pragma unroll
;             for (int b = 0; b < 2; ++b)
; #pragma unroll
;                 for (int m = 0; m < 4; ++m)
; #pragma unroll
;                     for (int n = 0; n < 2; ++n) acc[a][b][m][n] = (f32x4){0.f, 0.f, 0.f, 0.f};
;         cur = nxt; cA = nA; cB = nB; ++ui;
.LBB0_446:
	s_ashr_i32 s49, s48, 31
	s_lshl_b64 s[8:9], s[48:49], 20
	s_add_u32 s50, s62, s8
	s_addc_u32 s51, s63, s9
	s_and_b64 s[8:9], s[6:7], exec
	s_cselect_b32 s3, s51, s1
	s_cselect_b32 s33, s50, s0
	s_ashr_i32 s47, s46, 31
	s_lshl_b64 s[8:9], s[46:47], 20
	s_add_u32 s52, s64, s8
	s_addc_u32 s53, s65, s9
	s_and_b64 s[8:9], s[6:7], exec
	s_cselect_b32 s47, s53, s5
	s_cselect_b32 s49, s52, s4
	s_add_u32 s0, s0, 0x80080
	s_addc_u32 s1, s1, 0
	s_add_u32 s56, s4, 0x100
	s_waitcnt vmcnt(0)
	v_mov_b32_e32 v32, 0
	s_addc_u32 s57, s5, 0
	s_mov_b32 s58, -2
	v_mov_b32_e32 v33, v32
	v_mov_b32_e32 v34, v32
	v_mov_b32_e32 v35, v32
	v_mov_b32_e32 v36, v32
	v_mov_b32_e32 v37, v32
	v_mov_b32_e32 v38, v32
	v_mov_b32_e32 v39, v32
	v_mov_b32_e32 v48, v32
	v_mov_b32_e32 v49, v32
	v_mov_b32_e32 v50, v32
	v_mov_b32_e32 v51, v32
	v_mov_b32_e32 v52, v32
	v_mov_b32_e32 v53, v32
	v_mov_b32_e32 v54, v32
	v_mov_b32_e32 v55, v32
	v_mov_b32_e32 v64, v32
	v_mov_b32_e32 v65, v32
	v_mov_b32_e32 v66, v32
	v_mov_b32_e32 v67, v32
	v_mov_b32_e32 v68, v32
	v_mov_b32_e32 v69, v32
	v_mov_b32_e32 v70, v32
	v_mov_b32_e32 v71, v32
	v_mov_b32_e32 v80, v32
	v_mov_b32_e32 v81, v32
	v_mov_b32_e32 v82, v32
	v_mov_b32_e32 v83, v32
	v_mov_b32_e32 v84, v32
	v_mov_b32_e32 v85, v32
	v_mov_b32_e32 v86, v32
	v_mov_b32_e32 v87, v32
	v_mov_b32_e32 v40, v32
	v_mov_b32_e32 v41, v32
	v_mov_b32_e32 v42, v32
	v_mov_b32_e32 v43, v32
	v_mov_b32_e32 v44, v32
	v_mov_b32_e32 v45, v32
	v_mov_b32_e32 v46, v32
	v_mov_b32_e32 v47, v32
	v_mov_b32_e32 v56, v32
	v_mov_b32_e32 v57, v32
	v_mov_b32_e32 v58, v32
	v_mov_b32_e32 v59, v32
	v_mov_b32_e32 v60, v32
	v_mov_b32_e32 v61, v32
	v_mov_b32_e32 v62, v32
	v_mov_b32_e32 v63, v32
	v_mov_b32_e32 v72, v32
	v_mov_b32_e32 v73, v32
	v_mov_b32_e32 v74, v32
	v_mov_b32_e32 v75, v32
	v_mov_b32_e32 v76, v32
	v_mov_b32_e32 v77, v32
	v_mov_b32_e32 v78, v32
	v_mov_b32_e32 v79, v32
	v_mov_b32_e32 v88, v32
	v_mov_b32_e32 v89, v32
	v_mov_b32_e32 v90, v32
	v_mov_b32_e32 v91, v32
	v_mov_b32_e32 v92, v32
	v_mov_b32_e32 v93, v32
	v_mov_b32_e32 v94, v32
	v_mov_b32_e32 v95, v32
	v_mov_b32_e32 v96, v32
	v_mov_b32_e32 v97, v32
	v_mov_b32_e32 v98, v32
	v_mov_b32_e32 v99, v32
	v_mov_b32_e32 v100, v32
	v_mov_b32_e32 v101, v32
	v_mov_b32_e32 v102, v32
	v_mov_b32_e32 v103, v32
	v_mov_b32_e32 v112, v32
	v_mov_b32_e32 v113, v32
	v_mov_b32_e32 v114, v32
	v_mov_b32_e32 v115, v32
	v_mov_b32_e32 v116, v32
	v_mov_b32_e32 v117, v32
	v_mov_b32_e32 v118, v32
	v_mov_b32_e32 v119, v32
	v_mov_b32_e32 v0, v32
	v_mov_b32_e32 v1, v32
	v_mov_b32_e32 v2, v32
	v_mov_b32_e32 v3, v32
	v_mov_b32_e32 v4, v32
	v_mov_b32_e32 v5, v32
	v_mov_b32_e32 v6, v32
	v_mov_b32_e32 v7, v32
	v_mov_b32_e32 v16, v32
	v_mov_b32_e32 v17, v32
	v_mov_b32_e32 v18, v32
	v_mov_b32_e32 v19, v32
	v_mov_b32_e32 v20, v32
	v_mov_b32_e32 v21, v32
	v_mov_b32_e32 v22, v32
	v_mov_b32_e32 v23, v32
	v_mov_b32_e32 v104, v32
	v_mov_b32_e32 v105, v32
	v_mov_b32_e32 v106, v32
	v_mov_b32_e32 v107, v32
	v_mov_b32_e32 v108, v32
	v_mov_b32_e32 v109, v32
	v_mov_b32_e32 v110, v32
	v_mov_b32_e32 v111, v32
	v_mov_b32_e32 v120, v32
	v_mov_b32_e32 v121, v32
	v_mov_b32_e32 v122, v32
	v_mov_b32_e32 v123, v32
	v_mov_b32_e32 v124, v32
	v_mov_b32_e32 v125, v32
	v_mov_b32_e32 v126, v32
	v_mov_b32_e32 v127, v32
	v_mov_b32_e32 v8, v32
	v_mov_b32_e32 v9, v32
	v_mov_b32_e32 v10, v32
	v_mov_b32_e32 v11, v32
	v_mov_b32_e32 v12, v32
	v_mov_b32_e32 v13, v32
	v_mov_b32_e32 v14, v32
	v_mov_b32_e32 v15, v32
	v_mov_b32_e32 v24, v32
	v_mov_b32_e32 v25, v32
	v_mov_b32_e32 v26, v32
	v_mov_b32_e32 v27, v32
	v_mov_b32_e32 v28, v32
	v_mov_b32_e32 v29, v32
	v_mov_b32_e32 v30, v32
	v_mov_b32_e32 v31, v32
	s_mov_b64 vcc, 0x80
.LBB0_447:
	s_add_u32 s4, s0, 0xfff80080
	s_addc_u32 s5, s1, -1
	s_add_i32 s59, 0, 0x10000
	s_cmp_eq_u32 s58, 28
	s_cselect_b32 s9, s3, s5
	s_cselect_b32 s8, s33, s4
	s_cselect_b32 s5, s47, s57
	s_cselect_b32 s4, s49, s56
	s_add_i32 s81, 0, 0x14000
	v_add_u32_e32 v140, s59, v192
	v_add_u32_e32 v152, s81, v192
	ds_read_b128 v[128:131], v140
	ds_read_b128 v[132:135], v140 offset:1024
	ds_read_b128 v[136:139], v140 offset:2048
	ds_read_b128 v[140:143], v140 offset:3072
	ds_read_b128 v[144:147], v152
	ds_read_b128 v[148:151], v152 offset:1024
	ds_read_b128 v[176:179], v152 offset:2048
	ds_read_b128 v[180:183], v152 offset:3072
	v_lshl_add_u64 v[188:189], s[0:1], 0, v[172:173]
	s_add_i32 m0, s55, 0xc000
	ds_read_b128 v[184:187], v193
	ds_read_b128 v[194:197], v193 offset:1024
	ds_read_b128 v[198:201], v193 offset:2048
	ds_read_b128 v[202:205], v193 offset:3072
	ds_read_b128 v[206:209], v193 offset:4096
	ds_read_b128 v[210:213], v193 offset:5120
	ds_read_b128 v[214:217], v193 offset:6144
	ds_read_b128 v[218:221], v193 offset:7168
	global_load_lds_dwordx4 v[188:189], off
	v_lshl_add_u64 v[188:189], s[0:1], 0, v[174:175]
	s_add_i32 m0, s55, 0xe000
	s_nop 0
	global_load_lds_dwordx4 v[188:189], off
	s_waitcnt vmcnt(8)
	s_waitcnt lgkmcnt(0)
	s_setprio 1
	s_barrier
; #define PG8_STAGE(bufoff, gbase, voff) do { _Pragma("unroll") for (int _i = 0; _i < 2; ++_i) \
;         __builtin_amdgcn_global_load_lds((const unsigned*)((const char*)(gbase) + (voff)[_i]), (PG8_LAS unsigned*)(lds + (bufoff) + ldsw + _i * 8192), 16, 0, 0); } while (0)
; #define PG8_LDA(dst, b, h) do { _Pragma("unroll") for (int m = 0; m < 4; ++m) _Pragma("unroll") for (int k = 0; k < 2; ++k) dst[m][k] = *(const PG8_LAS bf16x8*)(lds + PG8_SA(b, h) + aoff + m * 2048 + k * 1024); } while (0)
; #define PG8_MMA(ai, bj, At, Bt) do { __builtin_amdgcn_s_setprio(1); _Pragma("unroll") for (int m = 0; m < 4; ++m) _Pragma("unroll") for (int n = 0; n < 2; ++n) _Pragma("unroll") for (int k = 0; k < 2; ++k) \
;         acc[ai][bj][m][n] = __builtin_amdgcn_mfma_f32_16x16x32_bf16(Bt[n][k], At[m][k], acc[ai][bj][m][n], 0, 0, 0); __builtin_amdgcn_s_setprio(0); } while (0)
; #define PG8_WAIT_V(n) asm volatile("s_waitcnt vmcnt(" #n ")" ::: "memory")
; #define PG8_WAIT_L(n) asm volatile("s_waitcnt lgkmcnt(" #n ")" ::: "memory")
; #define PG8_BAR __builtin_amdgcn_s_barrier()
; #define PG8_SCHED __builtin_amdgcn_sched_barrier(0)
; template <class Epi, class Sched, bool ALIGN_EPI = false, bool SP2 = false>
; __device__ __forceinline__ void gemm_phase(PG8_LAS unsigned char* lds, const Gemm g, const Sched& S, const Epi& E) {
;     ...
;             PG8_WAIT_V(8); PG8_WAIT_L(0); PG8_BAR; PG8_MMA(0, 0, At, B0); PG8_MMA(0, 1, At, B1); PG8_BAR; PG8_SCHED;
;             PG8_LDA(At, 0, 1); PG8_STAGE(PG8_SB(0, 0), b2, voffB); PG8_STAGE(PG8_SB(0, 1), b2 + hstep, voffB); PG8_STAGE(PG8_SA(0, 0), a2, voffA);
;             PG8_WAIT_V(8); PG8_WAIT_L(0); PG8_BAR; PG8_MMA(1, 0, At, B0); PG8_MMA(1, 1, At, B1); PG8_BAR; PG8_SCHED;
	v_mfma_f32_16x16x32_bf16 v[28:31], v[128:131], v[184:187], v[28:31]
	v_mfma_f32_16x16x32_bf16 v[24:27], v[136:139], v[184:187], v[24:27]
	v_mfma_f32_16x16x32_bf16 v[12:15], v[128:131], v[198:201], v[12:15]
	v_mfma_f32_16x16x32_bf16 v[8:11], v[136:139], v[198:201], v[8:11]
	v_mfma_f32_16x16x32_bf16 v[124:127], v[128:131], v[206:209], v[124:127]
	v_mfma_f32_16x16x32_bf16 v[120:123], v[136:139], v[206:209], v[120:123]
	v_mfma_f32_16x16x32_bf16 v[108:111], v[128:131], v[214:217], v[108:111]
	v_mfma_f32_16x16x32_bf16 v[104:107], v[136:139], v[214:217], v[104:107]
	v_mfma_f32_16x16x32_bf16 v[28:31], v[132:135], v[194:197], v[28:31]
	v_mfma_f32_16x16x32_bf16 v[24:27], v[140:143], v[194:197], v[24:27]
	v_mfma_f32_16x16x32_bf16 v[12:15], v[132:135], v[202:205], v[12:15]
	v_mfma_f32_16x16x32_bf16 v[8:11], v[140:143], v[202:205], v[8:11]
	v_mfma_f32_16x16x32_bf16 v[124:127], v[132:135], v[210:213], v[124:127]
	v_mfma_f32_16x16x32_bf16 v[120:123], v[140:143], v[210:213], v[120:123]
	v_mfma_f32_16x16x32_bf16 v[108:111], v[132:135], v[218:221], v[108:111]
	v_mfma_f32_16x16x32_bf16 v[104:107], v[140:143], v[218:221], v[104:107]
	s_setprio 0
	s_setprio 1
	v_mfma_f32_16x16x32_bf16 v[20:23], v[144:147], v[184:187], v[20:23]
	v_mfma_f32_16x16x32_bf16 v[16:19], v[176:179], v[184:187], v[16:19]
	v_mfma_f32_16x16x32_bf16 v[4:7], v[144:147], v[198:201], v[4:7]
	v_mfma_f32_16x16x32_bf16 v[0:3], v[176:179], v[198:201], v[0:3]
	v_mfma_f32_16x16x32_bf16 v[116:119], v[144:147], v[206:209], v[116:119]
	v_mfma_f32_16x16x32_bf16 v[112:115], v[176:179], v[206:209], v[112:115]
	v_mfma_f32_16x16x32_bf16 v[100:103], v[144:147], v[214:217], v[100:103]
	v_mfma_f32_16x16x32_bf16 v[96:99], v[176:179], v[214:217], v[96:99]
	v_mfma_f32_16x16x32_bf16 v[20:23], v[148:151], v[194:197], v[20:23]
	v_mfma_f32_16x16x32_bf16 v[16:19], v[180:183], v[194:197], v[16:19]
	v_mfma_f32_16x16x32_bf16 v[4:7], v[148:151], v[202:205], v[4:7]
	v_mfma_f32_16x16x32_bf16 v[0:3], v[180:183], v[202:205], v[0:3]
	v_mfma_f32_16x16x32_bf16 v[116:119], v[148:151], v[210:213], v[116:119]
	v_mfma_f32_16x16x32_bf16 v[112:115], v[180:183], v[210:213], v[112:115]
	v_mfma_f32_16x16x32_bf16 v[100:103], v[148:151], v[218:221], v[100:103]
	v_mfma_f32_16x16x32_bf16 v[96:99], v[180:183], v[218:221], v[96:99]
	s_setprio 0
	s_barrier
	s_add_i32 s59, s59, s66
	v_lshl_add_u64 v[188:189], s[4:5], 0, v[166:167]
	s_mov_b32 m0, s59
	ds_read_b128 v[184:187], v193 offset:16384
	ds_read_b128 v[194:197], v193 offset:17408
	ds_read_b128 v[198:201], v193 offset:18432
	ds_read_b128 v[202:205], v193 offset:19456
	ds_read_b128 v[206:209], v193 offset:20480
	ds_read_b128 v[210:213], v193 offset:21504
	ds_read_b128 v[214:217], v193 offset:22528
	ds_read_b128 v[218:221], v193 offset:23552
	global_load_lds_dwordx4 v[188:189], off
	s_add_i32 m0, s59, 0x2000
	s_add_u32 s60, s4, 0x80000
	v_lshl_add_u64 v[222:223], s[4:5], 0, v[170:171]
	s_addc_u32 s61, s5, 0
	s_add_i32 s59, s81, s66
	global_load_lds_dwordx4 v[222:223], off
	v_lshl_add_u64 v[224:225], s[60:61], 0, v[166:167]
	s_mov_b32 m0, s59
	v_lshl_add_u64 v[226:227], s[8:9], 0, v[168:169]
	global_load_lds_dwordx4 v[224:225], off
	v_lshl_add_u64 v[224:225], s[60:61], 0, v[170:171]
	s_add_i32 m0, s59, 0x2000
	s_nop 0
	global_load_lds_dwordx4 v[224:225], off
	v_lshl_add_u64 v[224:225], s[8:9], 0, v[164:165]
	s_mov_b32 m0, s55
	s_nop 0
	global_load_lds_dwordx4 v[224:225], off
	s_mov_b32 m0, s67
	s_nop 0
	global_load_lds_dwordx4 v[226:227], off
	s_waitcnt vmcnt(8)
	s_waitcnt lgkmcnt(0)
	s_setprio 1
	s_barrier
	v_mfma_f32_16x16x32_bf16 v[92:95], v[128:131], v[184:187], v[92:95]
	v_mfma_f32_16x16x32_bf16 v[88:91], v[136:139], v[184:187], v[88:91]
	v_mfma_f32_16x16x32_bf16 v[76:79], v[128:131], v[198:201], v[76:79]
	v_mfma_f32_16x16x32_bf16 v[72:75], v[136:139], v[198:201], v[72:75]
	v_mfma_f32_16x16x32_bf16 v[60:63], v[128:131], v[206:209], v[60:63]
	v_mfma_f32_16x16x32_bf16 v[56:59], v[136:139], v[206:209], v[56:59]
	v_mfma_f32_16x16x32_bf16 v[44:47], v[128:131], v[214:217], v[44:47]
	v_mfma_f32_16x16x32_bf16 v[40:43], v[136:139], v[214:217], v[40:43]
	v_mfma_f32_16x16x32_bf16 v[92:95], v[132:135], v[194:197], v[92:95]
	v_mfma_f32_16x16x32_bf16 v[88:91], v[140:143], v[194:197], v[88:91]
	v_mfma_f32_16x16x32_bf16 v[76:79], v[132:135], v[202:205], v[76:79]
	v_mfma_f32_16x16x32_bf16 v[72:75], v[140:143], v[202:205], v[72:75]
	v_mfma_f32_16x16x32_bf16 v[60:63], v[132:135], v[210:213], v[60:63]
	v_mfma_f32_16x16x32_bf16 v[56:59], v[140:143], v[210:213], v[56:59]
	v_mfma_f32_16x16x32_bf16 v[44:47], v[132:135], v[218:221], v[44:47]
	v_mfma_f32_16x16x32_bf16 v[40:43], v[140:143], v[218:221], v[40:43]
	s_setprio 0
	s_setprio 1
	v_mfma_f32_16x16x32_bf16 v[84:87], v[144:147], v[184:187], v[84:87]
	v_mfma_f32_16x16x32_bf16 v[80:83], v[176:179], v[184:187], v[80:83]
	v_mfma_f32_16x16x32_bf16 v[68:71], v[144:147], v[198:201], v[68:71]
	v_mfma_f32_16x16x32_bf16 v[64:67], v[176:179], v[198:201], v[64:67]
	v_mfma_f32_16x16x32_bf16 v[52:55], v[144:147], v[206:209], v[52:55]
	v_mfma_f32_16x16x32_bf16 v[48:51], v[176:179], v[206:209], v[48:51]
	v_mfma_f32_16x16x32_bf16 v[36:39], v[144:147], v[214:217], v[36:39]
	v_mfma_f32_16x16x32_bf16 v[32:35], v[176:179], v[214:217], v[32:35]
	v_mfma_f32_16x16x32_bf16 v[84:87], v[148:151], v[194:197], v[84:87]
	v_mfma_f32_16x16x32_bf16 v[80:83], v[180:183], v[194:197], v[80:83]
	v_mfma_f32_16x16x32_bf16 v[68:71], v[148:151], v[202:205], v[68:71]
	v_mfma_f32_16x16x32_bf16 v[64:67], v[180:183], v[202:205], v[64:67]
	v_mfma_f32_16x16x32_bf16 v[52:55], v[148:151], v[210:213], v[52:55]
	v_mfma_f32_16x16x32_bf16 v[48:51], v[180:183], v[210:213], v[48:51]
	v_mfma_f32_16x16x32_bf16 v[36:39], v[148:151], v[218:221], v[36:39]
	v_mfma_f32_16x16x32_bf16 v[32:35], v[180:183], v[218:221], v[32:35]
	s_setprio 0
	s_barrier
; #define PG8_STAGE(bufoff, gbase, voff) do { _Pragma("unroll") for (int _i = 0; _i < 2; ++_i) \
;         __builtin_amdgcn_global_load_lds((const unsigned*)((const char*)(gbase) + (voff)[_i]), (PG8_LAS unsigned*)(lds + (bufoff) + ldsw + _i * 8192), 16, 0, 0); } while (0)
; #define PG8_LDA(dst, b, h) do { _Pragma("unroll") for (int m = 0; m < 4; ++m) _Pragma("unroll") for (int k = 0; k < 2; ++k) dst[m][k] = *(const PG8_LAS bf16x8*)(lds + PG8_SA(b, h) + aoff + m * 2048 + k * 1024); } while (0)
; #define PG8_LDB(dst, b, h) do { _Pragma("unroll") for (int n = 0; n < 2; ++n) _Pragma("unroll") for (int k = 0; k < 2; ++k) dst[n][k] = *(const PG8_LAS bf16x8*)(lds + PG8_SB(b, h) + boff + n * 2048 + k * 1024); } while (0)
; #define PG8_MMA(ai, bj, At, Bt) do { __builtin_amdgcn_s_setprio(1); _Pragma("unroll") for (int m = 0; m < 4; ++m) _Pragma("unroll") for (int n = 0; n < 2; ++n) _Pragma("unroll") for (int k = 0; k < 2; ++k) \
;         acc[ai][bj][m][n] = __builtin_amdgcn_mfma_f32_16x16x32_bf16(Bt[n][k], At[m][k], acc[ai][bj][m][n], 0, 0, 0); __builtin_amdgcn_s_setprio(0); } while (0)
; #define PG8_WAIT_V(n) asm volatile("s_waitcnt vmcnt(" #n ")" ::: "memory")
; #define PG8_WAIT_L(n) asm volatile("s_waitcnt lgkmcnt(" #n ")" ::: "memory")
; #define PG8_BAR __builtin_amdgcn_s_barrier()
; #define PG8_SCHED __builtin_amdgcn_sched_barrier(0)
; template <class Epi, class Sched, bool ALIGN_EPI = false, bool SP2 = false>
; __device__ __forceinline__ void gemm_phase(PG8_LAS unsigned char* lds, const Gemm g, const Sched& S, const Epi& E) {
;     ...
;             PG8_LDB(B0, 1, 0); PG8_LDB(B1, 1, 1); PG8_SCHED; PG8_LDA(At, 1, 0); PG8_STAGE(PG8_SA(0, 1), a2 + hstep, voffA);
;             PG8_WAIT_V(8); PG8_WAIT_L(0); PG8_BAR; PG8_MMA(0, 0, At, B0); PG8_MMA(0, 1, At, B1); PG8_BAR; PG8_SCHED;
	s_add_i32 s59, 0, 0x18000
	s_add_i32 s60, 0, 0x1c000
	v_add_u32_e32 v140, s59, v192
	v_add_u32_e32 v152, s60, v192
	ds_read_b128 v[128:131], v140
	ds_read_b128 v[132:135], v140 offset:1024
	ds_read_b128 v[136:139], v140 offset:2048
	ds_read_b128 v[140:143], v140 offset:3072
	ds_read_b128 v[144:147], v152
	ds_read_b128 v[148:151], v152 offset:1024
	ds_read_b128 v[176:179], v152 offset:2048
	ds_read_b128 v[180:183], v152 offset:3072
	s_add_u32 s8, s8, 0x80000
	s_addc_u32 s9, s9, 0
	s_mov_b32 m0, s68
	v_lshl_add_u64 v[228:229], s[8:9], 0, v[164:165]
	ds_read_b128 v[184:187], v193 offset:32768
	ds_read_b128 v[194:197], v193 offset:33792
	ds_read_b128 v[198:201], v193 offset:34816
	ds_read_b128 v[202:205], v193 offset:35840
	ds_read_b128 v[206:209], v193 offset:36864
	ds_read_b128 v[210:213], v193 offset:37888
	ds_read_b128 v[214:217], v193 offset:38912
	ds_read_b128 v[218:221], v193 offset:39936
	global_load_lds_dwordx4 v[228:229], off
	v_lshl_add_u64 v[228:229], s[8:9], 0, v[168:169]
	s_mov_b32 m0, s69
	s_nop 0
	global_load_lds_dwordx4 v[228:229], off
	s_waitcnt vmcnt(8)
	s_waitcnt lgkmcnt(0)
	s_setprio 1
	s_barrier
	v_mfma_f32_16x16x32_bf16 v[28:31], v[128:131], v[184:187], v[28:31]
	v_mfma_f32_16x16x32_bf16 v[24:27], v[136:139], v[184:187], v[24:27]
	v_mfma_f32_16x16x32_bf16 v[12:15], v[128:131], v[198:201], v[12:15]
	v_mfma_f32_16x16x32_bf16 v[8:11], v[136:139], v[198:201], v[8:11]
	v_mfma_f32_16x16x32_bf16 v[124:127], v[128:131], v[206:209], v[124:127]
	v_mfma_f32_16x16x32_bf16 v[120:123], v[136:139], v[206:209], v[120:123]
	v_mfma_f32_16x16x32_bf16 v[108:111], v[128:131], v[214:217], v[108:111]
	v_mfma_f32_16x16x32_bf16 v[104:107], v[136:139], v[214:217], v[104:107]
	v_mfma_f32_16x16x32_bf16 v[28:31], v[132:135], v[194:197], v[28:31]
	v_mfma_f32_16x16x32_bf16 v[24:27], v[140:143], v[194:197], v[24:27]
	v_mfma_f32_16x16x32_bf16 v[12:15], v[132:135], v[202:205], v[12:15]
	v_mfma_f32_16x16x32_bf16 v[8:11], v[140:143], v[202:205], v[8:11]
	v_mfma_f32_16x16x32_bf16 v[124:127], v[132:135], v[210:213], v[124:127]
	v_mfma_f32_16x16x32_bf16 v[120:123], v[140:143], v[210:213], v[120:123]
	v_mfma_f32_16x16x32_bf16 v[108:111], v[132:135], v[218:221], v[108:111]
	v_mfma_f32_16x16x32_bf16 v[104:107], v[140:143], v[218:221], v[104:107]
	s_setprio 0
	s_setprio 1
	v_mfma_f32_16x16x32_bf16 v[20:23], v[144:147], v[184:187], v[20:23]
	v_mfma_f32_16x16x32_bf16 v[16:19], v[176:179], v[184:187], v[16:19]
	v_mfma_f32_16x16x32_bf16 v[4:7], v[144:147], v[198:201], v[4:7]
	v_mfma_f32_16x16x32_bf16 v[0:3], v[176:179], v[198:201], v[0:3]
	v_mfma_f32_16x16x32_bf16 v[116:119], v[144:147], v[206:209], v[116:119]
	v_mfma_f32_16x16x32_bf16 v[112:115], v[176:179], v[206:209], v[112:115]
	v_mfma_f32_16x16x32_bf16 v[100:103], v[144:147], v[214:217], v[100:103]
	v_mfma_f32_16x16x32_bf16 v[96:99], v[176:179], v[214:217], v[96:99]
	v_mfma_f32_16x16x32_bf16 v[20:23], v[148:151], v[194:197], v[20:23]
	v_mfma_f32_16x16x32_bf16 v[16:19], v[180:183], v[194:197], v[16:19]
	v_mfma_f32_16x16x32_bf16 v[4:7], v[148:151], v[202:205], v[4:7]
	v_mfma_f32_16x16x32_bf16 v[0:3], v[180:183], v[202:205], v[0:3]
	v_mfma_f32_16x16x32_bf16 v[116:119], v[148:151], v[210:213], v[116:119]
	v_mfma_f32_16x16x32_bf16 v[112:115], v[180:183], v[210:213], v[112:115]
	v_mfma_f32_16x16x32_bf16 v[100:103], v[148:151], v[218:221], v[100:103]
	v_mfma_f32_16x16x32_bf16 v[96:99], v[180:183], v[218:221], v[96:99]
	s_setprio 0
	s_barrier
; #define PG8_STAGE(bufoff, gbase, voff) do { _Pragma("unroll") for (int _i = 0; _i < 2; ++_i) \
;         __builtin_amdgcn_global_load_lds((const unsigned*)((const char*)(gbase) + (voff)[_i]), (PG8_LAS unsigned*)(lds + (bufoff) + ldsw + _i * 8192), 16, 0, 0); } while (0)
; #define PG8_LDA(dst, b, h) do { _Pragma("unroll") for (int m = 0; m < 4; ++m) _Pragma("unroll") for (int k = 0; k < 2; ++k) dst[m][k] = *(const PG8_LAS bf16x8*)(lds + PG8_SA(b, h) + aoff + m * 2048 + k * 1024); } while (0)
; #define PG8_MMA(ai, bj, At, Bt) do { __builtin_amdgcn_s_setprio(1); _Pragma("unroll") for (int m = 0; m < 4; ++m) _Pragma("unroll") for (int n = 0; n < 2; ++n) _Pragma("unroll") for (int k = 0; k < 2; ++k) \
;         acc[ai][bj][m][n] = __builtin_amdgcn_mfma_f32_16x16x32_bf16(Bt[n][k], At[m][k], acc[ai][bj][m][n], 0, 0, 0); __builtin_amdgcn_s_setprio(0); } while (0)
; #define PG8_WAIT_V(n) asm volatile("s_waitcnt vmcnt(" #n ")" ::: "memory")
; #define PG8_WAIT_L(n) asm volatile("s_waitcnt lgkmcnt(" #n ")" ::: "memory")
; #define PG8_BAR __builtin_amdgcn_s_barrier()
; #define PG8_SCHED __builtin_amdgcn_sched_barrier(0)
; template <class Epi, class Sched, bool ALIGN_EPI = false, bool SP2 = false>
; __device__ __forceinline__ void gemm_phase(PG8_LAS unsigned char* lds, const Gemm g, const Sched& S, const Epi& E) {
;     ...
;             PG8_LDA(At, 1, 1); PG8_STAGE(PG8_SB(1, 0), b3, voffB); PG8_STAGE(PG8_SB(1, 1), b3 + hstep, voffB); PG8_STAGE(PG8_SA(1, 0), a3, voffA);
;             PG8_WAIT_V(8); PG8_WAIT_L(0); PG8_BAR; PG8_MMA(1, 0, At, B0); PG8_MMA(1, 1, At, B1); PG8_BAR; PG8_SCHED;
;     ...
;         if constexpr (ALIGN_EPI) { if (wr == 0) PG8_BAR; }
	s_add_i32 s8, s59, s66
	v_lshl_add_u64 v[188:189], v[188:189], 0, vcc
	s_mov_b32 m0, s8
	ds_read_b128 v[184:187], v193 offset:49152
	ds_read_b128 v[194:197], v193 offset:50176
	ds_read_b128 v[198:201], v193 offset:51200
	ds_read_b128 v[202:205], v193 offset:52224
	ds_read_b128 v[206:209], v193 offset:53248
	ds_read_b128 v[210:213], v193 offset:54272
	ds_read_b128 v[214:217], v193 offset:55296
	ds_read_b128 v[218:221], v193 offset:56320
	global_load_lds_dwordx4 v[188:189], off
	s_add_i32 m0, s8, 0x2000
	s_add_u32 s4, s4, 0x80080
	v_lshl_add_u64 v[188:189], v[222:223], 0, vcc
	s_addc_u32 s5, s5, 0
	s_add_i32 s8, s60, s66
	global_load_lds_dwordx4 v[188:189], off
	v_lshl_add_u64 v[188:189], s[4:5], 0, v[166:167]
	s_mov_b32 m0, s8
	s_nop 0
	global_load_lds_dwordx4 v[188:189], off
	v_lshl_add_u64 v[188:189], s[4:5], 0, v[170:171]
	s_add_i32 m0, s8, 0x2000
	s_nop 0
	global_load_lds_dwordx4 v[188:189], off
	v_lshl_add_u64 v[188:189], v[224:225], 0, vcc
	s_mov_b32 m0, s72
	s_nop 0
	global_load_lds_dwordx4 v[188:189], off
	v_lshl_add_u64 v[188:189], v[226:227], 0, vcc
	s_mov_b32 m0, s73
	s_nop 0
	global_load_lds_dwordx4 v[188:189], off
	s_waitcnt vmcnt(8)
	s_waitcnt lgkmcnt(0)
	s_setprio 1
	s_barrier
	v_mfma_f32_16x16x32_bf16 v[92:95], v[128:131], v[184:187], v[92:95]
	v_mfma_f32_16x16x32_bf16 v[88:91], v[136:139], v[184:187], v[88:91]
	v_mfma_f32_16x16x32_bf16 v[76:79], v[128:131], v[198:201], v[76:79]
	v_mfma_f32_16x16x32_bf16 v[72:75], v[136:139], v[198:201], v[72:75]
	v_mfma_f32_16x16x32_bf16 v[60:63], v[128:131], v[206:209], v[60:63]
	v_mfma_f32_16x16x32_bf16 v[56:59], v[136:139], v[206:209], v[56:59]
	v_mfma_f32_16x16x32_bf16 v[44:47], v[128:131], v[214:217], v[44:47]
	v_mfma_f32_16x16x32_bf16 v[40:43], v[136:139], v[214:217], v[40:43]
	v_mfma_f32_16x16x32_bf16 v[92:95], v[132:135], v[194:197], v[92:95]
	v_mfma_f32_16x16x32_bf16 v[88:91], v[140:143], v[194:197], v[88:91]
	v_mfma_f32_16x16x32_bf16 v[76:79], v[132:135], v[202:205], v[76:79]
	v_mfma_f32_16x16x32_bf16 v[72:75], v[140:143], v[202:205], v[72:75]
	v_mfma_f32_16x16x32_bf16 v[60:63], v[132:135], v[210:213], v[60:63]
	v_mfma_f32_16x16x32_bf16 v[56:59], v[140:143], v[210:213], v[56:59]
	v_mfma_f32_16x16x32_bf16 v[44:47], v[132:135], v[218:221], v[44:47]
	v_mfma_f32_16x16x32_bf16 v[40:43], v[140:143], v[218:221], v[40:43]
	s_setprio 0
	s_setprio 1
	v_mfma_f32_16x16x32_bf16 v[84:87], v[144:147], v[184:187], v[84:87]
	v_mfma_f32_16x16x32_bf16 v[80:83], v[176:179], v[184:187], v[80:83]
	v_mfma_f32_16x16x32_bf16 v[68:71], v[144:147], v[198:201], v[68:71]
	v_mfma_f32_16x16x32_bf16 v[64:67], v[176:179], v[198:201], v[64:67]
	v_mfma_f32_16x16x32_bf16 v[52:55], v[144:147], v[206:209], v[52:55]
	v_mfma_f32_16x16x32_bf16 v[48:51], v[176:179], v[206:209], v[48:51]
	v_mfma_f32_16x16x32_bf16 v[36:39], v[144:147], v[214:217], v[36:39]
	v_mfma_f32_16x16x32_bf16 v[32:35], v[176:179], v[214:217], v[32:35]
	v_mfma_f32_16x16x32_bf16 v[84:87], v[148:151], v[194:197], v[84:87]
	v_mfma_f32_16x16x32_bf16 v[80:83], v[180:183], v[194:197], v[80:83]
	v_mfma_f32_16x16x32_bf16 v[68:71], v[148:151], v[202:205], v[68:71]
	v_mfma_f32_16x16x32_bf16 v[64:67], v[180:183], v[202:205], v[64:67]
	v_mfma_f32_16x16x32_bf16 v[52:55], v[148:151], v[210:213], v[52:55]
	v_mfma_f32_16x16x32_bf16 v[48:51], v[180:183], v[210:213], v[48:51]
	v_mfma_f32_16x16x32_bf16 v[36:39], v[148:151], v[218:221], v[36:39]
	v_mfma_f32_16x16x32_bf16 v[32:35], v[180:183], v[218:221], v[32:35]
	s_setprio 0
	s_barrier
	s_add_i32 s58, s58, 2
	s_add_u32 s0, s0, 0x100
	s_addc_u32 s1, s1, 0
	s_add_u32 s56, s56, 0x100
	s_addc_u32 s57, s57, 0
	s_cmp_gt_u32 s58, 29
	s_cbranch_scc0 .LBB0_447
	s_and_b64 vcc, exec, s[40:41]
	s_cbranch_vccz .LBB0_450
	s_barrier

; #define PG8_STAGE(bufoff, gbase, voff) do { _Pragma("unroll") for (int _i = 0; _i < 2; ++_i) \
;         __builtin_amdgcn_global_load_lds((const unsigned*)((const char*)(gbase) + (voff)[_i]), (PG8_LAS unsigned*)(lds + (bufoff) + ldsw + _i * 8192), 16, 0, 0); } while (0)
; #define PG8_WAIT_V(n) asm volatile("s_waitcnt vmcnt(" #n ")" ::: "memory")
; #define PG8_BAR __builtin_amdgcn_s_barrier()
; template <class Epi, class Sched, bool ALIGN_EPI = false, bool SP2 = false>
; __device__ __forceinline__ void gemm_phase(PG8_LAS unsigned char* lds, const Gemm g, const Sched& S, const Epi& E) {
;     int tid_l = threadIdx.x; asm volatile("" : "+v"(tid_l)); const int tid = tid_l, wid = __builtin_amdgcn_readfirstlane(tid >> 6), lane = tid & 63, wr = wid >> 2, wc = wid & 3, fr = lane & 15, fq = lane >> 4;
;     const int K = g.K, nt = K / BK;
;     unsigned voffA[2], voffB[2];
; #pragma unroll
;     for (int i = 0; i < 2; ++i) { int R, C; stage_rc(tid * 16 + i * 8192, R, C); const int Rb = Epi::PERM ? ((R & ~31) + perm32(R & 31)) : R;
;         voffA[i] = (unsigned)(R * K + C) * 2u; voffB[i] = (unsigned)(Rb * K + C) * 2u; }
;     const size_t kstep = (size_t)(BK * 2);
;     const size_t hstep = (size_t)HALF * K * 2;
;     const size_t tstep = 2 * hstep;
;     const unsigned ldsw = (unsigned)wid * 1024u;
;     const int aoff = lds_byte(wr * 64 + fr, fq * 8), boff = lds_byte(wc * 32 + fr, fq * 8);
;     ...
;     f32x4 acc[2][2][4][2];
; #pragma unroll
;     for (int a = 0; a < 2; ++a)
; #pragma unroll
;         for (int b = 0; b < 2; ++b)
; #pragma unroll
;             for (int m = 0; m < 4; ++m)
; #pragma unroll
;                 for (int n = 0; n < 2; ++n) acc[a][b][m][n] = (f32x4){0.f, 0.f, 0.f, 0.f};
;     bf16x8 At[4][2], B0[2][2], B1[2][2];
;     const char* cA = (const char*)g.A + (size_t)cur.pm * tstep; const char* cB = (const char*)g.Bt + (size_t)cur.pn * tstep;
;     S.a_ready(cur);
;     if constexpr (SP2) {
;         PG8_STAGE(PG8_SB(0, 0), cB, voffB); PG8_STAGE(PG8_SB(0, 1), cB + hstep, voffB); PG8_STAGE(PG8_SA(0, 0), cA, voffA); PG8_STAGE(PG8_SA(0, 1), cA + hstep, voffA);
;         if (wr == 1) PG8_BAR;
;         PG8_WAIT_V(2); PG8_BAR;
;         PG8_STAGE(PG8_SB(1, 0), cB + kstep, voffB); PG8_STAGE(PG8_SA(1, 0), cA + kstep, voffA); PG8_STAGE(PG8_SB(1, 1), cB + hstep + kstep, voffB);
;         PG8_WAIT_V(6); PG8_BAR;
.LBB0_873:
	v_lshl_add_u64 v[6:7], s[24:25], 0, v[152:153]
	v_mov_b32_e32 v33, v153
	v_lshl_add_u64 v[8:9], s[24:25], 0, v[32:33]
	v_mov_b32_e32 v41, v153
	s_and_b32 s34, s5, 3
	s_add_i32 m0, s35, 0x18000
	v_lshl_add_u64 v[6:7], v[6:7], 0, s[74:75]
	v_lshl_add_u64 v[10:11], s[14:15], 0, v[40:41]
	v_mov_b32_e32 v35, v153
	s_lshl_b32 s36, s4, 6
	s_lshl_b32 s4, s4, 13
	s_lshl_b32 s5, s34, 12
	s_waitcnt vmcnt(2)
	s_barrier
	global_load_lds_dwordx4 v[6:7], off
	v_lshl_add_u64 v[6:7], v[8:9], 0, s[74:75]
	s_add_i32 m0, s35, 0x1a000
	s_add_i32 s40, s35, 0x8000
	s_add_i32 s41, s35, 0xa000
	v_lshl_add_u64 v[12:13], s[14:15], 0, v[34:35]
	global_load_lds_dwordx4 v[6:7], off
	v_lshl_add_u64 v[6:7], v[10:11], 0, s[74:75]
	s_mov_b32 m0, s40
	s_add_u32 s0, s24, 0x80080
	global_load_lds_dwordx4 v[6:7], off
	v_lshl_add_u64 v[6:7], v[12:13], 0, s[74:75]
	s_mov_b32 m0, s41
	s_addc_u32 s1, s25, 0
	global_load_lds_dwordx4 v[6:7], off
	s_add_i32 m0, s35, 0x1c000
	v_lshl_add_u64 v[6:7], s[0:1], 0, v[152:153]
	global_load_lds_dwordx4 v[6:7], off
	v_lshl_add_u64 v[6:7], s[0:1], 0, v[32:33]
	s_add_i32 m0, s35, 0x1e000
	v_and_b32_e32 v144, 15, v220
	global_load_lds_dwordx4 v[6:7], off
	v_and_b32_e32 v6, 48, v220
	v_lshlrev_b32_e32 v7, 2, v220
	v_lshl_or_b32 v6, v144, 6, v6
	v_and_b32_e32 v7, 32, v7
	v_bitop3_b32 v8, v6, s4, v7 bitop3:0xde
	v_bitop3_b32 v50, v6, s5, v7 bitop3:0xde
	v_lshlrev_b32_e32 v6, 15, v4
	v_and_b32_e32 v6, 0xffff0000, v6
	v_lshl_add_u32 v3, v3, 12, v6
	v_and_b32_e32 v4, 1, v4
	v_lshl_or_b32 v3, v4, 6, v3
	v_lshl_add_u32 v42, v5, 1, v3
	v_lshlrev_b32_e32 v3, 15, v0
	v_and_b32_e32 v3, 0xffff0000, v3
	v_lshl_add_u32 v1, v1, 12, v3
	v_and_b32_e32 v0, 1, v0
	v_lshl_or_b32 v0, v0, 6, v1
	s_waitcnt vmcnt(6)
	v_lshl_add_u32 v44, v2, 1, v0
	v_mov_b32_e32 v2, v153
	v_mov_b32_e32 v3, v153
	v_readlane_b32 s0, v253, 27
	v_mov_b32_e32 v0, v153
	v_mov_b32_e32 v1, v153
	v_add_u32_e32 v51, 0, v8
	v_mov_b64_e32 v[6:7], v[2:3]
	v_mov_b64_e32 v[18:19], v[2:3]
	v_mov_b64_e32 v[22:23], v[2:3]
	v_mov_b64_e32 v[38:39], v[2:3]
	v_mov_b64_e32 v[54:55], v[2:3]
	v_mov_b64_e32 v[66:67], v[2:3]
	v_mov_b64_e32 v[70:71], v[2:3]
	v_mov_b64_e32 v[10:11], v[2:3]
	v_mov_b64_e32 v[14:15], v[2:3]
	v_mov_b64_e32 v[26:27], v[2:3]
	v_mov_b64_e32 v[30:31], v[2:3]
	v_mov_b64_e32 v[58:59], v[2:3]
	v_mov_b64_e32 v[62:63], v[2:3]
	v_mov_b64_e32 v[74:75], v[2:3]
	v_mov_b64_e32 v[78:79], v[2:3]
	v_mov_b64_e32 v[82:83], v[2:3]
	v_mov_b64_e32 v[86:87], v[2:3]
	v_mov_b64_e32 v[98:99], v[2:3]
	v_mov_b64_e32 v[102:103], v[2:3]
	v_mov_b64_e32 v[114:115], v[2:3]
	v_mov_b64_e32 v[118:119], v[2:3]
	v_mov_b64_e32 v[130:131], v[2:3]
	v_mov_b64_e32 v[134:135], v[2:3]
	v_mov_b64_e32 v[90:91], v[2:3]
	v_mov_b64_e32 v[94:95], v[2:3]
	v_mov_b64_e32 v[106:107], v[2:3]
	v_mov_b64_e32 v[110:111], v[2:3]
	v_mov_b64_e32 v[122:123], v[2:3]
	v_mov_b64_e32 v[126:127], v[2:3]
	v_mov_b64_e32 v[138:139], v[2:3]
	v_mov_b64_e32 v[142:143], v[2:3]
	s_mov_b32 s12, s0
	v_readlane_b32 s0, v253, 39
	v_mov_b32_e32 v43, v153
	v_mov_b32_e32 v45, v153
	s_mov_b32 s43, 0
	v_mov_b64_e32 v[4:5], v[0:1]
	v_mov_b64_e32 v[16:17], v[0:1]
	v_mov_b64_e32 v[20:21], v[0:1]
	v_mov_b64_e32 v[36:37], v[0:1]
	v_mov_b64_e32 v[52:53], v[0:1]
	v_mov_b64_e32 v[64:65], v[0:1]
	v_mov_b64_e32 v[68:69], v[0:1]
	v_mov_b64_e32 v[8:9], v[0:1]
	v_mov_b64_e32 v[12:13], v[0:1]
	v_mov_b64_e32 v[24:25], v[0:1]
	v_mov_b64_e32 v[28:29], v[0:1]
	v_mov_b64_e32 v[56:57], v[0:1]
	v_mov_b64_e32 v[60:61], v[0:1]
	v_mov_b64_e32 v[72:73], v[0:1]
	v_mov_b64_e32 v[76:77], v[0:1]
	v_mov_b64_e32 v[80:81], v[0:1]
	v_mov_b64_e32 v[84:85], v[0:1]
	v_mov_b64_e32 v[96:97], v[0:1]
	v_mov_b64_e32 v[100:101], v[0:1]
	v_mov_b64_e32 v[112:113], v[0:1]
	v_mov_b64_e32 v[116:117], v[0:1]
	v_mov_b64_e32 v[128:129], v[0:1]
	v_mov_b64_e32 v[132:133], v[0:1]
	v_mov_b64_e32 v[88:89], v[0:1]
	v_mov_b64_e32 v[92:93], v[0:1]
	v_mov_b64_e32 v[104:105], v[0:1]
	v_mov_b64_e32 v[108:109], v[0:1]
	v_mov_b64_e32 v[120:121], v[0:1]
	v_mov_b64_e32 v[124:125], v[0:1]
	v_mov_b64_e32 v[136:137], v[0:1]
	v_mov_b64_e32 v[140:141], v[0:1]
	s_mov_b32 s42, s0
	s_barrier
	v_readlane_b32 s1, v253, 40
	s_branch .LBB0_876
	s_nop 0
	s_nop 0
.LBB0_874:
	s_mov_b64 s[20:21], s[24:25]
	s_andn2_b64 vcc, exec, s[0:1]
	s_cbranch_vccz .LBB0_886

; #define PG8_STAGE(bufoff, gbase, voff) do { _Pragma("unroll") for (int _i = 0; _i < 2; ++_i) \
;         __builtin_amdgcn_global_load_lds((const unsigned*)((const char*)(gbase) + (voff)[_i]), (PG8_LAS unsigned*)(lds + (bufoff) + ldsw + _i * 8192), 16, 0, 0); } while (0)
; #define PG8_LDA(dst, b, h) do { _Pragma("unroll") for (int m = 0; m < 4; ++m) _Pragma("unroll") for (int k = 0; k < 2; ++k) dst[m][k] = *(const PG8_LAS bf16x8*)(lds + PG8_SA(b, h) + aoff + m * 2048 + k * 1024); } while (0)
; #define PG8_LDB(dst, b, h) do { _Pragma("unroll") for (int n = 0; n < 2; ++n) _Pragma("unroll") for (int k = 0; k < 2; ++k) dst[n][k] = *(const PG8_LAS bf16x8*)(lds + PG8_SB(b, h) + boff + n * 2048 + k * 1024); } while (0)
; #define PG8_WAIT_V(n) asm volatile("s_waitcnt vmcnt(" #n ")" ::: "memory")
; #define PG8_WAIT_L(n) asm volatile("s_waitcnt lgkmcnt(" #n ")" ::: "memory")
; #define PG8_BAR __builtin_amdgcn_s_barrier()
; #define PG8_SCHED __builtin_amdgcn_sched_barrier(0)
; template <class Epi, class Sched, bool ALIGN_EPI = false, bool SP2 = false>
; __device__ __forceinline__ void gemm_phase(PG8_LAS unsigned char* lds, const Gemm g, const Sched& S, const Epi& E) {
;     ...
;         const bool has_next = S.next(ui + 1, nxt);
;         const char* nA = has_next ? (const char*)g.A + (size_t)nxt.pm * tstep : cA; const char* nB = has_next ? (const char*)g.Bt + (size_t)nxt.pn * tstep : cB;
;         for (int t = 0; t < nt; t += 2) {
;             const bool last = (t == nt - 2);
;             const char* a1 = cA + (size_t)(t + 1) * kstep;
;             const char* a2 = last ? nA : cA + (size_t)(t + 2) * kstep; const char* b2 = last ? nB : cB + (size_t)(t + 2) * kstep;
;             const char* a3 = a2 + kstep; const char* b3 = b2 + kstep;
;             if (last && has_next) S.a_ready(nxt);
;             if constexpr (SP2) {
;             PG8_LDB(B0, 0, 0); PG8_LDB(B1, 0, 1); PG8_SCHED; PG8_LDA(At, 0, 0); PG8_STAGE(PG8_SA(1, 1), a1 + hstep, voffA);
;             PG8_WAIT_V(8); PG8_WAIT_L(0); PG8_BAR; PG8_MMA(0, 0, At, B0); PG8_MMA(0, 1, At, B1); PG8_BAR; PG8_SCHED;
;             PG8_LDA(At, 0, 1); PG8_STAGE(PG8_SB(0, 0), b2, voffB); PG8_STAGE(PG8_SB(0, 1), b2 + hstep, voffB); PG8_STAGE(PG8_SA(0, 0), a2, voffA);
;             PG8_WAIT_V(8); PG8_WAIT_L(0); PG8_BAR; PG8_MMA(1, 0, At, B0); PG8_MMA(1, 1, At, B1); PG8_BAR; PG8_SCHED;
.LBB0_882:
	s_add_u32 s45, s24, 0x100
	s_addc_u32 s46, s25, 0
	s_ashr_i32 s19, s18, 31
	s_lshl_b64 s[20:21], s[18:19], 20
	s_add_u32 s22, s30, s20
	s_addc_u32 s23, s31, s21
	s_and_b64 s[20:21], s[4:5], exec
	s_cselect_b32 s19, s23, s15
	s_cselect_b32 s47, s22, s14
	s_ashr_i32 s17, s16, 31
	s_lshl_b64 s[20:21], s[16:17], 20
	s_add_u32 s20, s8, s20
	s_addc_u32 s21, s9, s21
	s_and_b64 s[26:27], s[4:5], exec
	s_cselect_b32 s17, s21, s25
	s_cselect_b32 s48, s20, s24
	s_add_u32 s24, s14, 0x80080
	s_addc_u32 s25, s15, 0
	v_lshl_add_u64 v[46:47], s[24:25], 0, v[42:43]
	v_lshl_add_u64 v[48:49], s[24:25], 0, v[44:45]
	s_mov_b32 s49, -2
	s_mov_b64 s[24:25], 0
.LBB0_883:
	s_add_u32 s26, s14, s24
	s_addc_u32 s27, s15, s25
	s_add_u32 s26, s26, 0x100
	s_addc_u32 s27, s27, 0
	s_add_u32 s50, s45, s24
	s_addc_u32 s51, s46, s25
	s_add_i32 s52, 0, 0x10000
	s_cmpk_eq_i32 s24, 0xf00
	s_cselect_b32 s29, s19, s27
	s_cselect_b32 s28, s47, s26
	v_add_u32_e32 v145, s52, v50
	s_cselect_b32 s27, s17, s51
	s_cselect_b32 s26, s48, s50
	s_add_i32 s53, 0, 0x14000
	ds_read_b128 v[146:149], v145
	ds_read_b128 v[164:167], v145 offset:1024
	ds_read_b128 v[168:171], v145 offset:2048
	ds_read_b128 v[172:175], v145 offset:3072
	v_add_u32_e32 v145, s53, v50
	ds_read_b128 v[176:179], v145
	ds_read_b128 v[180:183], v145 offset:1024
	ds_read_b128 v[184:187], v145 offset:2048
	ds_read_b128 v[188:191], v145 offset:3072
	v_lshl_add_u64 v[150:151], v[46:47], 0, s[24:25]
	s_add_i32 m0, s35, 0xc000
	ds_read_b128 v[192:195], v51
	ds_read_b128 v[196:199], v51 offset:1024
	ds_read_b128 v[200:203], v51 offset:2048
	ds_read_b128 v[204:207], v51 offset:3072
	ds_read_b128 v[208:211], v51 offset:4096
	ds_read_b128 v[212:215], v51 offset:5120
	ds_read_b128 v[216:219], v51 offset:6144
	ds_read_b128 v[222:225], v51 offset:7168
	global_load_lds_dwordx4 v[150:151], off
	v_lshl_add_u64 v[150:151], v[48:49], 0, s[24:25]
	s_add_i32 m0, s35, 0xe000
	s_nop 0
	global_load_lds_dwordx4 v[150:151], off
	s_waitcnt vmcnt(8)
	s_waitcnt lgkmcnt(0)
	s_setprio 1
	s_barrier
	v_mfma_f32_16x16x32_bf16 v[140:143], v[146:149], v[192:195], v[140:143]
	v_mfma_f32_16x16x32_bf16 v[136:139], v[168:171], v[192:195], v[136:139]
	v_mfma_f32_16x16x32_bf16 v[124:127], v[146:149], v[200:203], v[124:127]
	v_mfma_f32_16x16x32_bf16 v[120:123], v[168:171], v[200:203], v[120:123]
	v_mfma_f32_16x16x32_bf16 v[108:111], v[146:149], v[208:211], v[108:111]
	v_mfma_f32_16x16x32_bf16 v[104:107], v[168:171], v[208:211], v[104:107]
	v_mfma_f32_16x16x32_bf16 v[92:95], v[146:149], v[216:219], v[92:95]
	v_mfma_f32_16x16x32_bf16 v[88:91], v[168:171], v[216:219], v[88:91]
	v_mfma_f32_16x16x32_bf16 v[140:143], v[164:167], v[196:199], v[140:143]
	v_mfma_f32_16x16x32_bf16 v[136:139], v[172:175], v[196:199], v[136:139]
	v_mfma_f32_16x16x32_bf16 v[124:127], v[164:167], v[204:207], v[124:127]
	v_mfma_f32_16x16x32_bf16 v[120:123], v[172:175], v[204:207], v[120:123]
	v_mfma_f32_16x16x32_bf16 v[108:111], v[164:167], v[212:215], v[108:111]
	v_mfma_f32_16x16x32_bf16 v[104:107], v[172:175], v[212:215], v[104:107]
	v_mfma_f32_16x16x32_bf16 v[92:95], v[164:167], v[222:225], v[92:95]
	v_mfma_f32_16x16x32_bf16 v[88:91], v[172:175], v[222:225], v[88:91]
	s_setprio 0
	s_setprio 1
	v_mfma_f32_16x16x32_bf16 v[132:135], v[176:179], v[192:195], v[132:135]
	v_mfma_f32_16x16x32_bf16 v[128:131], v[184:187], v[192:195], v[128:131]
	v_mfma_f32_16x16x32_bf16 v[116:119], v[176:179], v[200:203], v[116:119]
	v_mfma_f32_16x16x32_bf16 v[112:115], v[184:187], v[200:203], v[112:115]
	v_mfma_f32_16x16x32_bf16 v[100:103], v[176:179], v[208:211], v[100:103]
	v_mfma_f32_16x16x32_bf16 v[96:99], v[184:187], v[208:211], v[96:99]
	v_mfma_f32_16x16x32_bf16 v[84:87], v[176:179], v[216:219], v[84:87]
	v_mfma_f32_16x16x32_bf16 v[80:83], v[184:187], v[216:219], v[80:83]
	v_mfma_f32_16x16x32_bf16 v[132:135], v[180:183], v[196:199], v[132:135]
	v_mfma_f32_16x16x32_bf16 v[128:131], v[188:191], v[196:199], v[128:131]
	v_mfma_f32_16x16x32_bf16 v[116:119], v[180:183], v[204:207], v[116:119]
	v_mfma_f32_16x16x32_bf16 v[112:115], v[188:191], v[204:207], v[112:115]
	v_mfma_f32_16x16x32_bf16 v[100:103], v[180:183], v[212:215], v[100:103]
	v_mfma_f32_16x16x32_bf16 v[96:99], v[188:191], v[212:215], v[96:99]
	v_mfma_f32_16x16x32_bf16 v[84:87], v[180:183], v[222:225], v[84:87]
	v_mfma_f32_16x16x32_bf16 v[80:83], v[188:191], v[222:225], v[80:83]
	s_setprio 0
	s_barrier
	s_add_i32 s50, s52, s33
	v_lshl_add_u64 v[150:151], s[26:27], 0, v[152:153]
	s_mov_b32 m0, s50
	ds_read_b128 v[192:195], v51 offset:16384
	ds_read_b128 v[196:199], v51 offset:17408
	ds_read_b128 v[200:203], v51 offset:18432
	ds_read_b128 v[204:207], v51 offset:19456
	ds_read_b128 v[208:211], v51 offset:20480
	ds_read_b128 v[212:215], v51 offset:21504
	ds_read_b128 v[216:219], v51 offset:22528
	ds_read_b128 v[222:225], v51 offset:23552
	global_load_lds_dwordx4 v[150:151], off
	s_add_i32 m0, s50, 0x2000
	s_add_u32 s50, s26, 0x80000
	v_lshl_add_u64 v[226:227], s[26:27], 0, v[32:33]
	s_addc_u32 s51, s27, 0
	s_add_i32 s52, s53, s33
	global_load_lds_dwordx4 v[226:227], off
	v_lshl_add_u64 v[228:229], s[50:51], 0, v[152:153]
	s_mov_b32 m0, s52
	v_lshl_add_u64 v[230:231], s[28:29], 0, v[34:35]
	global_load_lds_dwordx4 v[228:229], off
	v_lshl_add_u64 v[228:229], s[50:51], 0, v[32:33]
	s_add_i32 m0, s52, 0x2000
	s_nop 0
	global_load_lds_dwordx4 v[228:229], off
	v_lshl_add_u64 v[228:229], s[28:29], 0, v[40:41]
	s_mov_b32 m0, s35
	s_nop 0
	global_load_lds_dwordx4 v[228:229], off
	s_mov_b32 m0, s37
	s_nop 0
	global_load_lds_dwordx4 v[230:231], off
	s_waitcnt vmcnt(8)
	s_waitcnt lgkmcnt(0)
	s_setprio 1
	s_barrier
; #define PG8_STAGE(bufoff, gbase, voff) do { _Pragma("unroll") for (int _i = 0; _i < 2; ++_i) \
;         __builtin_amdgcn_global_load_lds((const unsigned*)((const char*)(gbase) + (voff)[_i]), (PG8_LAS unsigned*)(lds + (bufoff) + ldsw + _i * 8192), 16, 0, 0); } while (0)
; #define PG8_LDA(dst, b, h) do { _Pragma("unroll") for (int m = 0; m < 4; ++m) _Pragma("unroll") for (int k = 0; k < 2; ++k) dst[m][k] = *(const PG8_LAS bf16x8*)(lds + PG8_SA(b, h) + aoff + m * 2048 + k * 1024); } while (0)
; #define PG8_LDB(dst, b, h) do { _Pragma("unroll") for (int n = 0; n < 2; ++n) _Pragma("unroll") for (int k = 0; k < 2; ++k) dst[n][k] = *(const PG8_LAS bf16x8*)(lds + PG8_SB(b, h) + boff + n * 2048 + k * 1024); } while (0)
; #define PG8_MMA(ai, bj, At, Bt) do { __builtin_amdgcn_s_setprio(1); _Pragma("unroll") for (int m = 0; m < 4; ++m) _Pragma("unroll") for (int n = 0; n < 2; ++n) _Pragma("unroll") for (int k = 0; k < 2; ++k) \
;         acc[ai][bj][m][n] = __builtin_amdgcn_mfma_f32_16x16x32_bf16(Bt[n][k], At[m][k], acc[ai][bj][m][n], 0, 0, 0); __builtin_amdgcn_s_setprio(0); } while (0)
; #define PG8_WAIT_V(n) asm volatile("s_waitcnt vmcnt(" #n ")" ::: "memory")
; #define PG8_WAIT_L(n) asm volatile("s_waitcnt lgkmcnt(" #n ")" ::: "memory")
; #define PG8_BAR __builtin_amdgcn_s_barrier()
; #define PG8_SCHED __builtin_amdgcn_sched_barrier(0)
; template <class Epi, class Sched, bool ALIGN_EPI = false, bool SP2 = false>
; __device__ __forceinline__ void gemm_phase(PG8_LAS unsigned char* lds, const Gemm g, const Sched& S, const Epi& E) {
;     ...
;             PG8_WAIT_V(8); PG8_WAIT_L(0); PG8_BAR; PG8_MMA(1, 0, At, B0); PG8_MMA(1, 1, At, B1); PG8_BAR; PG8_SCHED;
;             PG8_LDB(B0, 1, 0); PG8_LDB(B1, 1, 1); PG8_SCHED; PG8_LDA(At, 1, 0); PG8_STAGE(PG8_SA(0, 1), a2 + hstep, voffA);
;             PG8_WAIT_V(8); PG8_WAIT_L(0); PG8_BAR; PG8_MMA(0, 0, At, B0); PG8_MMA(0, 1, At, B1); PG8_BAR; PG8_SCHED;
	v_mfma_f32_16x16x32_bf16 v[76:79], v[146:149], v[192:195], v[76:79]
	v_mfma_f32_16x16x32_bf16 v[72:75], v[168:171], v[192:195], v[72:75]
	v_mfma_f32_16x16x32_bf16 v[60:63], v[146:149], v[200:203], v[60:63]
	v_mfma_f32_16x16x32_bf16 v[56:59], v[168:171], v[200:203], v[56:59]
	v_mfma_f32_16x16x32_bf16 v[28:31], v[146:149], v[208:211], v[28:31]
	v_mfma_f32_16x16x32_bf16 v[24:27], v[168:171], v[208:211], v[24:27]
	v_mfma_f32_16x16x32_bf16 v[12:15], v[146:149], v[216:219], v[12:15]
	v_mfma_f32_16x16x32_bf16 v[8:11], v[168:171], v[216:219], v[8:11]
	v_mfma_f32_16x16x32_bf16 v[76:79], v[164:167], v[196:199], v[76:79]
	v_mfma_f32_16x16x32_bf16 v[72:75], v[172:175], v[196:199], v[72:75]
	v_mfma_f32_16x16x32_bf16 v[60:63], v[164:167], v[204:207], v[60:63]
	v_mfma_f32_16x16x32_bf16 v[56:59], v[172:175], v[204:207], v[56:59]
	v_mfma_f32_16x16x32_bf16 v[28:31], v[164:167], v[212:215], v[28:31]
	v_mfma_f32_16x16x32_bf16 v[24:27], v[172:175], v[212:215], v[24:27]
	v_mfma_f32_16x16x32_bf16 v[12:15], v[164:167], v[222:225], v[12:15]
	v_mfma_f32_16x16x32_bf16 v[8:11], v[172:175], v[222:225], v[8:11]
	s_setprio 0
	s_setprio 1
	v_mfma_f32_16x16x32_bf16 v[68:71], v[176:179], v[192:195], v[68:71]
	v_mfma_f32_16x16x32_bf16 v[64:67], v[184:187], v[192:195], v[64:67]
	v_mfma_f32_16x16x32_bf16 v[52:55], v[176:179], v[200:203], v[52:55]
	v_mfma_f32_16x16x32_bf16 v[36:39], v[184:187], v[200:203], v[36:39]
	v_mfma_f32_16x16x32_bf16 v[20:23], v[176:179], v[208:211], v[20:23]
	v_mfma_f32_16x16x32_bf16 v[16:19], v[184:187], v[208:211], v[16:19]
	v_mfma_f32_16x16x32_bf16 v[4:7], v[176:179], v[216:219], v[4:7]
	v_mfma_f32_16x16x32_bf16 v[0:3], v[184:187], v[216:219], v[0:3]
	v_mfma_f32_16x16x32_bf16 v[68:71], v[180:183], v[196:199], v[68:71]
	v_mfma_f32_16x16x32_bf16 v[64:67], v[188:191], v[196:199], v[64:67]
	v_mfma_f32_16x16x32_bf16 v[52:55], v[180:183], v[204:207], v[52:55]
	v_mfma_f32_16x16x32_bf16 v[36:39], v[188:191], v[204:207], v[36:39]
	v_mfma_f32_16x16x32_bf16 v[20:23], v[180:183], v[212:215], v[20:23]
	v_mfma_f32_16x16x32_bf16 v[16:19], v[188:191], v[212:215], v[16:19]
	v_mfma_f32_16x16x32_bf16 v[4:7], v[180:183], v[222:225], v[4:7]
	v_mfma_f32_16x16x32_bf16 v[0:3], v[188:191], v[222:225], v[0:3]
	s_setprio 0
	s_barrier
	s_add_i32 s50, 0, 0x18000
	v_add_u32_e32 v145, s50, v50
	s_add_i32 s51, 0, 0x1c000
	ds_read_b128 v[146:149], v145
	ds_read_b128 v[164:167], v145 offset:1024
	ds_read_b128 v[168:171], v145 offset:2048
	ds_read_b128 v[172:175], v145 offset:3072
	v_add_u32_e32 v145, s51, v50
	ds_read_b128 v[176:179], v145
	ds_read_b128 v[180:183], v145 offset:1024
	ds_read_b128 v[184:187], v145 offset:2048
	ds_read_b128 v[188:191], v145 offset:3072
	s_add_u32 s28, s28, 0x80000
	s_addc_u32 s29, s29, 0
	s_mov_b32 m0, s38
	v_lshl_add_u64 v[232:233], s[28:29], 0, v[40:41]
	ds_read_b128 v[192:195], v51 offset:32768
	ds_read_b128 v[196:199], v51 offset:33792
	ds_read_b128 v[200:203], v51 offset:34816
	ds_read_b128 v[204:207], v51 offset:35840
	ds_read_b128 v[208:211], v51 offset:36864
	ds_read_b128 v[212:215], v51 offset:37888
	ds_read_b128 v[216:219], v51 offset:38912
	ds_read_b128 v[222:225], v51 offset:39936
	global_load_lds_dwordx4 v[232:233], off
	v_lshl_add_u64 v[232:233], s[28:29], 0, v[34:35]
	s_mov_b32 m0, s39
	s_nop 0
	global_load_lds_dwordx4 v[232:233], off
	s_waitcnt vmcnt(8)
	s_waitcnt lgkmcnt(0)
	s_setprio 1
	s_barrier
	v_mfma_f32_16x16x32_bf16 v[140:143], v[146:149], v[192:195], v[140:143]
	v_mfma_f32_16x16x32_bf16 v[136:139], v[168:171], v[192:195], v[136:139]
	v_mfma_f32_16x16x32_bf16 v[124:127], v[146:149], v[200:203], v[124:127]
	v_mfma_f32_16x16x32_bf16 v[120:123], v[168:171], v[200:203], v[120:123]
	v_mfma_f32_16x16x32_bf16 v[108:111], v[146:149], v[208:211], v[108:111]
	v_mfma_f32_16x16x32_bf16 v[104:107], v[168:171], v[208:211], v[104:107]
	v_mfma_f32_16x16x32_bf16 v[92:95], v[146:149], v[216:219], v[92:95]
	v_mfma_f32_16x16x32_bf16 v[88:91], v[168:171], v[216:219], v[88:91]
	v_mfma_f32_16x16x32_bf16 v[140:143], v[164:167], v[196:199], v[140:143]
	v_mfma_f32_16x16x32_bf16 v[136:139], v[172:175], v[196:199], v[136:139]
	v_mfma_f32_16x16x32_bf16 v[124:127], v[164:167], v[204:207], v[124:127]
	v_mfma_f32_16x16x32_bf16 v[120:123], v[172:175], v[204:207], v[120:123]
	v_mfma_f32_16x16x32_bf16 v[108:111], v[164:167], v[212:215], v[108:111]
	v_mfma_f32_16x16x32_bf16 v[104:107], v[172:175], v[212:215], v[104:107]
	v_mfma_f32_16x16x32_bf16 v[92:95], v[164:167], v[222:225], v[92:95]
	v_mfma_f32_16x16x32_bf16 v[88:91], v[172:175], v[222:225], v[88:91]
	s_setprio 0
	s_setprio 1
	v_mfma_f32_16x16x32_bf16 v[132:135], v[176:179], v[192:195], v[132:135]
	v_mfma_f32_16x16x32_bf16 v[128:131], v[184:187], v[192:195], v[128:131]
	v_mfma_f32_16x16x32_bf16 v[116:119], v[176:179], v[200:203], v[116:119]
	v_mfma_f32_16x16x32_bf16 v[112:115], v[184:187], v[200:203], v[112:115]
	v_mfma_f32_16x16x32_bf16 v[100:103], v[176:179], v[208:211], v[100:103]
	v_mfma_f32_16x16x32_bf16 v[96:99], v[184:187], v[208:211], v[96:99]
	v_mfma_f32_16x16x32_bf16 v[84:87], v[176:179], v[216:219], v[84:87]
	v_mfma_f32_16x16x32_bf16 v[80:83], v[184:187], v[216:219], v[80:83]
	v_mfma_f32_16x16x32_bf16 v[132:135], v[180:183], v[196:199], v[132:135]
	v_mfma_f32_16x16x32_bf16 v[128:131], v[188:191], v[196:199], v[128:131]
	v_mfma_f32_16x16x32_bf16 v[116:119], v[180:183], v[204:207], v[116:119]
	v_mfma_f32_16x16x32_bf16 v[112:115], v[188:191], v[204:207], v[112:115]
	v_mfma_f32_16x16x32_bf16 v[100:103], v[180:183], v[212:215], v[100:103]
	v_mfma_f32_16x16x32_bf16 v[96:99], v[188:191], v[212:215], v[96:99]
	v_mfma_f32_16x16x32_bf16 v[84:87], v[180:183], v[222:225], v[84:87]
	v_mfma_f32_16x16x32_bf16 v[80:83], v[188:191], v[222:225], v[80:83]
	s_setprio 0
	s_barrier
; #define PG8_STAGE(bufoff, gbase, voff) do { _Pragma("unroll") for (int _i = 0; _i < 2; ++_i) \
;         __builtin_amdgcn_global_load_lds((const unsigned*)((const char*)(gbase) + (voff)[_i]), (PG8_LAS unsigned*)(lds + (bufoff) + ldsw + _i * 8192), 16, 0, 0); } while (0)
; #define PG8_LDA(dst, b, h) do { _Pragma("unroll") for (int m = 0; m < 4; ++m) _Pragma("unroll") for (int k = 0; k < 2; ++k) dst[m][k] = *(const PG8_LAS bf16x8*)(lds + PG8_SA(b, h) + aoff + m * 2048 + k * 1024); } while (0)
; #define PG8_MMA(ai, bj, At, Bt) do { __builtin_amdgcn_s_setprio(1); _Pragma("unroll") for (int m = 0; m < 4; ++m) _Pragma("unroll") for (int n = 0; n < 2; ++n) _Pragma("unroll") for (int k = 0; k < 2; ++k) \
;         acc[ai][bj][m][n] = __builtin_amdgcn_mfma_f32_16x16x32_bf16(Bt[n][k], At[m][k], acc[ai][bj][m][n], 0, 0, 0); __builtin_amdgcn_s_setprio(0); } while (0)
; #define PG8_WAIT_V(n) asm volatile("s_waitcnt vmcnt(" #n ")" ::: "memory")
; #define PG8_WAIT_L(n) asm volatile("s_waitcnt lgkmcnt(" #n ")" ::: "memory")
; #define PG8_BAR __builtin_amdgcn_s_barrier()
; #define PG8_SCHED __builtin_amdgcn_sched_barrier(0)
; template <class Epi, class Sched, bool ALIGN_EPI = false, bool SP2 = false>
; __device__ __forceinline__ void gemm_phase(PG8_LAS unsigned char* lds, const Gemm g, const Sched& S, const Epi& E) {
;     ...
;             PG8_LDA(At, 1, 1); PG8_STAGE(PG8_SB(1, 0), b3, voffB); PG8_STAGE(PG8_SB(1, 1), b3 + hstep, voffB); PG8_STAGE(PG8_SA(1, 0), a3, voffA);
;             PG8_WAIT_V(8); PG8_WAIT_L(0); PG8_BAR; PG8_MMA(1, 0, At, B0); PG8_MMA(1, 1, At, B1); PG8_BAR; PG8_SCHED;
;     ...
;         if (!has_next) break;
; #pragma unroll
;         for (int a = 0; a < 2; ++a)
; #pragma unroll
;             for (int b = 0; b < 2; ++b)
; #pragma unroll
;                 for (int m = 0; m < 4; ++m)
; #pragma unroll
;                     for (int n = 0; n < 2; ++n) acc[a][b][m][n] = (f32x4){0.f, 0.f, 0.f, 0.f};
;         cur = nxt; cA = nA; cB = nB; ++ui;
	s_add_i32 s28, s50, s33
	v_lshl_add_u64 v[150:151], v[150:151], 0, s[74:75]
	s_mov_b32 m0, s28
	ds_read_b128 v[192:195], v51 offset:49152
	ds_read_b128 v[196:199], v51 offset:50176
	ds_read_b128 v[200:203], v51 offset:51200
	ds_read_b128 v[204:207], v51 offset:52224
	ds_read_b128 v[208:211], v51 offset:53248
	ds_read_b128 v[212:215], v51 offset:54272
	ds_read_b128 v[216:219], v51 offset:55296
	ds_read_b128 v[222:225], v51 offset:56320
	global_load_lds_dwordx4 v[150:151], off
	s_add_i32 m0, s28, 0x2000
	s_add_u32 s26, s26, 0x80080
	v_lshl_add_u64 v[150:151], v[226:227], 0, s[74:75]
	s_addc_u32 s27, s27, 0
	s_add_i32 s28, s51, s33
	global_load_lds_dwordx4 v[150:151], off
	v_lshl_add_u64 v[150:151], s[26:27], 0, v[152:153]
	s_mov_b32 m0, s28
	s_nop 0
	global_load_lds_dwordx4 v[150:151], off
	v_lshl_add_u64 v[150:151], s[26:27], 0, v[32:33]
	s_add_i32 m0, s28, 0x2000
	s_nop 0
	global_load_lds_dwordx4 v[150:151], off
	v_lshl_add_u64 v[150:151], v[228:229], 0, s[74:75]
	s_mov_b32 m0, s40
	s_nop 0
	global_load_lds_dwordx4 v[150:151], off
	v_lshl_add_u64 v[150:151], v[230:231], 0, s[74:75]
	s_mov_b32 m0, s41
	s_nop 0
	global_load_lds_dwordx4 v[150:151], off
	s_waitcnt vmcnt(8)
	s_waitcnt lgkmcnt(0)
	s_setprio 1
	s_barrier
	v_mfma_f32_16x16x32_bf16 v[76:79], v[146:149], v[192:195], v[76:79]
	v_mfma_f32_16x16x32_bf16 v[72:75], v[168:171], v[192:195], v[72:75]
	v_mfma_f32_16x16x32_bf16 v[60:63], v[146:149], v[200:203], v[60:63]
	v_mfma_f32_16x16x32_bf16 v[56:59], v[168:171], v[200:203], v[56:59]
	v_mfma_f32_16x16x32_bf16 v[28:31], v[146:149], v[208:211], v[28:31]
	v_mfma_f32_16x16x32_bf16 v[24:27], v[168:171], v[208:211], v[24:27]
	v_mfma_f32_16x16x32_bf16 v[12:15], v[146:149], v[216:219], v[12:15]
	v_mfma_f32_16x16x32_bf16 v[8:11], v[168:171], v[216:219], v[8:11]
	v_mfma_f32_16x16x32_bf16 v[76:79], v[164:167], v[196:199], v[76:79]
	v_mfma_f32_16x16x32_bf16 v[72:75], v[172:175], v[196:199], v[72:75]
	v_mfma_f32_16x16x32_bf16 v[60:63], v[164:167], v[204:207], v[60:63]
	v_mfma_f32_16x16x32_bf16 v[56:59], v[172:175], v[204:207], v[56:59]
	v_mfma_f32_16x16x32_bf16 v[28:31], v[164:167], v[212:215], v[28:31]
	v_mfma_f32_16x16x32_bf16 v[24:27], v[172:175], v[212:215], v[24:27]
	v_mfma_f32_16x16x32_bf16 v[12:15], v[164:167], v[222:225], v[12:15]
	v_mfma_f32_16x16x32_bf16 v[8:11], v[172:175], v[222:225], v[8:11]
	s_setprio 0
	s_setprio 1
	v_mfma_f32_16x16x32_bf16 v[68:71], v[176:179], v[192:195], v[68:71]
	v_mfma_f32_16x16x32_bf16 v[64:67], v[184:187], v[192:195], v[64:67]
	v_mfma_f32_16x16x32_bf16 v[52:55], v[176:179], v[200:203], v[52:55]
	v_mfma_f32_16x16x32_bf16 v[36:39], v[184:187], v[200:203], v[36:39]
	v_mfma_f32_16x16x32_bf16 v[20:23], v[176:179], v[208:211], v[20:23]
	v_mfma_f32_16x16x32_bf16 v[16:19], v[184:187], v[208:211], v[16:19]
	v_mfma_f32_16x16x32_bf16 v[4:7], v[176:179], v[216:219], v[4:7]
	v_mfma_f32_16x16x32_bf16 v[0:3], v[184:187], v[216:219], v[0:3]
	v_mfma_f32_16x16x32_bf16 v[68:71], v[180:183], v[196:199], v[68:71]
	v_mfma_f32_16x16x32_bf16 v[64:67], v[188:191], v[196:199], v[64:67]
	v_mfma_f32_16x16x32_bf16 v[52:55], v[180:183], v[204:207], v[52:55]
	v_mfma_f32_16x16x32_bf16 v[36:39], v[188:191], v[204:207], v[36:39]
	v_mfma_f32_16x16x32_bf16 v[20:23], v[180:183], v[212:215], v[20:23]
	v_mfma_f32_16x16x32_bf16 v[16:19], v[188:191], v[212:215], v[16:19]
	v_mfma_f32_16x16x32_bf16 v[4:7], v[180:183], v[222:225], v[4:7]
	v_mfma_f32_16x16x32_bf16 v[0:3], v[188:191], v[222:225], v[0:3]
	s_setprio 0
	s_barrier
	s_add_i32 s49, s49, 2
	s_add_u32 s24, s24, 0x100
	s_addc_u32 s25, s25, 0
	s_cmp_gt_u32 s49, 29
	s_cbranch_scc0 .LBB0_883
	s_add_u32 s24, s45, 0xffffff00
	s_addc_u32 s25, s46, -1
	s_andn2_b64 vcc, exec, s[4:5]
	s_cbranch_vccnz .LBB0_874
	v_mov_b32_e32 v0, 0
	s_mov_b32 s12, s16
	s_mov_b32 s42, s18
	s_mov_b64 s[14:15], s[22:23]
	s_mov_b32 s43, s44
	v_mov_b32_e32 v1, v0
	v_mov_b32_e32 v2, v0
	v_mov_b32_e32 v3, v0
	v_mov_b32_e32 v4, v0
	v_mov_b32_e32 v5, v0
	v_mov_b32_e32 v6, v0
	v_mov_b32_e32 v7, v0
	v_mov_b32_e32 v16, v0
	v_mov_b32_e32 v17, v0
	v_mov_b32_e32 v18, v0
	v_mov_b32_e32 v19, v0
	v_mov_b32_e32 v20, v0
	v_mov_b32_e32 v21, v0
	v_mov_b32_e32 v22, v0
	v_mov_b32_e32 v23, v0
	v_mov_b32_e32 v36, v0
	v_mov_b32_e32 v37, v0
	v_mov_b32_e32 v38, v0
	v_mov_b32_e32 v39, v0
	v_mov_b32_e32 v52, v0
	v_mov_b32_e32 v53, v0
	v_mov_b32_e32 v54, v0
	v_mov_b32_e32 v55, v0
	v_mov_b32_e32 v64, v0
	v_mov_b32_e32 v65, v0
	v_mov_b32_e32 v66, v0
	v_mov_b32_e32 v67, v0
	v_mov_b32_e32 v68, v0
	v_mov_b32_e32 v69, v0
	v_mov_b32_e32 v70, v0
	v_mov_b32_e32 v71, v0
	v_mov_b32_e32 v8, v0
	v_mov_b32_e32 v9, v0
	v_mov_b32_e32 v10, v0
	v_mov_b32_e32 v11, v0
	v_mov_b32_e32 v12, v0
	v_mov_b32_e32 v13, v0
	v_mov_b32_e32 v14, v0
	v_mov_b32_e32 v15, v0
	v_mov_b32_e32 v24, v0
	v_mov_b32_e32 v25, v0
	v_mov_b32_e32 v26, v0
	v_mov_b32_e32 v27, v0
	v_mov_b32_e32 v28, v0
	v_mov_b32_e32 v29, v0
	v_mov_b32_e32 v30, v0
	v_mov_b32_e32 v31, v0
	v_mov_b32_e32 v56, v0
	v_mov_b32_e32 v57, v0
	v_mov_b32_e32 v58, v0
	v_mov_b32_e32 v59, v0
	v_mov_b32_e32 v60, v0
	v_mov_b32_e32 v61, v0
	v_mov_b32_e32 v62, v0
	v_mov_b32_e32 v63, v0
	v_mov_b32_e32 v72, v0
	v_mov_b32_e32 v73, v0
	v_mov_b32_e32 v74, v0
	v_mov_b32_e32 v75, v0
	v_mov_b32_e32 v76, v0
	v_mov_b32_e32 v77, v0
	v_mov_b32_e32 v78, v0
	v_mov_b32_e32 v79, v0
	v_mov_b32_e32 v80, v0
	v_mov_b32_e32 v81, v0
	v_mov_b32_e32 v82, v0
	v_mov_b32_e32 v83, v0
	v_mov_b32_e32 v84, v0
	v_mov_b32_e32 v85, v0
	v_mov_b32_e32 v86, v0
	v_mov_b32_e32 v87, v0
	v_mov_b32_e32 v96, v0
	v_mov_b32_e32 v97, v0
	v_mov_b32_e32 v98, v0
	v_mov_b32_e32 v99, v0
	v_mov_b32_e32 v100, v0
	v_mov_b32_e32 v101, v0
	v_mov_b32_e32 v102, v0
	v_mov_b32_e32 v103, v0
	v_mov_b32_e32 v112, v0
	v_mov_b32_e32 v113, v0
	v_mov_b32_e32 v114, v0
	v_mov_b32_e32 v115, v0
	v_mov_b32_e32 v116, v0
	v_mov_b32_e32 v117, v0
	v_mov_b32_e32 v118, v0
	v_mov_b32_e32 v119, v0
	v_mov_b32_e32 v128, v0
	v_mov_b32_e32 v129, v0
	v_mov_b32_e32 v130, v0
	v_mov_b32_e32 v131, v0
	v_mov_b32_e32 v132, v0
	v_mov_b32_e32 v133, v0
	v_mov_b32_e32 v134, v0
	v_mov_b32_e32 v135, v0
	v_mov_b32_e32 v88, v0
	v_mov_b32_e32 v89, v0
	v_mov_b32_e32 v90, v0
	v_mov_b32_e32 v91, v0
	v_mov_b32_e32 v92, v0
	v_mov_b32_e32 v93, v0
	v_mov_b32_e32 v94, v0
	v_mov_b32_e32 v95, v0
	v_mov_b32_e32 v104, v0
	v_mov_b32_e32 v105, v0
	v_mov_b32_e32 v106, v0
	v_mov_b32_e32 v107, v0
	v_mov_b32_e32 v108, v0
	v_mov_b32_e32 v109, v0
	v_mov_b32_e32 v110, v0
	v_mov_b32_e32 v111, v0
	v_mov_b32_e32 v120, v0
	v_mov_b32_e32 v121, v0
	v_mov_b32_e32 v122, v0
	v_mov_b32_e32 v123, v0
	v_mov_b32_e32 v124, v0
	v_mov_b32_e32 v125, v0
	v_mov_b32_e32 v126, v0
	v_mov_b32_e32 v127, v0
	v_mov_b32_e32 v136, v0
	v_mov_b32_e32 v137, v0
	v_mov_b32_e32 v138, v0
	v_mov_b32_e32 v139, v0
	v_mov_b32_e32 v140, v0
	v_mov_b32_e32 v141, v0
	v_mov_b32_e32 v142, v0
	v_mov_b32_e32 v143, v0
	s_andn2_b64 vcc, exec, s[0:1]
	s_cbranch_vccnz .LBB0_875

; __device__ __forceinline__ unsigned xb_ld(unsigned* p)              { return __hip_atomic_load(p, __ATOMIC_RELAXED, __HIP_MEMORY_SCOPE_AGENT); }
; __device__ __forceinline__ unsigned xb_add(unsigned* p, unsigned v) { return __hip_atomic_fetch_add(p, v, __ATOMIC_RELAXED, __HIP_MEMORY_SCOPE_AGENT); }
; #define XB_SPIN(cond, bar) do { unsigned _sp = 0; while (cond) { __builtin_amdgcn_s_sleep(1); \
;     if ((++_sp & 255u) == 0u) { if (xb_ld(&(bar)[XB_TMO])) break; if (_sp > XB_SPIN_CAP) { atomicAdd(&(bar)[XB_TMO], 1u); break; } } } } while (0)
; __device__ __forceinline__ void xcd_barrier(const XcdBarrier& b) {
;     ...
;         const unsigned old = xb_add(&bar[XB_XSUB(b.x)], 1u);
;         const unsigned gen = old / nloc;
;         if (old + 1u == (gen + 1u) * nloc) {
;             __builtin_amdgcn_fence(__ATOMIC_RELEASE, "agent");
;             asm volatile("s_waitcnt vmcnt(0)" ::: "memory");
;             const unsigned og = xb_add(&bar[XB_TOP], 1u);
;             const unsigned tg = og / nx;
;             if (og + 1u == (tg + 1u) * nx) xb_add(&bar[XB_TOPGEN], 1u);
;             else XB_SPIN(xb_ld(&bar[XB_TOPGEN]) == tg, bar);
;             __builtin_amdgcn_fence(__ATOMIC_ACQUIRE, "agent");
;             xb_add(&bar[XB_XGEN(b.x)], 1u);
;             asm volatile("s_waitcnt vmcnt(0)" ::: "memory");
;         } else {
;             XB_SPIN(xb_ld(&bar[XB_XGEN(b.x)]) == gen, bar);
;             __builtin_amdgcn_fence(__ATOMIC_ACQUIRE, "agent");
.LBB0_925:
	s_or_b64 exec, exec, s[18:19]
	v_cvt_f32_u32_e32 v19, v17
	s_waitcnt vmcnt(0)
	v_readfirstlane_b32 s13, v18
	v_sub_u32_e32 v18, 0, v17
	v_rcp_iflag_f32_e32 v19, v19
	v_add_u32_e32 v32, s13, v3
	v_mul_f32_e32 v19, 0x4f7ffffe, v19
	v_cvt_u32_f32_e32 v19, v19
	v_mul_lo_u32 v3, v18, v19
	v_mul_hi_u32 v3, v19, v3
	v_add_u32_e32 v3, v19, v3
	v_mul_hi_u32 v3, v32, v3
	v_mul_lo_u32 v18, v3, v17
	v_sub_u32_e32 v18, v32, v18
	v_add_u32_e32 v19, 1, v3
	v_cmp_ge_u32_e32 vcc, v18, v17
	s_nop 1
	v_cndmask_b32_e32 v3, v3, v19, vcc
	v_sub_u32_e32 v19, v18, v17
	v_cndmask_b32_e32 v18, v18, v19, vcc
	v_add_u32_e32 v19, 1, v3
	v_cmp_ge_u32_e32 vcc, v18, v17
	v_add_u32_e32 v18, 1, v32
	s_nop 0
	v_cndmask_b32_e32 v3, v3, v19, vcc
	v_mul_lo_u32 v19, v17, v3
	v_add_u32_e32 v17, v19, v17
	v_cmp_ne_u32_e32 vcc, v18, v17
	s_and_saveexec_b64 s[16:17], vcc
	s_xor_b64 s[16:17], exec, s[16:17]
	s_cbranch_execz .LBB0_939
	s_waitcnt lgkmcnt(0)
	buffer_inv sc1
	v_mad_u32_u24 v3, v3, v2, v2
	v_mov_b32_e32 v2, 0x2e403000
	global_load_dword v2, v2, s[10:11] offset:1024 sc1
	s_add_u32 s22, s10, 0x2e403400
	s_addc_u32 s23, s11, 0
	s_waitcnt vmcnt(0)
	v_cmp_lt_u32_e32 vcc, v2, v3
	s_and_saveexec_b64 s[18:19], vcc
	s_cbranch_execz .LBB0_938
	s_add_u32 s20, s10, 0x2e400200
	s_addc_u32 s21, s11, 0
	s_mov_b32 s13, 1
	s_mov_b64 s[24:25], 0
	s_branch .LBB0_929

; __device__ __forceinline__ unsigned xb_ld(unsigned* p)              { return __hip_atomic_load(p, __ATOMIC_RELAXED, __HIP_MEMORY_SCOPE_AGENT); }
; #define XB_SPIN(cond, bar) do { unsigned _sp = 0; while (cond) { __builtin_amdgcn_s_sleep(1); \
;     if ((++_sp & 255u) == 0u) { if (xb_ld(&(bar)[XB_TMO])) break; if (_sp > XB_SPIN_CAP) { atomicAdd(&(bar)[XB_TMO], 1u); break; } } } } while (0)
; __device__ __forceinline__ void xcd_barrier(const XcdBarrier& b) {
;     ...
;             XB_SPIN(xb_ld(&bar[XB_XGEN(b.x)]) == gen, bar);
.LBB0_931:
	global_load_dword v2, v153, s[22:23] sc1
	s_add_i32 s13, s13, 1
	s_mov_b64 s[30:31], -1
	s_waitcnt vmcnt(0)
	v_cmp_ge_u32_e32 vcc, v2, v3
	s_orn2_b64 s[28:29], vcc, exec
	s_branch .LBB0_928

; __device__ __forceinline__ unsigned xb_ld(unsigned* p)              { return __hip_atomic_load(p, __ATOMIC_RELAXED, __HIP_MEMORY_SCOPE_AGENT); }
; __device__ __forceinline__ unsigned xb_add(unsigned* p, unsigned v) { return __hip_atomic_fetch_add(p, v, __ATOMIC_RELAXED, __HIP_MEMORY_SCOPE_AGENT); }
; #define XB_SPIN(cond, bar) do { unsigned _sp = 0; while (cond) { __builtin_amdgcn_s_sleep(1); \
;     if ((++_sp & 255u) == 0u) { if (xb_ld(&(bar)[XB_TMO])) break; if (_sp > XB_SPIN_CAP) { atomicAdd(&(bar)[XB_TMO], 1u); break; } } } } while (0)
; __device__ __forceinline__ void xcd_barrier(const XcdBarrier& b) {
;     ...
;         const unsigned old = xb_add(&bar[XB_XSUB(b.x)], 1u);
;         const unsigned gen = old / nloc;
;         if (old + 1u == (gen + 1u) * nloc) {
;             __builtin_amdgcn_fence(__ATOMIC_RELEASE, "agent");
;             asm volatile("s_waitcnt vmcnt(0)" ::: "memory");
;             const unsigned og = xb_add(&bar[XB_TOP], 1u);
;             const unsigned tg = og / nx;
;             if (og + 1u == (tg + 1u) * nx) xb_add(&bar[XB_TOPGEN], 1u);
;             else XB_SPIN(xb_ld(&bar[XB_TOPGEN]) == tg, bar);
;             __builtin_amdgcn_fence(__ATOMIC_ACQUIRE, "agent");
;             xb_add(&bar[XB_XGEN(b.x)], 1u);
;             asm volatile("s_waitcnt vmcnt(0)" ::: "memory");
;         } else {
;             XB_SPIN(xb_ld(&bar[XB_XGEN(b.x)]) == gen, bar);
;             __builtin_amdgcn_fence(__ATOMIC_ACQUIRE, "agent");
.LBB0_986:
	s_or_b64 exec, exec, s[10:11]
	v_cvt_f32_u32_e32 v4, v2
	s_waitcnt vmcnt(0)
	v_readfirstlane_b32 s8, v3
	v_sub_u32_e32 v3, 0, v2
	v_rcp_iflag_f32_e32 v4, v4
	v_add_u32_e32 v5, s8, v1
	v_mul_f32_e32 v4, 0x4f7ffffe, v4
	v_cvt_u32_f32_e32 v4, v4
	v_mul_lo_u32 v1, v3, v4
	v_mul_hi_u32 v1, v4, v1
	v_add_u32_e32 v1, v4, v1
	v_mul_hi_u32 v1, v5, v1
	v_mul_lo_u32 v3, v1, v2
	v_sub_u32_e32 v3, v5, v3
	v_add_u32_e32 v4, 1, v1
	v_cmp_ge_u32_e32 vcc, v3, v2
	s_nop 1
	v_cndmask_b32_e32 v1, v1, v4, vcc
	v_sub_u32_e32 v4, v3, v2
	v_cndmask_b32_e32 v3, v3, v4, vcc
	v_add_u32_e32 v4, 1, v1
	v_cmp_ge_u32_e32 vcc, v3, v2
	v_add_u32_e32 v3, 1, v5
	s_nop 0
	v_cndmask_b32_e32 v1, v1, v4, vcc
	v_mul_lo_u32 v4, v2, v1
	v_add_u32_e32 v2, v4, v2
	v_cmp_ne_u32_e32 vcc, v3, v2
	s_and_saveexec_b64 s[8:9], vcc
	s_xor_b64 s[8:9], exec, s[8:9]
	s_cbranch_execz .LBB0_1000
	s_waitcnt lgkmcnt(0)
	buffer_inv sc1
	v_mad_u32_u24 v1, v1, v0, v0
	v_mov_b32_e32 v0, 0x2e403000
	global_load_dword v0, v0, s[2:3] offset:1024 sc1
	s_add_u32 s14, s2, 0x2e403400
	s_addc_u32 s15, s3, 0
	s_waitcnt vmcnt(0)
	v_cmp_lt_u32_e32 vcc, v0, v1
	s_and_saveexec_b64 s[10:11], vcc
	s_cbranch_execz .LBB0_999
	s_add_u32 s12, s2, 0x2e400200
	s_addc_u32 s13, s3, 0
	s_mov_b32 s26, 1
	s_mov_b64 s[16:17], 0
	s_branch .LBB0_990

; __device__ __forceinline__ unsigned xb_ld(unsigned* p)              { return __hip_atomic_load(p, __ATOMIC_RELAXED, __HIP_MEMORY_SCOPE_AGENT); }
; #define XB_SPIN(cond, bar) do { unsigned _sp = 0; while (cond) { __builtin_amdgcn_s_sleep(1); \
;     if ((++_sp & 255u) == 0u) { if (xb_ld(&(bar)[XB_TMO])) break; if (_sp > XB_SPIN_CAP) { atomicAdd(&(bar)[XB_TMO], 1u); break; } } } } while (0)
; __device__ __forceinline__ void xcd_barrier(const XcdBarrier& b) {
;     ...
;             XB_SPIN(xb_ld(&bar[XB_XGEN(b.x)]) == gen, bar);
.LBB0_992:
	global_load_dword v0, v153, s[14:15] sc1
	s_add_i32 s26, s26, 1
	s_mov_b64 s[22:23], -1
	s_waitcnt vmcnt(0)
	v_cmp_ge_u32_e32 vcc, v0, v1
	s_orn2_b64 s[20:21], vcc, exec
	s_branch .LBB0_989

; #define PG8_STAGE(bufoff, gbase, voff) do { _Pragma("unroll") for (int _i = 0; _i < 2; ++_i) \
;         __builtin_amdgcn_global_load_lds((const unsigned*)((const char*)(gbase) + (voff)[_i]), (PG8_LAS unsigned*)(lds + (bufoff) + ldsw + _i * 8192), 16, 0, 0); } while (0)
; #define PG8_LDA(dst, b, h) do { _Pragma("unroll") for (int m = 0; m < 4; ++m) _Pragma("unroll") for (int k = 0; k < 2; ++k) dst[m][k] = *(const PG8_LAS bf16x8*)(lds + PG8_SA(b, h) + aoff + m * 2048 + k * 1024); } while (0)
; #define PG8_LDB(dst, b, h) do { _Pragma("unroll") for (int n = 0; n < 2; ++n) _Pragma("unroll") for (int k = 0; k < 2; ++k) dst[n][k] = *(const PG8_LAS bf16x8*)(lds + PG8_SB(b, h) + boff + n * 2048 + k * 1024); } while (0)
; #define PG8_WAIT_V(n) asm volatile("s_waitcnt vmcnt(" #n ")" ::: "memory")
; #define PG8_WAIT_L(n) asm volatile("s_waitcnt lgkmcnt(" #n ")" ::: "memory")
; #define PG8_BAR __builtin_amdgcn_s_barrier()
; template <class Epi, class Sched, bool ALIGN_EPI = false, bool SP2 = false>
; __device__ __forceinline__ void gemm_phase(PG8_LAS unsigned char* lds, const Gemm g, const Sched& S, const Epi& E) {
;     ...
;         const bool has_next = S.next(ui + 1, nxt);
;         const char* nA = has_next ? (const char*)g.A + (size_t)nxt.pm * tstep : cA; const char* nB = has_next ? (const char*)g.Bt + (size_t)nxt.pn * tstep : cB;
;         for (int t = 0; t < nt; t += 2) {
;             const bool last = (t == nt - 2);
;             const char* a1 = cA + (size_t)(t + 1) * kstep;
;             const char* a2 = last ? nA : cA + (size_t)(t + 2) * kstep; const char* b2 = last ? nB : cB + (size_t)(t + 2) * kstep;
;             const char* a3 = a2 + kstep; const char* b3 = b2 + kstep;
;             if (last && has_next) S.a_ready(nxt);
;             if constexpr (SP2) {
;             PG8_LDB(B0, 0, 0); PG8_LDB(B1, 0, 1); PG8_SCHED; PG8_LDA(At, 0, 0); PG8_STAGE(PG8_SA(1, 1), a1 + hstep, voffA);
;             PG8_WAIT_V(8); PG8_WAIT_L(0); PG8_BAR; PG8_MMA(0, 0, At, B0); PG8_MMA(0, 1, At, B1); PG8_BAR; PG8_SCHED;
;     ...
; #pragma unroll
;         for (int a = 0; a < 2; ++a)
; #pragma unroll
;             for (int b = 0; b < 2; ++b)
; #pragma unroll
;                 for (int m = 0; m < 4; ++m)
; #pragma unroll
;                     for (int n = 0; n < 2; ++n) acc[a][b][m][n] = (f32x4){0.f, 0.f, 0.f, 0.f};
;         cur = nxt; cA = nA; cB = nB; ++ui;
.LBB0_1057:
	s_ashr_i32 s21, s20, 31
	s_lshl_b64 s[22:23], s[20:21], 20
	s_add_u32 s22, s12, s22
	s_addc_u32 s23, s13, s23
	s_and_b64 s[24:25], s[0:1], exec
	s_cselect_b32 s21, s23, s27
	s_cselect_b32 s47, s22, s26
	s_ashr_i32 s19, s18, 31
	s_lshl_b64 s[24:25], s[18:19], 20
	s_add_u32 s24, s33, s24
	s_addc_u32 s25, s34, s25
	s_and_b64 s[30:31], s[0:1], exec
	s_cselect_b32 s19, s25, s29
	s_cselect_b32 s48, s24, s28
	s_add_u32 s26, s26, 0x80080
	s_addc_u32 s27, s27, 0
	s_add_u32 s49, s28, 0x100
	v_mov_b32_e32 v0, 0
	s_addc_u32 s50, s29, 0
	s_mov_b32 s51, -2
	v_mov_b32_e32 v1, v0
	v_mov_b32_e32 v2, v0
	v_mov_b32_e32 v3, v0
	v_mov_b32_e32 v4, v0
	v_mov_b32_e32 v5, v0
	v_mov_b32_e32 v6, v0
	v_mov_b32_e32 v7, v0
	v_mov_b32_e32 v16, v0
	v_mov_b32_e32 v17, v0
	v_mov_b32_e32 v18, v0
	v_mov_b32_e32 v19, v0
	v_mov_b32_e32 v20, v0
	v_mov_b32_e32 v21, v0
	v_mov_b32_e32 v22, v0
	v_mov_b32_e32 v23, v0
	v_mov_b32_e32 v32, v0
	v_mov_b32_e32 v33, v0
	v_mov_b32_e32 v34, v0
	v_mov_b32_e32 v35, v0
	v_mov_b32_e32 v36, v0
	v_mov_b32_e32 v37, v0
	v_mov_b32_e32 v38, v0
	v_mov_b32_e32 v39, v0
	v_mov_b32_e32 v48, v0
	v_mov_b32_e32 v49, v0
	v_mov_b32_e32 v50, v0
	v_mov_b32_e32 v51, v0
	v_mov_b32_e32 v52, v0
	v_mov_b32_e32 v53, v0
	v_mov_b32_e32 v54, v0
	v_mov_b32_e32 v55, v0
	v_mov_b32_e32 v8, v0
	v_mov_b32_e32 v9, v0
	v_mov_b32_e32 v10, v0
	v_mov_b32_e32 v11, v0
	v_mov_b32_e32 v12, v0
	v_mov_b32_e32 v13, v0
	v_mov_b32_e32 v14, v0
	v_mov_b32_e32 v15, v0
	v_mov_b32_e32 v24, v0
	v_mov_b32_e32 v25, v0
	v_mov_b32_e32 v26, v0
	v_mov_b32_e32 v27, v0
	v_mov_b32_e32 v28, v0
	v_mov_b32_e32 v29, v0
	v_mov_b32_e32 v30, v0
	v_mov_b32_e32 v31, v0
	v_mov_b32_e32 v40, v0
	v_mov_b32_e32 v41, v0
	v_mov_b32_e32 v42, v0
	v_mov_b32_e32 v43, v0
	v_mov_b32_e32 v44, v0
	v_mov_b32_e32 v45, v0
	v_mov_b32_e32 v46, v0
	v_mov_b32_e32 v47, v0
	v_mov_b32_e32 v56, v0
	v_mov_b32_e32 v57, v0
	v_mov_b32_e32 v58, v0
	v_mov_b32_e32 v59, v0
	v_mov_b32_e32 v60, v0
	v_mov_b32_e32 v61, v0
	v_mov_b32_e32 v62, v0
	v_mov_b32_e32 v63, v0
	v_mov_b32_e32 v64, v0
	v_mov_b32_e32 v65, v0
	v_mov_b32_e32 v66, v0
	v_mov_b32_e32 v67, v0
	v_mov_b32_e32 v68, v0
	v_mov_b32_e32 v69, v0
	v_mov_b32_e32 v70, v0
	v_mov_b32_e32 v71, v0
	v_mov_b32_e32 v80, v0
	v_mov_b32_e32 v81, v0
	v_mov_b32_e32 v82, v0
	v_mov_b32_e32 v83, v0
	v_mov_b32_e32 v84, v0
	v_mov_b32_e32 v85, v0
	v_mov_b32_e32 v86, v0
	v_mov_b32_e32 v87, v0
	v_mov_b32_e32 v96, v0
	v_mov_b32_e32 v97, v0
	v_mov_b32_e32 v98, v0
	v_mov_b32_e32 v99, v0
	v_mov_b32_e32 v100, v0
	v_mov_b32_e32 v101, v0
	v_mov_b32_e32 v102, v0
	v_mov_b32_e32 v103, v0
	v_mov_b32_e32 v112, v0
	v_mov_b32_e32 v113, v0
	v_mov_b32_e32 v114, v0
	v_mov_b32_e32 v115, v0
	v_mov_b32_e32 v116, v0
	v_mov_b32_e32 v117, v0
	v_mov_b32_e32 v118, v0
	v_mov_b32_e32 v119, v0
	v_mov_b32_e32 v72, v0
	v_mov_b32_e32 v73, v0
	v_mov_b32_e32 v74, v0
	v_mov_b32_e32 v75, v0
	v_mov_b32_e32 v76, v0
	v_mov_b32_e32 v77, v0
	v_mov_b32_e32 v78, v0
	v_mov_b32_e32 v79, v0
	v_mov_b32_e32 v88, v0
	v_mov_b32_e32 v89, v0
	v_mov_b32_e32 v90, v0
	v_mov_b32_e32 v91, v0
	v_mov_b32_e32 v92, v0
	v_mov_b32_e32 v93, v0
	v_mov_b32_e32 v94, v0
	v_mov_b32_e32 v95, v0
	v_mov_b32_e32 v104, v0
	v_mov_b32_e32 v105, v0
	v_mov_b32_e32 v106, v0
	v_mov_b32_e32 v107, v0
	v_mov_b32_e32 v108, v0
	v_mov_b32_e32 v109, v0
	v_mov_b32_e32 v110, v0
	v_mov_b32_e32 v111, v0
	v_mov_b32_e32 v120, v0
	v_mov_b32_e32 v121, v0
	v_mov_b32_e32 v122, v0
	v_mov_b32_e32 v123, v0
	v_mov_b32_e32 v124, v0
	v_mov_b32_e32 v125, v0
	v_mov_b32_e32 v126, v0
	v_mov_b32_e32 v127, v0
	s_nop 0
	s_nop 0
	s_nop 0
	s_nop 0
	s_nop 0
	s_nop 0
	s_nop 0
	s_nop 0
	s_nop 0
	s_nop 0
	s_nop 0
	s_nop 0
.LBB0_1058:
	s_add_u32 s28, s26, 0xfff80080
	s_addc_u32 s29, s27, -1
	s_add_i32 s52, 0, 0x10000
	s_cmp_eq_u32 s51, 28
	s_cselect_b32 s31, s21, s29
	s_cselect_b32 s30, s47, s28
	v_add_u32_e32 v150, s52, v144
	s_cselect_b32 s29, s19, s50
	s_cselect_b32 s28, s48, s49
	s_add_i32 s54, 0, 0x14000
	ds_read_b128 v[138:141], v150
	ds_read_b128 v[146:149], v150 offset:1024
	ds_read_b128 v[164:167], v150 offset:2048
	ds_read_b128 v[168:171], v150 offset:3072
	v_add_u32_e32 v150, s54, v144
	ds_read_b128 v[172:175], v150
	ds_read_b128 v[176:179], v150 offset:1024
	ds_read_b128 v[180:183], v150 offset:2048
	ds_read_b128 v[184:187], v150 offset:3072
	v_lshl_add_u64 v[150:151], s[26:27], 0, v[134:135]
	s_add_i32 m0, s36, 0xc000
	ds_read_b128 v[188:191], v145
	ds_read_b128 v[192:195], v145 offset:1024
	ds_read_b128 v[196:199], v145 offset:2048
	ds_read_b128 v[200:203], v145 offset:3072
	ds_read_b128 v[204:207], v145 offset:4096
	ds_read_b128 v[208:211], v145 offset:5120
	ds_read_b128 v[212:215], v145 offset:6144
	ds_read_b128 v[216:219], v145 offset:7168
	global_load_lds_dwordx4 v[150:151], off
	v_lshl_add_u64 v[150:151], s[26:27], 0, v[136:137]
	s_add_i32 m0, s36, 0xe000
	s_nop 0
	global_load_lds_dwordx4 v[150:151], off
	s_waitcnt vmcnt(8)
	s_waitcnt lgkmcnt(0)
	s_setprio 1
	s_barrier
; #define PG8_STAGE(bufoff, gbase, voff) do { _Pragma("unroll") for (int _i = 0; _i < 2; ++_i) \
;         __builtin_amdgcn_global_load_lds((const unsigned*)((const char*)(gbase) + (voff)[_i]), (PG8_LAS unsigned*)(lds + (bufoff) + ldsw + _i * 8192), 16, 0, 0); } while (0)
; #define PG8_LDA(dst, b, h) do { _Pragma("unroll") for (int m = 0; m < 4; ++m) _Pragma("unroll") for (int k = 0; k < 2; ++k) dst[m][k] = *(const PG8_LAS bf16x8*)(lds + PG8_SA(b, h) + aoff + m * 2048 + k * 1024); } while (0)
; #define PG8_MMA(ai, bj, At, Bt) do { __builtin_amdgcn_s_setprio(1); _Pragma("unroll") for (int m = 0; m < 4; ++m) _Pragma("unroll") for (int n = 0; n < 2; ++n) _Pragma("unroll") for (int k = 0; k < 2; ++k) \
;         acc[ai][bj][m][n] = __builtin_amdgcn_mfma_f32_16x16x32_bf16(Bt[n][k], At[m][k], acc[ai][bj][m][n], 0, 0, 0); __builtin_amdgcn_s_setprio(0); } while (0)
; #define PG8_WAIT_V(n) asm volatile("s_waitcnt vmcnt(" #n ")" ::: "memory")
; #define PG8_WAIT_L(n) asm volatile("s_waitcnt lgkmcnt(" #n ")" ::: "memory")
; #define PG8_BAR __builtin_amdgcn_s_barrier()
; #define PG8_SCHED __builtin_amdgcn_sched_barrier(0)
; template <class Epi, class Sched, bool ALIGN_EPI = false, bool SP2 = false>
; __device__ __forceinline__ void gemm_phase(PG8_LAS unsigned char* lds, const Gemm g, const Sched& S, const Epi& E) {
;     ...
;             PG8_WAIT_V(8); PG8_WAIT_L(0); PG8_BAR; PG8_MMA(0, 0, At, B0); PG8_MMA(0, 1, At, B1); PG8_BAR; PG8_SCHED;
;             PG8_LDA(At, 0, 1); PG8_STAGE(PG8_SB(0, 0), b2, voffB); PG8_STAGE(PG8_SB(0, 1), b2 + hstep, voffB); PG8_STAGE(PG8_SA(0, 0), a2, voffA);
;             PG8_WAIT_V(8); PG8_WAIT_L(0); PG8_BAR; PG8_MMA(1, 0, At, B0); PG8_MMA(1, 1, At, B1); PG8_BAR; PG8_SCHED;
	v_mfma_f32_16x16x32_bf16 v[124:127], v[138:141], v[188:191], v[124:127]
	v_mfma_f32_16x16x32_bf16 v[120:123], v[164:167], v[188:191], v[120:123]
	v_mfma_f32_16x16x32_bf16 v[108:111], v[138:141], v[196:199], v[108:111]
	v_mfma_f32_16x16x32_bf16 v[104:107], v[164:167], v[196:199], v[104:107]
	v_mfma_f32_16x16x32_bf16 v[92:95], v[138:141], v[204:207], v[92:95]
	v_mfma_f32_16x16x32_bf16 v[88:91], v[164:167], v[204:207], v[88:91]
	v_mfma_f32_16x16x32_bf16 v[76:79], v[138:141], v[212:215], v[76:79]
	v_mfma_f32_16x16x32_bf16 v[72:75], v[164:167], v[212:215], v[72:75]
	v_mfma_f32_16x16x32_bf16 v[124:127], v[146:149], v[192:195], v[124:127]
	v_mfma_f32_16x16x32_bf16 v[120:123], v[168:171], v[192:195], v[120:123]
	v_mfma_f32_16x16x32_bf16 v[108:111], v[146:149], v[200:203], v[108:111]
	v_mfma_f32_16x16x32_bf16 v[104:107], v[168:171], v[200:203], v[104:107]
	v_mfma_f32_16x16x32_bf16 v[92:95], v[146:149], v[208:211], v[92:95]
	v_mfma_f32_16x16x32_bf16 v[88:91], v[168:171], v[208:211], v[88:91]
	v_mfma_f32_16x16x32_bf16 v[76:79], v[146:149], v[216:219], v[76:79]
	v_mfma_f32_16x16x32_bf16 v[72:75], v[168:171], v[216:219], v[72:75]
	s_setprio 0
	s_setprio 1
	v_mfma_f32_16x16x32_bf16 v[116:119], v[172:175], v[188:191], v[116:119]
	v_mfma_f32_16x16x32_bf16 v[112:115], v[180:183], v[188:191], v[112:115]
	v_mfma_f32_16x16x32_bf16 v[100:103], v[172:175], v[196:199], v[100:103]
	v_mfma_f32_16x16x32_bf16 v[96:99], v[180:183], v[196:199], v[96:99]
	v_mfma_f32_16x16x32_bf16 v[84:87], v[172:175], v[204:207], v[84:87]
	v_mfma_f32_16x16x32_bf16 v[80:83], v[180:183], v[204:207], v[80:83]
	v_mfma_f32_16x16x32_bf16 v[68:71], v[172:175], v[212:215], v[68:71]
	v_mfma_f32_16x16x32_bf16 v[64:67], v[180:183], v[212:215], v[64:67]
	v_mfma_f32_16x16x32_bf16 v[116:119], v[176:179], v[192:195], v[116:119]
	v_mfma_f32_16x16x32_bf16 v[112:115], v[184:187], v[192:195], v[112:115]
	v_mfma_f32_16x16x32_bf16 v[100:103], v[176:179], v[200:203], v[100:103]
	v_mfma_f32_16x16x32_bf16 v[96:99], v[184:187], v[200:203], v[96:99]
	v_mfma_f32_16x16x32_bf16 v[84:87], v[176:179], v[208:211], v[84:87]
	v_mfma_f32_16x16x32_bf16 v[80:83], v[184:187], v[208:211], v[80:83]
	v_mfma_f32_16x16x32_bf16 v[68:71], v[176:179], v[216:219], v[68:71]
	v_mfma_f32_16x16x32_bf16 v[64:67], v[184:187], v[216:219], v[64:67]
	s_setprio 0
	s_barrier
	s_add_i32 s52, s52, s35
	v_lshl_add_u64 v[150:151], s[28:29], 0, v[152:153]
	s_mov_b32 m0, s52
	ds_read_b128 v[188:191], v145 offset:16384
	ds_read_b128 v[192:195], v145 offset:17408
	ds_read_b128 v[196:199], v145 offset:18432
	ds_read_b128 v[200:203], v145 offset:19456
	ds_read_b128 v[204:207], v145 offset:20480
	ds_read_b128 v[208:211], v145 offset:21504
	ds_read_b128 v[212:215], v145 offset:22528
	ds_read_b128 v[216:219], v145 offset:23552
	global_load_lds_dwordx4 v[150:151], off
	s_add_i32 m0, s52, 0x2000
	s_add_u32 s52, s28, 0x80000
	v_lshl_add_u64 v[220:221], s[28:29], 0, v[128:129]
	s_addc_u32 s53, s29, 0
	s_add_i32 s54, s54, s35
	global_load_lds_dwordx4 v[220:221], off
	v_lshl_add_u64 v[222:223], s[52:53], 0, v[152:153]
	s_mov_b32 m0, s54
	v_lshl_add_u64 v[224:225], s[30:31], 0, v[130:131]
	global_load_lds_dwordx4 v[222:223], off
	v_lshl_add_u64 v[222:223], s[52:53], 0, v[128:129]
	s_add_i32 m0, s54, 0x2000
	s_nop 0
	global_load_lds_dwordx4 v[222:223], off
	v_lshl_add_u64 v[222:223], s[30:31], 0, v[132:133]
	s_mov_b32 m0, s36
	s_nop 0
	global_load_lds_dwordx4 v[222:223], off
	s_mov_b32 m0, s37
	s_nop 0
	global_load_lds_dwordx4 v[224:225], off
	s_waitcnt vmcnt(8)
	s_waitcnt lgkmcnt(0)
	s_setprio 1
	s_barrier
	v_mfma_f32_16x16x32_bf16 v[60:63], v[138:141], v[188:191], v[60:63]
	v_mfma_f32_16x16x32_bf16 v[56:59], v[164:167], v[188:191], v[56:59]
	v_mfma_f32_16x16x32_bf16 v[44:47], v[138:141], v[196:199], v[44:47]
	v_mfma_f32_16x16x32_bf16 v[40:43], v[164:167], v[196:199], v[40:43]
	v_mfma_f32_16x16x32_bf16 v[28:31], v[138:141], v[204:207], v[28:31]
	v_mfma_f32_16x16x32_bf16 v[24:27], v[164:167], v[204:207], v[24:27]
	v_mfma_f32_16x16x32_bf16 v[12:15], v[138:141], v[212:215], v[12:15]
	v_mfma_f32_16x16x32_bf16 v[8:11], v[164:167], v[212:215], v[8:11]
	v_mfma_f32_16x16x32_bf16 v[60:63], v[146:149], v[192:195], v[60:63]
	v_mfma_f32_16x16x32_bf16 v[56:59], v[168:171], v[192:195], v[56:59]
	v_mfma_f32_16x16x32_bf16 v[44:47], v[146:149], v[200:203], v[44:47]
	v_mfma_f32_16x16x32_bf16 v[40:43], v[168:171], v[200:203], v[40:43]
	v_mfma_f32_16x16x32_bf16 v[28:31], v[146:149], v[208:211], v[28:31]
	v_mfma_f32_16x16x32_bf16 v[24:27], v[168:171], v[208:211], v[24:27]
	v_mfma_f32_16x16x32_bf16 v[12:15], v[146:149], v[216:219], v[12:15]
	v_mfma_f32_16x16x32_bf16 v[8:11], v[168:171], v[216:219], v[8:11]
	s_setprio 0
	s_setprio 1
	v_mfma_f32_16x16x32_bf16 v[52:55], v[172:175], v[188:191], v[52:55]
	v_mfma_f32_16x16x32_bf16 v[48:51], v[180:183], v[188:191], v[48:51]
	v_mfma_f32_16x16x32_bf16 v[36:39], v[172:175], v[196:199], v[36:39]
	v_mfma_f32_16x16x32_bf16 v[32:35], v[180:183], v[196:199], v[32:35]
	v_mfma_f32_16x16x32_bf16 v[20:23], v[172:175], v[204:207], v[20:23]
	v_mfma_f32_16x16x32_bf16 v[16:19], v[180:183], v[204:207], v[16:19]
	v_mfma_f32_16x16x32_bf16 v[4:7], v[172:175], v[212:215], v[4:7]
	v_mfma_f32_16x16x32_bf16 v[0:3], v[180:183], v[212:215], v[0:3]
	v_mfma_f32_16x16x32_bf16 v[52:55], v[176:179], v[192:195], v[52:55]
	v_mfma_f32_16x16x32_bf16 v[48:51], v[184:187], v[192:195], v[48:51]
	v_mfma_f32_16x16x32_bf16 v[36:39], v[176:179], v[200:203], v[36:39]
	v_mfma_f32_16x16x32_bf16 v[32:35], v[184:187], v[200:203], v[32:35]
	v_mfma_f32_16x16x32_bf16 v[20:23], v[176:179], v[208:211], v[20:23]
	v_mfma_f32_16x16x32_bf16 v[16:19], v[184:187], v[208:211], v[16:19]
	v_mfma_f32_16x16x32_bf16 v[4:7], v[176:179], v[216:219], v[4:7]
	v_mfma_f32_16x16x32_bf16 v[0:3], v[184:187], v[216:219], v[0:3]
	s_setprio 0
	s_barrier
; #define PG8_STAGE(bufoff, gbase, voff) do { _Pragma("unroll") for (int _i = 0; _i < 2; ++_i) \
;         __builtin_amdgcn_global_load_lds((const unsigned*)((const char*)(gbase) + (voff)[_i]), (PG8_LAS unsigned*)(lds + (bufoff) + ldsw + _i * 8192), 16, 0, 0); } while (0)
; #define PG8_LDA(dst, b, h) do { _Pragma("unroll") for (int m = 0; m < 4; ++m) _Pragma("unroll") for (int k = 0; k < 2; ++k) dst[m][k] = *(const PG8_LAS bf16x8*)(lds + PG8_SA(b, h) + aoff + m * 2048 + k * 1024); } while (0)
; #define PG8_LDB(dst, b, h) do { _Pragma("unroll") for (int n = 0; n < 2; ++n) _Pragma("unroll") for (int k = 0; k < 2; ++k) dst[n][k] = *(const PG8_LAS bf16x8*)(lds + PG8_SB(b, h) + boff + n * 2048 + k * 1024); } while (0)
; #define PG8_MMA(ai, bj, At, Bt) do { __builtin_amdgcn_s_setprio(1); _Pragma("unroll") for (int m = 0; m < 4; ++m) _Pragma("unroll") for (int n = 0; n < 2; ++n) _Pragma("unroll") for (int k = 0; k < 2; ++k) \
;         acc[ai][bj][m][n] = __builtin_amdgcn_mfma_f32_16x16x32_bf16(Bt[n][k], At[m][k], acc[ai][bj][m][n], 0, 0, 0); __builtin_amdgcn_s_setprio(0); } while (0)
; #define PG8_WAIT_V(n) asm volatile("s_waitcnt vmcnt(" #n ")" ::: "memory")
; #define PG8_WAIT_L(n) asm volatile("s_waitcnt lgkmcnt(" #n ")" ::: "memory")
; #define PG8_BAR __builtin_amdgcn_s_barrier()
; #define PG8_SCHED __builtin_amdgcn_sched_barrier(0)
; template <class Epi, class Sched, bool ALIGN_EPI = false, bool SP2 = false>
; __device__ __forceinline__ void gemm_phase(PG8_LAS unsigned char* lds, const Gemm g, const Sched& S, const Epi& E) {
;     ...
;             PG8_LDB(B0, 1, 0); PG8_LDB(B1, 1, 1); PG8_SCHED; PG8_LDA(At, 1, 0); PG8_STAGE(PG8_SA(0, 1), a2 + hstep, voffA);
;             PG8_WAIT_V(8); PG8_WAIT_L(0); PG8_BAR; PG8_MMA(0, 0, At, B0); PG8_MMA(0, 1, At, B1); PG8_BAR; PG8_SCHED;
	s_add_i32 s52, 0, 0x18000
	s_add_i32 s53, 0, 0x1c000
	v_add_u32_e32 v168, s52, v144
	v_add_u32_e32 v184, s53, v144
	ds_read_b128 v[138:141], v168
	ds_read_b128 v[146:149], v168 offset:1024
	ds_read_b128 v[164:167], v168 offset:2048
	ds_read_b128 v[168:171], v168 offset:3072
	ds_read_b128 v[172:175], v184
	ds_read_b128 v[176:179], v184 offset:1024
	ds_read_b128 v[180:183], v184 offset:2048
	ds_read_b128 v[184:187], v184 offset:3072
	s_add_u32 s30, s30, 0x80000
	s_addc_u32 s31, s31, 0
	s_mov_b32 m0, s38
	v_lshl_add_u64 v[226:227], s[30:31], 0, v[132:133]
	ds_read_b128 v[188:191], v145 offset:32768
	ds_read_b128 v[192:195], v145 offset:33792
	ds_read_b128 v[196:199], v145 offset:34816
	ds_read_b128 v[200:203], v145 offset:35840
	ds_read_b128 v[204:207], v145 offset:36864
	ds_read_b128 v[208:211], v145 offset:37888
	ds_read_b128 v[212:215], v145 offset:38912
	ds_read_b128 v[216:219], v145 offset:39936
	global_load_lds_dwordx4 v[226:227], off
	v_lshl_add_u64 v[226:227], s[30:31], 0, v[130:131]
	s_mov_b32 m0, s39
	s_nop 0
	global_load_lds_dwordx4 v[226:227], off
	s_waitcnt vmcnt(8)
	s_waitcnt lgkmcnt(0)
	s_setprio 1
	s_barrier
	v_mfma_f32_16x16x32_bf16 v[124:127], v[138:141], v[188:191], v[124:127]
	v_mfma_f32_16x16x32_bf16 v[120:123], v[164:167], v[188:191], v[120:123]
	v_mfma_f32_16x16x32_bf16 v[108:111], v[138:141], v[196:199], v[108:111]
	v_mfma_f32_16x16x32_bf16 v[104:107], v[164:167], v[196:199], v[104:107]
	v_mfma_f32_16x16x32_bf16 v[92:95], v[138:141], v[204:207], v[92:95]
	v_mfma_f32_16x16x32_bf16 v[88:91], v[164:167], v[204:207], v[88:91]
	v_mfma_f32_16x16x32_bf16 v[76:79], v[138:141], v[212:215], v[76:79]
	v_mfma_f32_16x16x32_bf16 v[72:75], v[164:167], v[212:215], v[72:75]
	v_mfma_f32_16x16x32_bf16 v[124:127], v[146:149], v[192:195], v[124:127]
	v_mfma_f32_16x16x32_bf16 v[120:123], v[168:171], v[192:195], v[120:123]
	v_mfma_f32_16x16x32_bf16 v[108:111], v[146:149], v[200:203], v[108:111]
	v_mfma_f32_16x16x32_bf16 v[104:107], v[168:171], v[200:203], v[104:107]
	v_mfma_f32_16x16x32_bf16 v[92:95], v[146:149], v[208:211], v[92:95]
	v_mfma_f32_16x16x32_bf16 v[88:91], v[168:171], v[208:211], v[88:91]
	v_mfma_f32_16x16x32_bf16 v[76:79], v[146:149], v[216:219], v[76:79]
	v_mfma_f32_16x16x32_bf16 v[72:75], v[168:171], v[216:219], v[72:75]
	s_setprio 0
	s_setprio 1
	v_mfma_f32_16x16x32_bf16 v[116:119], v[172:175], v[188:191], v[116:119]
	v_mfma_f32_16x16x32_bf16 v[112:115], v[180:183], v[188:191], v[112:115]
	v_mfma_f32_16x16x32_bf16 v[100:103], v[172:175], v[196:199], v[100:103]
	v_mfma_f32_16x16x32_bf16 v[96:99], v[180:183], v[196:199], v[96:99]
	v_mfma_f32_16x16x32_bf16 v[84:87], v[172:175], v[204:207], v[84:87]
	v_mfma_f32_16x16x32_bf16 v[80:83], v[180:183], v[204:207], v[80:83]
	v_mfma_f32_16x16x32_bf16 v[68:71], v[172:175], v[212:215], v[68:71]
	v_mfma_f32_16x16x32_bf16 v[64:67], v[180:183], v[212:215], v[64:67]
	v_mfma_f32_16x16x32_bf16 v[116:119], v[176:179], v[192:195], v[116:119]
	v_mfma_f32_16x16x32_bf16 v[112:115], v[184:187], v[192:195], v[112:115]
	v_mfma_f32_16x16x32_bf16 v[100:103], v[176:179], v[200:203], v[100:103]
	v_mfma_f32_16x16x32_bf16 v[96:99], v[184:187], v[200:203], v[96:99]
	v_mfma_f32_16x16x32_bf16 v[84:87], v[176:179], v[208:211], v[84:87]
	v_mfma_f32_16x16x32_bf16 v[80:83], v[184:187], v[208:211], v[80:83]
	v_mfma_f32_16x16x32_bf16 v[68:71], v[176:179], v[216:219], v[68:71]
	v_mfma_f32_16x16x32_bf16 v[64:67], v[184:187], v[216:219], v[64:67]
	s_setprio 0
	s_barrier
; #define PG8_STAGE(bufoff, gbase, voff) do { _Pragma("unroll") for (int _i = 0; _i < 2; ++_i) \
;         __builtin_amdgcn_global_load_lds((const unsigned*)((const char*)(gbase) + (voff)[_i]), (PG8_LAS unsigned*)(lds + (bufoff) + ldsw + _i * 8192), 16, 0, 0); } while (0)
; #define PG8_LDA(dst, b, h) do { _Pragma("unroll") for (int m = 0; m < 4; ++m) _Pragma("unroll") for (int k = 0; k < 2; ++k) dst[m][k] = *(const PG8_LAS bf16x8*)(lds + PG8_SA(b, h) + aoff + m * 2048 + k * 1024); } while (0)
; #define PG8_MMA(ai, bj, At, Bt) do { __builtin_amdgcn_s_setprio(1); _Pragma("unroll") for (int m = 0; m < 4; ++m) _Pragma("unroll") for (int n = 0; n < 2; ++n) _Pragma("unroll") for (int k = 0; k < 2; ++k) \
;         acc[ai][bj][m][n] = __builtin_amdgcn_mfma_f32_16x16x32_bf16(Bt[n][k], At[m][k], acc[ai][bj][m][n], 0, 0, 0); __builtin_amdgcn_s_setprio(0); } while (0)
; #define PG8_WAIT_V(n) asm volatile("s_waitcnt vmcnt(" #n ")" ::: "memory")
; #define PG8_WAIT_L(n) asm volatile("s_waitcnt lgkmcnt(" #n ")" ::: "memory")
; #define PG8_BAR __builtin_amdgcn_s_barrier()
; #define PG8_SCHED __builtin_amdgcn_sched_barrier(0)
; template <class Epi, class Sched, bool ALIGN_EPI = false, bool SP2 = false>
; __device__ __forceinline__ void gemm_phase(PG8_LAS unsigned char* lds, const Gemm g, const Sched& S, const Epi& E) {
;     ...
;             PG8_LDA(At, 1, 1); PG8_STAGE(PG8_SB(1, 0), b3, voffB); PG8_STAGE(PG8_SB(1, 1), b3 + hstep, voffB); PG8_STAGE(PG8_SA(1, 0), a3, voffA);
;             PG8_WAIT_V(8); PG8_WAIT_L(0); PG8_BAR; PG8_MMA(1, 0, At, B0); PG8_MMA(1, 1, At, B1); PG8_BAR; PG8_SCHED;
;     ...
;         if constexpr (ALIGN_EPI) { if (wr == 0) PG8_BAR; }
	s_add_i32 s30, s52, s35
	v_lshl_add_u64 v[150:151], v[150:151], 0, s[74:75]
	s_mov_b32 m0, s30
	ds_read_b128 v[188:191], v145 offset:49152
	ds_read_b128 v[192:195], v145 offset:50176
	ds_read_b128 v[196:199], v145 offset:51200
	ds_read_b128 v[200:203], v145 offset:52224
	ds_read_b128 v[204:207], v145 offset:53248
	ds_read_b128 v[208:211], v145 offset:54272
	ds_read_b128 v[212:215], v145 offset:55296
	ds_read_b128 v[216:219], v145 offset:56320
	global_load_lds_dwordx4 v[150:151], off
	s_add_i32 m0, s30, 0x2000
	s_add_u32 s28, s28, 0x80080
	v_lshl_add_u64 v[150:151], v[220:221], 0, s[74:75]
	s_addc_u32 s29, s29, 0
	s_add_i32 s30, s53, s35
	global_load_lds_dwordx4 v[150:151], off
	v_lshl_add_u64 v[150:151], s[28:29], 0, v[152:153]
	s_mov_b32 m0, s30
	s_nop 0
	global_load_lds_dwordx4 v[150:151], off
	v_lshl_add_u64 v[150:151], s[28:29], 0, v[128:129]
	s_add_i32 m0, s30, 0x2000
	s_nop 0
	global_load_lds_dwordx4 v[150:151], off
	v_lshl_add_u64 v[150:151], v[222:223], 0, s[74:75]
	s_mov_b32 m0, s42
	s_nop 0
	global_load_lds_dwordx4 v[150:151], off
	v_lshl_add_u64 v[150:151], v[224:225], 0, s[74:75]
	s_mov_b32 m0, s43
	s_nop 0
	global_load_lds_dwordx4 v[150:151], off
	s_waitcnt vmcnt(8)
	s_waitcnt lgkmcnt(0)
	s_setprio 1
	s_barrier
	v_mfma_f32_16x16x32_bf16 v[60:63], v[138:141], v[188:191], v[60:63]
	v_mfma_f32_16x16x32_bf16 v[56:59], v[164:167], v[188:191], v[56:59]
	v_mfma_f32_16x16x32_bf16 v[44:47], v[138:141], v[196:199], v[44:47]
	v_mfma_f32_16x16x32_bf16 v[40:43], v[164:167], v[196:199], v[40:43]
	v_mfma_f32_16x16x32_bf16 v[28:31], v[138:141], v[204:207], v[28:31]
	v_mfma_f32_16x16x32_bf16 v[24:27], v[164:167], v[204:207], v[24:27]
	v_mfma_f32_16x16x32_bf16 v[12:15], v[138:141], v[212:215], v[12:15]
	v_mfma_f32_16x16x32_bf16 v[8:11], v[164:167], v[212:215], v[8:11]
	v_mfma_f32_16x16x32_bf16 v[60:63], v[146:149], v[192:195], v[60:63]
	v_mfma_f32_16x16x32_bf16 v[56:59], v[168:171], v[192:195], v[56:59]
	v_mfma_f32_16x16x32_bf16 v[44:47], v[146:149], v[200:203], v[44:47]
	v_mfma_f32_16x16x32_bf16 v[40:43], v[168:171], v[200:203], v[40:43]
	v_mfma_f32_16x16x32_bf16 v[28:31], v[146:149], v[208:211], v[28:31]
	v_mfma_f32_16x16x32_bf16 v[24:27], v[168:171], v[208:211], v[24:27]
	v_mfma_f32_16x16x32_bf16 v[12:15], v[146:149], v[216:219], v[12:15]
	v_mfma_f32_16x16x32_bf16 v[8:11], v[168:171], v[216:219], v[8:11]
	s_setprio 0
	s_setprio 1
	v_mfma_f32_16x16x32_bf16 v[52:55], v[172:175], v[188:191], v[52:55]
	v_mfma_f32_16x16x32_bf16 v[48:51], v[180:183], v[188:191], v[48:51]
	v_mfma_f32_16x16x32_bf16 v[36:39], v[172:175], v[196:199], v[36:39]
	v_mfma_f32_16x16x32_bf16 v[32:35], v[180:183], v[196:199], v[32:35]
	v_mfma_f32_16x16x32_bf16 v[20:23], v[172:175], v[204:207], v[20:23]
	v_mfma_f32_16x16x32_bf16 v[16:19], v[180:183], v[204:207], v[16:19]
	v_mfma_f32_16x16x32_bf16 v[4:7], v[172:175], v[212:215], v[4:7]
	v_mfma_f32_16x16x32_bf16 v[0:3], v[180:183], v[212:215], v[0:3]
	v_mfma_f32_16x16x32_bf16 v[52:55], v[176:179], v[192:195], v[52:55]
	v_mfma_f32_16x16x32_bf16 v[48:51], v[184:187], v[192:195], v[48:51]
	v_mfma_f32_16x16x32_bf16 v[36:39], v[176:179], v[200:203], v[36:39]
	v_mfma_f32_16x16x32_bf16 v[32:35], v[184:187], v[200:203], v[32:35]
	v_mfma_f32_16x16x32_bf16 v[20:23], v[176:179], v[208:211], v[20:23]
	v_mfma_f32_16x16x32_bf16 v[16:19], v[184:187], v[208:211], v[16:19]
	v_mfma_f32_16x16x32_bf16 v[4:7], v[176:179], v[216:219], v[4:7]
	v_mfma_f32_16x16x32_bf16 v[0:3], v[184:187], v[216:219], v[0:3]
	s_setprio 0
	s_barrier
	s_add_i32 s51, s51, 2
	s_add_u32 s26, s26, 0x100
	s_addc_u32 s27, s27, 0
	s_add_u32 s49, s49, 0x100
	s_addc_u32 s50, s50, 0
	s_cmp_gt_u32 s51, 29
	s_cbranch_scc0 .LBB0_1058
	s_and_b64 vcc, exec, s[16:17]
	s_cbranch_vccz .LBB0_1061
	s_barrier

; #define PG8_STAGE(bufoff, gbase, voff) do { _Pragma("unroll") for (int _i = 0; _i < 2; ++_i) \
;         __builtin_amdgcn_global_load_lds((const unsigned*)((const char*)(gbase) + (voff)[_i]), (PG8_LAS unsigned*)(lds + (bufoff) + ldsw + _i * 8192), 16, 0, 0); } while (0)
; #define PG8_WAIT_V(n) asm volatile("s_waitcnt vmcnt(" #n ")" ::: "memory")
; #define PG8_BAR __builtin_amdgcn_s_barrier()
; template <class Epi, class Sched, bool ALIGN_EPI = false, bool SP2 = false>
; __device__ __forceinline__ void gemm_phase(PG8_LAS unsigned char* lds, const Gemm g, const Sched& S, const Epi& E) {
;     int tid_l = threadIdx.x; asm volatile("" : "+v"(tid_l)); const int tid = tid_l, wid = __builtin_amdgcn_readfirstlane(tid >> 6), lane = tid & 63, wr = wid >> 2, wc = wid & 3, fr = lane & 15, fq = lane >> 4;
;     const int K = g.K, nt = K / BK;
;     unsigned voffA[2], voffB[2];
; #pragma unroll
;     for (int i = 0; i < 2; ++i) { int R, C; stage_rc(tid * 16 + i * 8192, R, C); const int Rb = Epi::PERM ? ((R & ~31) + perm32(R & 31)) : R;
;         voffA[i] = (unsigned)(R * K + C) * 2u; voffB[i] = (unsigned)(Rb * K + C) * 2u; }
;     const size_t kstep = (size_t)(BK * 2);
;     const size_t hstep = (size_t)HALF * K * 2;
;     const size_t tstep = 2 * hstep;
;     const unsigned ldsw = (unsigned)wid * 1024u;
;     const int aoff = lds_byte(wr * 64 + fr, fq * 8), boff = lds_byte(wc * 32 + fr, fq * 8);
;     ...
;     f32x4 acc[2][2][4][2];
; #pragma unroll
;     for (int a = 0; a < 2; ++a)
; #pragma unroll
;         for (int b = 0; b < 2; ++b)
; #pragma unroll
;             for (int m = 0; m < 4; ++m)
; #pragma unroll
;                 for (int n = 0; n < 2; ++n) acc[a][b][m][n] = (f32x4){0.f, 0.f, 0.f, 0.f};
;     bf16x8 At[4][2], B0[2][2], B1[2][2];
;     const char* cA = (const char*)g.A + (size_t)cur.pm * tstep; const char* cB = (const char*)g.Bt + (size_t)cur.pn * tstep;
;     S.a_ready(cur);
;     if constexpr (SP2) {
;         PG8_STAGE(PG8_SB(0, 0), cB, voffB); PG8_STAGE(PG8_SB(0, 1), cB + hstep, voffB); PG8_STAGE(PG8_SA(0, 0), cA, voffA); PG8_STAGE(PG8_SA(0, 1), cA + hstep, voffA);
;         if (wr == 1) PG8_BAR;
;         PG8_WAIT_V(2); PG8_BAR;
;         PG8_STAGE(PG8_SB(1, 0), cB + kstep, voffB); PG8_STAGE(PG8_SA(1, 0), cA + kstep, voffA); PG8_STAGE(PG8_SB(1, 1), cB + hstep + kstep, voffB);
;         PG8_WAIT_V(6); PG8_BAR;
.LBB0_1159:
	v_lshl_add_u64 v[6:7], s[22:23], 0, v[152:153]
	v_mov_b32_e32 v33, v153
	v_lshl_add_u64 v[8:9], s[22:23], 0, v[32:33]
	v_mov_b32_e32 v41, v153
	s_and_b32 s34, s5, 3
	s_add_i32 m0, s35, 0x18000
	v_lshl_add_u64 v[6:7], v[6:7], 0, s[74:75]
	v_lshl_add_u64 v[10:11], s[2:3], 0, v[40:41]
	v_mov_b32_e32 v35, v153
	s_lshl_b32 s36, s4, 6
	s_lshl_b32 s4, s4, 13
	s_lshl_b32 s5, s34, 12
	s_waitcnt vmcnt(2)
	s_barrier
	global_load_lds_dwordx4 v[6:7], off
	v_lshl_add_u64 v[6:7], v[8:9], 0, s[74:75]
	s_add_i32 m0, s35, 0x1a000
	s_add_i32 s40, s35, 0x8000
	s_add_i32 s41, s35, 0xa000
	v_lshl_add_u64 v[12:13], s[2:3], 0, v[34:35]
	global_load_lds_dwordx4 v[6:7], off
	v_lshl_add_u64 v[6:7], v[10:11], 0, s[74:75]
	s_mov_b32 m0, s40
	s_add_u32 s0, s22, 0x200080
	global_load_lds_dwordx4 v[6:7], off
	v_lshl_add_u64 v[6:7], v[12:13], 0, s[74:75]
	s_mov_b32 m0, s41
	s_addc_u32 s1, s23, 0
	global_load_lds_dwordx4 v[6:7], off
	s_add_i32 m0, s35, 0x1c000
	v_lshl_add_u64 v[6:7], s[0:1], 0, v[152:153]
	global_load_lds_dwordx4 v[6:7], off
	v_lshl_add_u64 v[6:7], s[0:1], 0, v[32:33]
	s_add_i32 m0, s35, 0x1e000
	v_and_b32_e32 v144, 15, v234
	global_load_lds_dwordx4 v[6:7], off
	v_and_b32_e32 v6, 48, v234
	v_lshlrev_b32_e32 v7, 2, v234
	v_lshl_or_b32 v6, v144, 6, v6
	v_and_b32_e32 v7, 32, v7
	v_bitop3_b32 v8, v6, s4, v7 bitop3:0xde
	v_bitop3_b32 v50, v6, s5, v7 bitop3:0xde
	v_lshlrev_b32_e32 v6, 17, v4
	v_and_b32_e32 v6, 0xfffc0000, v6
	v_lshl_add_u32 v3, v3, 14, v6
	v_and_b32_e32 v4, 1, v4
	v_lshl_or_b32 v3, v4, 6, v3
	v_lshl_add_u32 v42, v5, 1, v3
	v_lshlrev_b32_e32 v3, 17, v0
	v_and_b32_e32 v3, 0xfffc0000, v3
	v_lshl_add_u32 v1, v1, 14, v3
	v_and_b32_e32 v0, 1, v0
	v_lshl_or_b32 v0, v0, 6, v1
	s_waitcnt vmcnt(6)
	v_lshl_add_u32 v44, v2, 1, v0
	v_mov_b32_e32 v2, v153
	v_mov_b32_e32 v3, v153
	v_readlane_b32 s0, v253, 27
	v_mov_b32_e32 v0, v153
	v_mov_b32_e32 v1, v153
	v_add_u32_e32 v51, 0, v8
	v_mov_b64_e32 v[6:7], v[2:3]
	v_mov_b64_e32 v[18:19], v[2:3]
	v_mov_b64_e32 v[22:23], v[2:3]
	v_mov_b64_e32 v[38:39], v[2:3]
	v_mov_b64_e32 v[54:55], v[2:3]
	v_mov_b64_e32 v[66:67], v[2:3]
	v_mov_b64_e32 v[70:71], v[2:3]
	v_mov_b64_e32 v[10:11], v[2:3]
	v_mov_b64_e32 v[14:15], v[2:3]
	v_mov_b64_e32 v[26:27], v[2:3]
	v_mov_b64_e32 v[30:31], v[2:3]
	v_mov_b64_e32 v[58:59], v[2:3]
	v_mov_b64_e32 v[62:63], v[2:3]
	v_mov_b64_e32 v[74:75], v[2:3]
	v_mov_b64_e32 v[78:79], v[2:3]
	v_mov_b64_e32 v[82:83], v[2:3]
	v_mov_b64_e32 v[86:87], v[2:3]
	v_mov_b64_e32 v[98:99], v[2:3]
	v_mov_b64_e32 v[102:103], v[2:3]
	v_mov_b64_e32 v[114:115], v[2:3]
	v_mov_b64_e32 v[118:119], v[2:3]
	v_mov_b64_e32 v[130:131], v[2:3]
	v_mov_b64_e32 v[134:135], v[2:3]
	v_mov_b64_e32 v[90:91], v[2:3]
	v_mov_b64_e32 v[94:95], v[2:3]
	v_mov_b64_e32 v[106:107], v[2:3]
	v_mov_b64_e32 v[110:111], v[2:3]
	v_mov_b64_e32 v[122:123], v[2:3]
	v_mov_b64_e32 v[126:127], v[2:3]
	v_mov_b64_e32 v[138:139], v[2:3]
	v_mov_b64_e32 v[142:143], v[2:3]
	s_mov_b32 s6, s0
	v_readlane_b32 s0, v253, 39
	v_mov_b32_e32 v43, v153
	v_mov_b32_e32 v45, v153
	s_mov_b32 s43, 0
	v_mov_b64_e32 v[4:5], v[0:1]
	v_mov_b64_e32 v[16:17], v[0:1]
	v_mov_b64_e32 v[20:21], v[0:1]
	v_mov_b64_e32 v[36:37], v[0:1]
	v_mov_b64_e32 v[52:53], v[0:1]
	v_mov_b64_e32 v[64:65], v[0:1]
	v_mov_b64_e32 v[68:69], v[0:1]
	v_mov_b64_e32 v[8:9], v[0:1]
	v_mov_b64_e32 v[12:13], v[0:1]
	v_mov_b64_e32 v[24:25], v[0:1]
	v_mov_b64_e32 v[28:29], v[0:1]
	v_mov_b64_e32 v[56:57], v[0:1]
	v_mov_b64_e32 v[60:61], v[0:1]
	v_mov_b64_e32 v[72:73], v[0:1]
	v_mov_b64_e32 v[76:77], v[0:1]
	v_mov_b64_e32 v[80:81], v[0:1]
	v_mov_b64_e32 v[84:85], v[0:1]
	v_mov_b64_e32 v[96:97], v[0:1]
	v_mov_b64_e32 v[100:101], v[0:1]
	v_mov_b64_e32 v[112:113], v[0:1]
	v_mov_b64_e32 v[116:117], v[0:1]
	v_mov_b64_e32 v[128:129], v[0:1]
	v_mov_b64_e32 v[132:133], v[0:1]
	v_mov_b64_e32 v[88:89], v[0:1]
	v_mov_b64_e32 v[92:93], v[0:1]
	v_mov_b64_e32 v[104:105], v[0:1]
	v_mov_b64_e32 v[108:109], v[0:1]
	v_mov_b64_e32 v[120:121], v[0:1]
	v_mov_b64_e32 v[124:125], v[0:1]
	v_mov_b64_e32 v[136:137], v[0:1]
	v_mov_b64_e32 v[140:141], v[0:1]
	s_mov_b32 s42, s0
	s_barrier
	v_readlane_b32 s1, v253, 40
	s_branch .LBB0_1162
	s_nop 0
	s_nop 0
.LBB0_1160:
	s_mov_b64 s[18:19], s[22:23]
	s_andn2_b64 vcc, exec, s[0:1]
	s_cbranch_vccz .LBB0_1172

; __device__ __forceinline__ unsigned xb_ld(unsigned* p)              { return __hip_atomic_load(p, __ATOMIC_RELAXED, __HIP_MEMORY_SCOPE_AGENT); }
; __device__ __forceinline__ unsigned xb_add(unsigned* p, unsigned v) { return __hip_atomic_fetch_add(p, v, __ATOMIC_RELAXED, __HIP_MEMORY_SCOPE_AGENT); }
; #define XB_SPIN(cond, bar) do { unsigned _sp = 0; while (cond) { __builtin_amdgcn_s_sleep(1); \
;     if ((++_sp & 255u) == 0u) { if (xb_ld(&(bar)[XB_TMO])) break; if (_sp > XB_SPIN_CAP) { atomicAdd(&(bar)[XB_TMO], 1u); break; } } } } while (0)
; __device__ __forceinline__ void xcd_barrier(const XcdBarrier& b) {
;     ...
;             const unsigned og = xb_add(&bar[XB_TOP], 1u);
;             const unsigned tg = og / nx;
;             if (og + 1u == (tg + 1u) * nx) xb_add(&bar[XB_TOPGEN], 1u);
;             else XB_SPIN(xb_ld(&bar[XB_TOPGEN]) == tg, bar);
.LBB0_1210:
	s_or_b64 exec, exec, s[16:17]
	v_cvt_f32_u32_e32 v7, v5
	s_waitcnt vmcnt(0)
	v_readfirstlane_b32 s7, v6
	v_sub_u32_e32 v6, 0, v5
	v_rcp_iflag_f32_e32 v7, v7
	v_add_u32_e32 v18, s7, v3
	v_mul_f32_e32 v7, 0x4f7ffffe, v7
	v_cvt_u32_f32_e32 v7, v7
	v_mul_lo_u32 v3, v6, v7
	v_mul_hi_u32 v3, v7, v3
	v_add_u32_e32 v3, v7, v3
	v_mul_hi_u32 v3, v18, v3
	v_mul_lo_u32 v6, v3, v5
	v_sub_u32_e32 v6, v18, v6
	v_add_u32_e32 v7, 1, v3
	v_cmp_ge_u32_e32 vcc, v6, v5
	s_nop 1
	v_cndmask_b32_e32 v3, v3, v7, vcc
	v_sub_u32_e32 v7, v6, v5
	v_cndmask_b32_e32 v6, v6, v7, vcc
	v_add_u32_e32 v7, 1, v3
	v_cmp_ge_u32_e32 vcc, v6, v5
	v_add_u32_e32 v6, 1, v18
	s_nop 0
	v_cndmask_b32_e32 v3, v3, v7, vcc
	v_mul_lo_u32 v7, v5, v3
	v_add_u32_e32 v5, v7, v5
	v_cmp_ne_u32_e32 vcc, v6, v5
	s_and_saveexec_b64 s[14:15], vcc
	s_xor_b64 s[14:15], exec, s[14:15]
	s_cbranch_execz .LBB0_1224
	s_waitcnt lgkmcnt(0)
	buffer_inv sc1
	v_mad_u32_u24 v3, v3, v2, v2
	v_mov_b32_e32 v2, 0x2e403000
	global_load_dword v2, v2, s[12:13] offset:1024 sc1
	s_add_u32 s20, s12, 0x2e403400
	s_addc_u32 s21, s13, 0
	s_waitcnt vmcnt(0)
	v_cmp_lt_u32_e32 vcc, v2, v3
	s_and_saveexec_b64 s[16:17], vcc
	s_cbranch_execz .LBB0_1223
	s_add_u32 s18, s12, 0x2e400200
	s_addc_u32 s19, s13, 0
	s_mov_b32 s7, 1
	s_mov_b64 s[22:23], 0
	s_branch .LBB0_1214

; __device__ __forceinline__ unsigned xb_ld(unsigned* p)              { return __hip_atomic_load(p, __ATOMIC_RELAXED, __HIP_MEMORY_SCOPE_AGENT); }
; #define XB_SPIN(cond, bar) do { unsigned _sp = 0; while (cond) { __builtin_amdgcn_s_sleep(1); \
;     if ((++_sp & 255u) == 0u) { if (xb_ld(&(bar)[XB_TMO])) break; if (_sp > XB_SPIN_CAP) { atomicAdd(&(bar)[XB_TMO], 1u); break; } } } } while (0)
; __device__ __forceinline__ void xcd_barrier(const XcdBarrier& b) {
;     ...
;             else XB_SPIN(xb_ld(&bar[XB_TOPGEN]) == tg, bar);
.LBB0_1216:
	global_load_dword v2, v153, s[20:21] sc1
	s_add_i32 s7, s7, 1
	s_mov_b64 s[28:29], -1
	s_waitcnt vmcnt(0)
	v_cmp_ge_u32_e32 vcc, v2, v3
	s_orn2_b64 s[26:27], vcc, exec
	s_branch .LBB0_1213
